# v43 + GEMM loops: MMA-tail bookkeeping (phases 2/4/6/8) moved to the end of the same phase's load segment, barrier directly after the last MFMA
# speedup vs baseline: 1.0106x; 1.0102x over previous
.LBB0_127:
	s_add_u32 s22, s20, 0xfff80080
	s_addc_u32 s23, s21, -1
	s_add_i32 s50, 0, 0x10000
	s_cmp_eq_u32 s49, 4
	s_cselect_b32 s23, s81, s23
	s_cselect_b32 s22, s80, s22
	s_cselect_b32 s39, s19, s48
	s_cselect_b32 s38, s31, s47
	v_lshl_add_u64 v[178:179], s[20:21], 0, v[138:139]
	s_add_i32 m0, s27, 0xc000
	ds_read_b128 v[162:165], v144
	ds_read_b128 v[166:169], v144 offset:1024
	ds_read_b128 v[170:173], v144 offset:2048
	ds_read_b128 v[174:177], v144 offset:3072
	ds_read_b128 v[192:195], v144 offset:4096
	ds_read_b128 v[196:199], v144 offset:5120
	ds_read_b128 v[200:203], v144 offset:6144
	ds_read_b128 v[204:207], v144 offset:7168
	global_load_lds_dwordx4 v[178:179], off
	v_lshl_add_u64 v[178:179], s[20:21], 0, v[140:141]
	s_add_i32 m0, s27, 0xe000
	s_nop 0
	global_load_lds_dwordx4 v[178:179], off
	s_waitcnt lgkmcnt(8)
	s_barrier
	s_waitcnt lgkmcnt(0)
	v_mfma_f32_16x16x32_bf16 v[126:129], v[146:149], v[162:165], v[126:129]
	v_mfma_f32_16x16x32_bf16 v[122:125], v[154:157], v[162:165], v[122:125]
	v_mfma_f32_16x16x32_bf16 v[118:121], v[146:149], v[170:173], v[118:121]
	v_mfma_f32_16x16x32_bf16 v[114:117], v[154:157], v[170:173], v[114:117]
	v_mfma_f32_16x16x32_bf16 v[102:105], v[146:149], v[192:195], v[102:105]
	v_mfma_f32_16x16x32_bf16 v[98:101], v[154:157], v[192:195], v[98:101]
	v_mfma_f32_16x16x32_bf16 v[86:89], v[146:149], v[200:203], v[86:89]
	v_mfma_f32_16x16x32_bf16 v[82:85], v[154:157], v[200:203], v[82:85]
	v_mfma_f32_16x16x32_bf16 v[126:129], v[150:153], v[166:169], v[126:129]
	v_mfma_f32_16x16x32_bf16 v[122:125], v[158:161], v[166:169], v[122:125]
	v_mfma_f32_16x16x32_bf16 v[118:121], v[150:153], v[174:177], v[118:121]
	v_mfma_f32_16x16x32_bf16 v[114:117], v[158:161], v[174:177], v[114:117]
	v_mfma_f32_16x16x32_bf16 v[102:105], v[150:153], v[196:199], v[102:105]
	v_mfma_f32_16x16x32_bf16 v[98:101], v[158:161], v[196:199], v[98:101]
	v_mfma_f32_16x16x32_bf16 v[86:89], v[150:153], v[204:207], v[86:89]
	v_mfma_f32_16x16x32_bf16 v[82:85], v[158:161], v[204:207], v[82:85]
	s_barrier
	s_add_i32 s52, 0, 0x14000
	s_add_i32 s50, s50, s26
	v_add_u32_e32 v145, s52, v142
	v_lshl_add_u64 v[178:179], s[38:39], 0, v[134:135]
	s_mov_b32 m0, s50
	ds_read_b128 v[208:211], v145
	ds_read_b128 v[224:227], v145 offset:1024
	ds_read_b128 v[228:231], v145 offset:2048
	ds_read_b128 v[232:235], v145 offset:3072
	global_load_lds_dwordx4 v[178:179], off
	v_lshl_add_u64 v[212:213], s[38:39], 0, v[130:131]
	s_add_i32 m0, s50, 0x2000
	s_nop 0
	global_load_lds_dwordx4 v[212:213], off
	s_mov_b32 m0, s27
	v_lshl_add_u64 v[236:237], s[22:23], 0, v[136:137]
	s_barrier
	s_waitcnt lgkmcnt(0)
	v_mfma_f32_16x16x32_bf16 v[110:113], v[208:211], v[162:165], v[110:113]
	v_mfma_f32_16x16x32_bf16 v[106:109], v[228:231], v[162:165], v[106:109]
	v_mfma_f32_16x16x32_bf16 v[94:97], v[208:211], v[170:173], v[94:97]
	v_mfma_f32_16x16x32_bf16 v[90:93], v[228:231], v[170:173], v[90:93]
	v_mfma_f32_16x16x32_bf16 v[78:81], v[208:211], v[192:195], v[78:81]
	v_mfma_f32_16x16x32_bf16 v[74:77], v[228:231], v[192:195], v[74:77]
	v_mfma_f32_16x16x32_bf16 v[70:73], v[208:211], v[200:203], v[70:73]
	v_mfma_f32_16x16x32_bf16 v[66:69], v[228:231], v[200:203], v[66:69]
	v_mfma_f32_16x16x32_bf16 v[110:113], v[224:227], v[166:169], v[110:113]
	v_mfma_f32_16x16x32_bf16 v[106:109], v[232:235], v[166:169], v[106:109]
	v_mfma_f32_16x16x32_bf16 v[94:97], v[224:227], v[174:177], v[94:97]
	v_mfma_f32_16x16x32_bf16 v[90:93], v[232:235], v[174:177], v[90:93]
	v_mfma_f32_16x16x32_bf16 v[78:81], v[224:227], v[196:199], v[78:81]
	v_mfma_f32_16x16x32_bf16 v[74:77], v[232:235], v[196:199], v[74:77]
	v_mfma_f32_16x16x32_bf16 v[70:73], v[224:227], v[204:207], v[70:73]
	v_mfma_f32_16x16x32_bf16 v[66:69], v[232:235], v[204:207], v[66:69]
	s_barrier
	ds_read_b128 v[162:165], v144 offset:16384
	ds_read_b128 v[166:169], v144 offset:17408
	ds_read_b128 v[170:173], v144 offset:18432
	ds_read_b128 v[174:177], v144 offset:19456
	ds_read_b128 v[192:195], v144 offset:20480
	ds_read_b128 v[196:199], v144 offset:21504
	ds_read_b128 v[200:203], v144 offset:22528
	ds_read_b128 v[204:207], v144 offset:23552
	global_load_lds_dwordx4 v[236:237], off
	v_lshl_add_u64 v[238:239], s[22:23], 0, v[132:133]
	s_mov_b32 m0, s28
	s_nop 0
	global_load_lds_dwordx4 v[238:239], off
	s_waitcnt vmcnt(10)
	s_barrier
	s_waitcnt lgkmcnt(0)
	v_mfma_f32_16x16x32_bf16 v[62:65], v[146:149], v[162:165], v[62:65]
	v_mfma_f32_16x16x32_bf16 v[58:61], v[154:157], v[162:165], v[58:61]
	v_mfma_f32_16x16x32_bf16 v[54:57], v[146:149], v[170:173], v[54:57]
	v_mfma_f32_16x16x32_bf16 v[50:53], v[154:157], v[170:173], v[50:53]
	v_mfma_f32_16x16x32_bf16 v[38:41], v[146:149], v[192:195], v[38:41]
	v_mfma_f32_16x16x32_bf16 v[34:37], v[154:157], v[192:195], v[34:37]
	v_mfma_f32_16x16x32_bf16 v[22:25], v[146:149], v[200:203], v[22:25]
	v_mfma_f32_16x16x32_bf16 v[18:21], v[154:157], v[200:203], v[18:21]
	v_mfma_f32_16x16x32_bf16 v[62:65], v[150:153], v[166:169], v[62:65]
	v_mfma_f32_16x16x32_bf16 v[58:61], v[158:161], v[166:169], v[58:61]
	v_mfma_f32_16x16x32_bf16 v[54:57], v[150:153], v[174:177], v[54:57]
	v_mfma_f32_16x16x32_bf16 v[50:53], v[158:161], v[174:177], v[50:53]
	v_mfma_f32_16x16x32_bf16 v[38:41], v[150:153], v[196:199], v[38:41]
	v_mfma_f32_16x16x32_bf16 v[34:37], v[158:161], v[196:199], v[34:37]
	v_mfma_f32_16x16x32_bf16 v[22:25], v[150:153], v[204:207], v[22:25]
	v_mfma_f32_16x16x32_bf16 v[18:21], v[158:161], v[204:207], v[18:21]
	s_barrier
	s_add_u32 s50, s38, 0x20000
	s_addc_u32 s51, s39, 0
	s_add_i32 s52, s52, s26
	v_lshl_add_u64 v[146:147], s[50:51], 0, v[134:135]
	s_mov_b32 m0, s52
	s_nop 0
	global_load_lds_dwordx4 v[146:147], off
	v_lshl_add_u64 v[146:147], s[50:51], 0, v[130:131]
	s_add_i32 m0, s52, 0x2000
	s_nop 0
	global_load_lds_dwordx4 v[146:147], off
	v_add_u32_e32 v145, 0x18000, v142
	ds_read_b128 v[146:149], v145
	ds_read_b128 v[150:153], v145 offset:1024
	ds_read_b128 v[154:157], v145 offset:2048
	ds_read_b128 v[158:161], v145 offset:3072
	s_add_i32 s50, 0, 0x18000
	s_waitcnt vmcnt(6)
	s_barrier
	v_mfma_f32_16x16x32_bf16 v[46:49], v[208:211], v[162:165], v[46:49]
	v_mfma_f32_16x16x32_bf16 v[42:45], v[228:231], v[162:165], v[42:45]
	v_mfma_f32_16x16x32_bf16 v[30:33], v[208:211], v[170:173], v[30:33]
	v_mfma_f32_16x16x32_bf16 v[26:29], v[228:231], v[170:173], v[26:29]
	v_mfma_f32_16x16x32_bf16 v[14:17], v[208:211], v[192:195], v[14:17]
	v_mfma_f32_16x16x32_bf16 v[10:13], v[228:231], v[192:195], v[10:13]
	v_mfma_f32_16x16x32_bf16 v[6:9], v[208:211], v[200:203], v[6:9]
	v_mfma_f32_16x16x32_bf16 v[2:5], v[228:231], v[200:203], v[2:5]
	v_mfma_f32_16x16x32_bf16 v[46:49], v[224:227], v[166:169], v[46:49]
	v_mfma_f32_16x16x32_bf16 v[42:45], v[232:235], v[166:169], v[42:45]
	v_mfma_f32_16x16x32_bf16 v[30:33], v[224:227], v[174:177], v[30:33]
	v_mfma_f32_16x16x32_bf16 v[26:29], v[232:235], v[174:177], v[26:29]
	v_mfma_f32_16x16x32_bf16 v[14:17], v[224:227], v[196:199], v[14:17]
	v_mfma_f32_16x16x32_bf16 v[10:13], v[232:235], v[196:199], v[10:13]
	v_mfma_f32_16x16x32_bf16 v[6:9], v[224:227], v[204:207], v[6:9]
	v_mfma_f32_16x16x32_bf16 v[2:5], v[232:235], v[204:207], v[2:5]
	s_barrier
	s_add_u32 s22, s22, 0x80000
	s_addc_u32 s23, s23, 0
	s_mov_b32 m0, s29
	v_lshl_add_u64 v[208:209], s[22:23], 0, v[136:137]
	ds_read_b128 v[162:165], v144 offset:32768
	ds_read_b128 v[166:169], v144 offset:33792
	ds_read_b128 v[170:173], v144 offset:34816
	ds_read_b128 v[174:177], v144 offset:35840
	ds_read_b128 v[192:195], v144 offset:36864
	ds_read_b128 v[196:199], v144 offset:37888
	ds_read_b128 v[200:203], v144 offset:38912
	ds_read_b128 v[204:207], v144 offset:39936
	global_load_lds_dwordx4 v[208:209], off
	v_lshl_add_u64 v[208:209], s[22:23], 0, v[132:133]
	s_mov_b32 m0, s36
	s_nop 0
	global_load_lds_dwordx4 v[208:209], off
	s_waitcnt lgkmcnt(8)
	s_barrier
	s_waitcnt lgkmcnt(0)
	v_mfma_f32_16x16x32_bf16 v[126:129], v[146:149], v[162:165], v[126:129]
	v_mfma_f32_16x16x32_bf16 v[122:125], v[154:157], v[162:165], v[122:125]
	v_mfma_f32_16x16x32_bf16 v[118:121], v[146:149], v[170:173], v[118:121]
	v_mfma_f32_16x16x32_bf16 v[114:117], v[154:157], v[170:173], v[114:117]
	v_mfma_f32_16x16x32_bf16 v[102:105], v[146:149], v[192:195], v[102:105]
	v_mfma_f32_16x16x32_bf16 v[98:101], v[154:157], v[192:195], v[98:101]
	v_mfma_f32_16x16x32_bf16 v[86:89], v[146:149], v[200:203], v[86:89]
	v_mfma_f32_16x16x32_bf16 v[82:85], v[154:157], v[200:203], v[82:85]
	v_mfma_f32_16x16x32_bf16 v[126:129], v[150:153], v[166:169], v[126:129]
	v_mfma_f32_16x16x32_bf16 v[122:125], v[158:161], v[166:169], v[122:125]
	v_mfma_f32_16x16x32_bf16 v[118:121], v[150:153], v[174:177], v[118:121]
	v_mfma_f32_16x16x32_bf16 v[114:117], v[158:161], v[174:177], v[114:117]
	v_mfma_f32_16x16x32_bf16 v[102:105], v[150:153], v[196:199], v[102:105]
	v_mfma_f32_16x16x32_bf16 v[98:101], v[158:161], v[196:199], v[98:101]
	v_mfma_f32_16x16x32_bf16 v[86:89], v[150:153], v[204:207], v[86:89]
	v_mfma_f32_16x16x32_bf16 v[82:85], v[158:161], v[204:207], v[82:85]
	s_barrier
	s_add_i32 s51, 0, 0x1c000
	s_add_i32 s22, s50, s26
	v_add_u32_e32 v145, s51, v142
	v_lshl_add_u64 v[178:179], v[178:179], 0, s[78:79]
	s_mov_b32 m0, s22
	ds_read_b128 v[208:211], v145
	ds_read_b128 v[224:227], v145 offset:1024
	ds_read_b128 v[228:231], v145 offset:2048
	ds_read_b128 v[232:235], v145 offset:3072
	global_load_lds_dwordx4 v[178:179], off
	v_lshl_add_u64 v[178:179], v[212:213], 0, s[78:79]
	s_add_i32 m0, s22, 0x2000
	s_nop 0
	global_load_lds_dwordx4 v[178:179], off
	s_mov_b32 m0, s42
	v_lshl_add_u64 v[178:179], v[236:237], 0, s[78:79]
	s_barrier
	s_waitcnt lgkmcnt(0)
	v_mfma_f32_16x16x32_bf16 v[110:113], v[208:211], v[162:165], v[110:113]
	v_mfma_f32_16x16x32_bf16 v[106:109], v[228:231], v[162:165], v[106:109]
	v_mfma_f32_16x16x32_bf16 v[94:97], v[208:211], v[170:173], v[94:97]
	v_mfma_f32_16x16x32_bf16 v[90:93], v[228:231], v[170:173], v[90:93]
	v_mfma_f32_16x16x32_bf16 v[78:81], v[208:211], v[192:195], v[78:81]
	v_mfma_f32_16x16x32_bf16 v[74:77], v[228:231], v[192:195], v[74:77]
	v_mfma_f32_16x16x32_bf16 v[70:73], v[208:211], v[200:203], v[70:73]
	v_mfma_f32_16x16x32_bf16 v[66:69], v[228:231], v[200:203], v[66:69]
	v_mfma_f32_16x16x32_bf16 v[110:113], v[224:227], v[166:169], v[110:113]
	v_mfma_f32_16x16x32_bf16 v[106:109], v[232:235], v[166:169], v[106:109]
	v_mfma_f32_16x16x32_bf16 v[94:97], v[224:227], v[174:177], v[94:97]
	v_mfma_f32_16x16x32_bf16 v[90:93], v[232:235], v[174:177], v[90:93]
	v_mfma_f32_16x16x32_bf16 v[78:81], v[224:227], v[196:199], v[78:81]
	v_mfma_f32_16x16x32_bf16 v[74:77], v[232:235], v[196:199], v[74:77]
	v_mfma_f32_16x16x32_bf16 v[70:73], v[224:227], v[204:207], v[70:73]
	v_mfma_f32_16x16x32_bf16 v[66:69], v[232:235], v[204:207], v[66:69]
	s_barrier
	ds_read_b128 v[162:165], v144 offset:49152
	ds_read_b128 v[166:169], v144 offset:50176
	ds_read_b128 v[170:173], v144 offset:51200
	ds_read_b128 v[174:177], v144 offset:52224
	ds_read_b128 v[192:195], v144 offset:53248
	ds_read_b128 v[196:199], v144 offset:54272
	ds_read_b128 v[200:203], v144 offset:55296
	ds_read_b128 v[204:207], v144 offset:56320
	global_load_lds_dwordx4 v[178:179], off
	v_lshl_add_u64 v[178:179], v[238:239], 0, s[78:79]
	s_mov_b32 m0, s43
	s_nop 0
	global_load_lds_dwordx4 v[178:179], off
	s_waitcnt vmcnt(10)
	s_barrier
	s_waitcnt lgkmcnt(0)
	v_mfma_f32_16x16x32_bf16 v[62:65], v[146:149], v[162:165], v[62:65]
	v_mfma_f32_16x16x32_bf16 v[58:61], v[154:157], v[162:165], v[58:61]
	v_mfma_f32_16x16x32_bf16 v[54:57], v[146:149], v[170:173], v[54:57]
	v_mfma_f32_16x16x32_bf16 v[50:53], v[154:157], v[170:173], v[50:53]
	v_mfma_f32_16x16x32_bf16 v[38:41], v[146:149], v[192:195], v[38:41]
	v_mfma_f32_16x16x32_bf16 v[34:37], v[154:157], v[192:195], v[34:37]
	v_mfma_f32_16x16x32_bf16 v[22:25], v[146:149], v[200:203], v[22:25]
	v_mfma_f32_16x16x32_bf16 v[18:21], v[154:157], v[200:203], v[18:21]
	v_mfma_f32_16x16x32_bf16 v[62:65], v[150:153], v[166:169], v[62:65]
	v_mfma_f32_16x16x32_bf16 v[58:61], v[158:161], v[166:169], v[58:61]
	v_mfma_f32_16x16x32_bf16 v[54:57], v[150:153], v[174:177], v[54:57]
	v_mfma_f32_16x16x32_bf16 v[50:53], v[158:161], v[174:177], v[50:53]
	v_mfma_f32_16x16x32_bf16 v[38:41], v[150:153], v[196:199], v[38:41]
	v_mfma_f32_16x16x32_bf16 v[34:37], v[158:161], v[196:199], v[34:37]
	v_mfma_f32_16x16x32_bf16 v[22:25], v[150:153], v[204:207], v[22:25]
	v_mfma_f32_16x16x32_bf16 v[18:21], v[158:161], v[204:207], v[18:21]
	s_barrier
	s_add_u32 s22, s38, 0x20080
	s_addc_u32 s23, s39, 0
	s_add_i32 s38, s51, s26
	v_lshl_add_u64 v[146:147], s[22:23], 0, v[134:135]
	s_mov_b32 m0, s38
	s_nop 0
	global_load_lds_dwordx4 v[146:147], off
	v_lshl_add_u64 v[146:147], s[22:23], 0, v[130:131]
	s_add_i32 m0, s38, 0x2000
	s_nop 0
	global_load_lds_dwordx4 v[146:147], off
	v_add_u32_e32 v145, 0x10000, v142
	ds_read_b128 v[146:149], v145
	ds_read_b128 v[150:153], v145 offset:1024
	ds_read_b128 v[154:157], v145 offset:2048
	ds_read_b128 v[158:161], v145 offset:3072
	s_add_i32 s49, s49, 2
	s_add_u32 s20, s20, 0x100
	s_addc_u32 s21, s21, 0
	s_add_u32 s47, s47, 0x100
	s_addc_u32 s48, s48, 0
	s_cmp_gt_u32 s49, 5
	s_waitcnt vmcnt(6)
	s_barrier
	v_mfma_f32_16x16x32_bf16 v[46:49], v[208:211], v[162:165], v[46:49]
	v_mfma_f32_16x16x32_bf16 v[42:45], v[228:231], v[162:165], v[42:45]
	v_mfma_f32_16x16x32_bf16 v[30:33], v[208:211], v[170:173], v[30:33]
	v_mfma_f32_16x16x32_bf16 v[26:29], v[228:231], v[170:173], v[26:29]
	v_mfma_f32_16x16x32_bf16 v[14:17], v[208:211], v[192:195], v[14:17]
	v_mfma_f32_16x16x32_bf16 v[10:13], v[228:231], v[192:195], v[10:13]
	v_mfma_f32_16x16x32_bf16 v[6:9], v[208:211], v[200:203], v[6:9]
	v_mfma_f32_16x16x32_bf16 v[2:5], v[228:231], v[200:203], v[2:5]
	v_mfma_f32_16x16x32_bf16 v[46:49], v[224:227], v[166:169], v[46:49]
	v_mfma_f32_16x16x32_bf16 v[42:45], v[232:235], v[166:169], v[42:45]
	v_mfma_f32_16x16x32_bf16 v[30:33], v[224:227], v[174:177], v[30:33]
	v_mfma_f32_16x16x32_bf16 v[26:29], v[232:235], v[174:177], v[26:29]
	v_mfma_f32_16x16x32_bf16 v[14:17], v[224:227], v[196:199], v[14:17]
	v_mfma_f32_16x16x32_bf16 v[10:13], v[232:235], v[196:199], v[10:13]
	v_mfma_f32_16x16x32_bf16 v[6:9], v[224:227], v[204:207], v[6:9]
	v_mfma_f32_16x16x32_bf16 v[2:5], v[232:235], v[204:207], v[2:5]
	s_barrier
	s_cbranch_scc0 .LBB0_127
	s_waitcnt lgkmcnt(0)
	v_lshl_add_u32 v146, s46, 8, v1
	v_lshl_or_b32 v148, s45, 8, v143
	v_ashrrev_i32_e32 v147, 31, v146
	v_readlane_b32 s48, v254, 40
	v_ashrrev_i32_e32 v149, 31, v148
	v_lshlrev_b64 v[150:151], 12, v[146:147]
	v_readlane_b32 s52, v254, 44
	v_readlane_b32 s53, v254, 45
	v_lshlrev_b64 v[148:149], 1, v[148:149]
	s_mov_b32 s19, 0x80000
	v_lshl_add_u64 v[150:151], s[52:53], 0, v[150:151]
	v_lshl_add_u64 v[150:151], v[150:151], 0, v[148:149]
	s_mov_b64 s[20:21], 0x80000
	v_cvt_pk_bf16_f32 v62, v62, v63
	v_cvt_pk_bf16_f32 v63, v64, v65
	v_cvt_pk_bf16_f32 v64, v58, v59
	v_add_co_u32_e32 v58, vcc, s19, v150
	v_cvt_pk_bf16_f32 v70, v70, v71
	v_cvt_pk_bf16_f32 v71, v72, v73
	v_cvt_pk_bf16_f32 v72, v66, v67
	v_lshl_add_u64 v[66:67], v[150:151], 0, s[20:21]
	v_addc_co_u32_e32 v59, vcc, 0, v151, vcc
	v_cvt_pk_bf16_f32 v46, v46, v47
	v_cvt_pk_bf16_f32 v47, v48, v49
	v_cvt_pk_bf16_f32 v48, v42, v43
	v_cvt_pk_bf16_f32 v49, v44, v45
	s_mov_b32 s19, 0x90000
	v_cvt_pk_bf16_f32 v110, v110, v111
	v_cvt_pk_bf16_f32 v111, v112, v113
	v_cvt_pk_bf16_f32 v112, v106, v107
	v_or_b32_e32 v106, 16, v146
	global_store_dwordx4 v[66:67], v[46:49], off offset:256
	s_mov_b64 s[20:21], 0x90000
	v_ashrrev_i32_e32 v107, 31, v106
	v_add_co_u32_e32 v48, vcc, s19, v150
	v_cvt_pk_bf16_f32 v94, v94, v95
	v_cvt_pk_bf16_f32 v95, v96, v97
	v_cvt_pk_bf16_f32 v96, v90, v91
	v_or_b32_e32 v90, 32, v146
	v_lshl_add_u64 v[46:47], v[150:151], 0, s[20:21]
	v_addc_co_u32_e32 v49, vcc, 0, v151, vcc
	v_cvt_pk_bf16_f32 v30, v30, v31
	v_cvt_pk_bf16_f32 v31, v32, v33
	v_cvt_pk_bf16_f32 v32, v26, v27
	v_cvt_pk_bf16_f32 v33, v28, v29
	s_mov_b32 s19, 0xa0000
	v_lshlrev_b64 v[106:107], 12, v[106:107]
	v_ashrrev_i32_e32 v91, 31, v90
	v_cvt_pk_bf16_f32 v78, v78, v79
	v_cvt_pk_bf16_f32 v79, v80, v81
	v_cvt_pk_bf16_f32 v80, v74, v75
	v_or_b32_e32 v74, 48, v146
	global_store_dwordx4 v[46:47], v[30:33], off offset:256
	s_mov_b64 s[20:21], 0xa0000
	v_cvt_pk_bf16_f32 v113, v108, v109
	v_add_co_u32_e32 v32, vcc, s19, v150
	v_lshl_add_u64 v[106:107], s[52:53], 0, v[106:107]
	v_lshlrev_b64 v[90:91], 12, v[90:91]
	v_ashrrev_i32_e32 v75, 31, v74
	v_lshl_add_u64 v[30:31], v[150:151], 0, s[20:21]
	v_addc_co_u32_e32 v33, vcc, 0, v151, vcc
	v_cvt_pk_bf16_f32 v14, v14, v15
	v_cvt_pk_bf16_f32 v15, v16, v17
	v_cvt_pk_bf16_f32 v16, v10, v11
	v_cvt_pk_bf16_f32 v17, v12, v13
	s_mov_b32 s19, 0xb0000
	global_store_dwordx4 v[150:151], v[110:113], off offset:256
	v_cvt_pk_bf16_f32 v97, v92, v93
	v_lshl_add_u64 v[90:91], s[52:53], 0, v[90:91]
	v_lshl_add_u64 v[110:111], v[106:107], 0, v[148:149]
	v_lshlrev_b64 v[74:75], 12, v[74:75]
	global_store_dwordx4 v[30:31], v[14:17], off offset:256
	global_store_dwordx4 v[110:111], v[94:97], off offset:256
	v_cvt_pk_bf16_f32 v81, v76, v77
	v_add_co_u32_e32 v16, vcc, s19, v150
	v_lshl_add_u64 v[94:95], v[90:91], 0, v[148:149]
	v_lshl_add_u64 v[74:75], s[52:53], 0, v[74:75]
	s_mov_b64 s[20:21], 0xb0000
	v_addc_co_u32_e32 v17, vcc, 0, v151, vcc
	v_cvt_pk_bf16_f32 v126, v126, v127
	v_cvt_pk_bf16_f32 v127, v128, v129
	v_cvt_pk_bf16_f32 v128, v122, v123
	v_cvt_pk_bf16_f32 v129, v124, v125
	v_cvt_pk_bf16_f32 v106, v118, v119
	v_cvt_pk_bf16_f32 v107, v120, v121
	v_cvt_pk_bf16_f32 v108, v114, v115
	v_cvt_pk_bf16_f32 v109, v116, v117
	v_cvt_pk_bf16_f32 v90, v102, v103
	v_cvt_pk_bf16_f32 v91, v104, v105
	v_cvt_pk_bf16_f32 v92, v98, v99
	v_cvt_pk_bf16_f32 v93, v100, v101
	global_store_dwordx4 v[94:95], v[78:81], off offset:256
	v_cvt_pk_bf16_f32 v76, v82, v83
	v_cvt_pk_bf16_f32 v77, v84, v85
	v_lshl_add_u64 v[78:79], v[74:75], 0, v[148:149]
	v_cvt_pk_bf16_f32 v74, v86, v87
	v_cvt_pk_bf16_f32 v75, v88, v89
	v_cvt_pk_bf16_f32 v73, v68, v69
	v_cvt_pk_bf16_f32 v65, v60, v61
	v_cvt_pk_bf16_f32 v42, v54, v55
	v_cvt_pk_bf16_f32 v43, v56, v57
	v_cvt_pk_bf16_f32 v44, v50, v51
	v_cvt_pk_bf16_f32 v45, v52, v53
	v_cvt_pk_bf16_f32 v26, v38, v39
	v_cvt_pk_bf16_f32 v27, v40, v41
	v_cvt_pk_bf16_f32 v28, v34, v35
	v_cvt_pk_bf16_f32 v29, v36, v37
	v_lshl_add_u64 v[14:15], v[150:151], 0, s[20:21]
	v_cvt_pk_bf16_f32 v10, v22, v23
	v_cvt_pk_bf16_f32 v11, v24, v25
	v_cvt_pk_bf16_f32 v12, v18, v19
	v_cvt_pk_bf16_f32 v13, v20, v21
	v_cvt_pk_bf16_f32 v6, v6, v7
	v_cvt_pk_bf16_f32 v7, v8, v9
	v_cvt_pk_bf16_f32 v8, v2, v3
	v_cvt_pk_bf16_f32 v9, v4, v5
	s_and_b64 vcc, exec, s[0:1]
	s_mov_b32 s45, s18
	s_mov_b32 s46, s30
	s_mov_b64 s[22:23], s[82:83]
	s_mov_b64 s[20:21], s[80:81]
	s_mov_b32 s64, 0x800000
	s_movk_i32 s65, 0x1fff
	v_readlane_b32 s49, v254, 41
	v_readlane_b32 s50, v254, 42
	v_readlane_b32 s51, v254, 43
	v_readlane_b32 s54, v254, 46
	v_readlane_b32 s55, v254, 47
	v_readlane_b32 s56, v254, 48
	v_readlane_b32 s57, v254, 49
	v_readlane_b32 s58, v254, 50
	v_readlane_b32 s59, v254, 51
	v_readlane_b32 s60, v254, 52
	v_readlane_b32 s61, v254, 53
	v_readlane_b32 s62, v254, 54
	v_readlane_b32 s63, v254, 55
	global_store_dwordx4 v[150:151], v[126:129], off
	global_store_dwordx4 v[110:111], v[106:109], off
	global_store_dwordx4 v[94:95], v[90:93], off
	global_store_dwordx4 v[78:79], v[74:77], off
	global_store_dwordx4 v[78:79], v[70:73], off offset:256
	global_store_dwordx4 v[58:59], v[62:65], off
	global_store_dwordx4 v[48:49], v[42:45], off
	global_store_dwordx4 v[32:33], v[26:29], off
	global_store_dwordx4 v[16:17], v[10:13], off
	global_store_dwordx4 v[14:15], v[6:9], off offset:256
	s_cbranch_vccz .LBB0_118
	s_waitcnt vmcnt(0)
	v_readlane_b32 s44, v255, 30
	s_mov_b32 s66, s90
	s_cmpk_gt_u32 s25, 0xff
	v_readlane_b32 s45, v255, 31
	v_readlane_b32 s42, v255, 32
	s_cbranch_scc1 .LBB0_131
	s_barrier

.LBB0_240:
	s_add_u32 s22, s80, 0xfff80080
	s_addc_u32 s23, s81, -1
	s_add_i32 s52, 0, 0x10000
	s_cmp_eq_u32 s51, 28
	s_cselect_b32 s23, s21, s23
	s_cselect_b32 s22, s47, s22
	s_cselect_b32 s83, s19, s50
	s_cselect_b32 s82, s48, s49
	v_lshl_add_u64 v[178:179], s[80:81], 0, v[134:135]
	s_add_i32 m0, s27, 0xc000
	ds_read_b128 v[158:161], v140
	ds_read_b128 v[162:165], v140 offset:1024
	ds_read_b128 v[166:169], v140 offset:2048
	ds_read_b128 v[170:173], v140 offset:3072
	ds_read_b128 v[174:177], v140 offset:4096
	ds_read_b128 v[192:195], v140 offset:5120
	ds_read_b128 v[196:199], v140 offset:6144
	ds_read_b128 v[200:203], v140 offset:7168
	global_load_lds_dwordx4 v[178:179], off
	v_lshl_add_u64 v[178:179], s[80:81], 0, v[136:137]
	s_add_i32 m0, s27, 0xe000
	s_nop 0
	global_load_lds_dwordx4 v[178:179], off
	s_waitcnt lgkmcnt(8)
	s_barrier
	s_waitcnt lgkmcnt(0)
	v_mfma_f32_16x16x32_bf16 v[126:129], v[142:145], v[158:161], v[126:129]
	v_mfma_f32_16x16x32_bf16 v[122:125], v[150:153], v[158:161], v[122:125]
	v_mfma_f32_16x16x32_bf16 v[118:121], v[142:145], v[166:169], v[118:121]
	v_mfma_f32_16x16x32_bf16 v[114:117], v[150:153], v[166:169], v[114:117]
	v_mfma_f32_16x16x32_bf16 v[110:113], v[142:145], v[174:177], v[110:113]
	v_mfma_f32_16x16x32_bf16 v[102:105], v[150:153], v[174:177], v[102:105]
	v_mfma_f32_16x16x32_bf16 v[94:97], v[142:145], v[196:199], v[94:97]
	v_mfma_f32_16x16x32_bf16 v[86:89], v[150:153], v[196:199], v[86:89]
	v_mfma_f32_16x16x32_bf16 v[126:129], v[146:149], v[162:165], v[126:129]
	v_mfma_f32_16x16x32_bf16 v[122:125], v[154:157], v[162:165], v[122:125]
	v_mfma_f32_16x16x32_bf16 v[118:121], v[146:149], v[170:173], v[118:121]
	v_mfma_f32_16x16x32_bf16 v[114:117], v[154:157], v[170:173], v[114:117]
	v_mfma_f32_16x16x32_bf16 v[110:113], v[146:149], v[192:195], v[110:113]
	v_mfma_f32_16x16x32_bf16 v[102:105], v[154:157], v[192:195], v[102:105]
	v_mfma_f32_16x16x32_bf16 v[94:97], v[146:149], v[200:203], v[94:97]
	v_mfma_f32_16x16x32_bf16 v[86:89], v[154:157], v[200:203], v[86:89]
	s_barrier
	s_add_i32 s54, 0, 0x14000
	s_add_i32 s52, s52, s26
	v_add_u32_e32 v141, s54, v138
	v_lshl_add_u64 v[178:179], s[82:83], 0, v[132:133]
	s_mov_b32 m0, s52
	ds_read_b128 v[204:207], v141
	ds_read_b128 v[208:211], v141 offset:1024
	ds_read_b128 v[224:227], v141 offset:2048
	ds_read_b128 v[228:231], v141 offset:3072
	global_load_lds_dwordx4 v[178:179], off
	v_lshl_add_u64 v[212:213], s[82:83], 0, v[130:131]
	s_add_i32 m0, s52, 0x2000
	s_nop 0
	global_load_lds_dwordx4 v[212:213], off
	s_mov_b32 m0, s27
	v_lshl_add_u64 v[232:233], s[22:23], 0, v[132:133]
	s_barrier
	s_waitcnt lgkmcnt(0)
	v_mfma_f32_16x16x32_bf16 v[106:109], v[204:207], v[158:161], v[106:109]
	v_mfma_f32_16x16x32_bf16 v[98:101], v[224:227], v[158:161], v[98:101]
	v_mfma_f32_16x16x32_bf16 v[90:93], v[204:207], v[166:169], v[90:93]
	v_mfma_f32_16x16x32_bf16 v[82:85], v[224:227], v[166:169], v[82:85]
	v_mfma_f32_16x16x32_bf16 v[78:81], v[204:207], v[174:177], v[78:81]
	v_mfma_f32_16x16x32_bf16 v[74:77], v[224:227], v[174:177], v[74:77]
	v_mfma_f32_16x16x32_bf16 v[70:73], v[204:207], v[196:199], v[70:73]
	v_mfma_f32_16x16x32_bf16 v[66:69], v[224:227], v[196:199], v[66:69]
	v_mfma_f32_16x16x32_bf16 v[106:109], v[208:211], v[162:165], v[106:109]
	v_mfma_f32_16x16x32_bf16 v[98:101], v[228:231], v[162:165], v[98:101]
	v_mfma_f32_16x16x32_bf16 v[90:93], v[208:211], v[170:173], v[90:93]
	v_mfma_f32_16x16x32_bf16 v[82:85], v[228:231], v[170:173], v[82:85]
	v_mfma_f32_16x16x32_bf16 v[78:81], v[208:211], v[192:195], v[78:81]
	v_mfma_f32_16x16x32_bf16 v[74:77], v[228:231], v[192:195], v[74:77]
	v_mfma_f32_16x16x32_bf16 v[70:73], v[208:211], v[200:203], v[70:73]
	v_mfma_f32_16x16x32_bf16 v[66:69], v[228:231], v[200:203], v[66:69]
	s_barrier
	ds_read_b128 v[158:161], v140 offset:16384
	ds_read_b128 v[162:165], v140 offset:17408
	ds_read_b128 v[166:169], v140 offset:18432
	ds_read_b128 v[170:173], v140 offset:19456
	ds_read_b128 v[174:177], v140 offset:20480
	ds_read_b128 v[192:195], v140 offset:21504
	ds_read_b128 v[196:199], v140 offset:22528
	ds_read_b128 v[200:203], v140 offset:23552
	global_load_lds_dwordx4 v[232:233], off
	v_lshl_add_u64 v[234:235], s[22:23], 0, v[130:131]
	s_mov_b32 m0, s28
	s_nop 0
	global_load_lds_dwordx4 v[234:235], off
	s_waitcnt vmcnt(10)
	s_barrier
	s_waitcnt lgkmcnt(0)
	v_mfma_f32_16x16x32_bf16 v[62:65], v[142:145], v[158:161], v[62:65]
	v_mfma_f32_16x16x32_bf16 v[58:61], v[150:153], v[158:161], v[58:61]
	v_mfma_f32_16x16x32_bf16 v[54:57], v[142:145], v[166:169], v[54:57]
	v_mfma_f32_16x16x32_bf16 v[50:53], v[150:153], v[166:169], v[50:53]
	v_mfma_f32_16x16x32_bf16 v[46:49], v[142:145], v[174:177], v[46:49]
	v_mfma_f32_16x16x32_bf16 v[38:41], v[150:153], v[174:177], v[38:41]
	v_mfma_f32_16x16x32_bf16 v[30:33], v[142:145], v[196:199], v[30:33]
	v_mfma_f32_16x16x32_bf16 v[22:25], v[150:153], v[196:199], v[22:25]
	v_mfma_f32_16x16x32_bf16 v[62:65], v[146:149], v[162:165], v[62:65]
	v_mfma_f32_16x16x32_bf16 v[58:61], v[154:157], v[162:165], v[58:61]
	v_mfma_f32_16x16x32_bf16 v[54:57], v[146:149], v[170:173], v[54:57]
	v_mfma_f32_16x16x32_bf16 v[50:53], v[154:157], v[170:173], v[50:53]
	v_mfma_f32_16x16x32_bf16 v[46:49], v[146:149], v[192:195], v[46:49]
	v_mfma_f32_16x16x32_bf16 v[38:41], v[154:157], v[192:195], v[38:41]
	v_mfma_f32_16x16x32_bf16 v[30:33], v[146:149], v[200:203], v[30:33]
	v_mfma_f32_16x16x32_bf16 v[22:25], v[154:157], v[200:203], v[22:25]
	s_barrier
	s_add_u32 s52, s82, 0x80000
	s_addc_u32 s53, s83, 0
	s_add_i32 s54, s54, s26
	v_lshl_add_u64 v[142:143], s[52:53], 0, v[132:133]
	s_mov_b32 m0, s54
	s_nop 0
	global_load_lds_dwordx4 v[142:143], off
	v_lshl_add_u64 v[142:143], s[52:53], 0, v[130:131]
	s_add_i32 m0, s54, 0x2000
	s_nop 0
	global_load_lds_dwordx4 v[142:143], off
	v_add_u32_e32 v141, 0x18000, v138
	ds_read_b128 v[142:145], v141
	ds_read_b128 v[146:149], v141 offset:1024
	ds_read_b128 v[150:153], v141 offset:2048
	ds_read_b128 v[154:157], v141 offset:3072
	s_add_i32 s52, 0, 0x18000
	s_waitcnt vmcnt(6)
	s_barrier
	v_mfma_f32_16x16x32_bf16 v[42:45], v[204:207], v[158:161], v[42:45]
	v_mfma_f32_16x16x32_bf16 v[34:37], v[224:227], v[158:161], v[34:37]
	v_mfma_f32_16x16x32_bf16 v[26:29], v[204:207], v[166:169], v[26:29]
	v_mfma_f32_16x16x32_bf16 v[18:21], v[224:227], v[166:169], v[18:21]
	v_mfma_f32_16x16x32_bf16 v[14:17], v[204:207], v[174:177], v[14:17]
	v_mfma_f32_16x16x32_bf16 v[10:13], v[224:227], v[174:177], v[10:13]
	v_mfma_f32_16x16x32_bf16 v[6:9], v[204:207], v[196:199], v[6:9]
	v_mfma_f32_16x16x32_bf16 v[2:5], v[224:227], v[196:199], v[2:5]
	v_mfma_f32_16x16x32_bf16 v[42:45], v[208:211], v[162:165], v[42:45]
	v_mfma_f32_16x16x32_bf16 v[34:37], v[228:231], v[162:165], v[34:37]
	v_mfma_f32_16x16x32_bf16 v[26:29], v[208:211], v[170:173], v[26:29]
	v_mfma_f32_16x16x32_bf16 v[18:21], v[228:231], v[170:173], v[18:21]
	v_mfma_f32_16x16x32_bf16 v[14:17], v[208:211], v[192:195], v[14:17]
	v_mfma_f32_16x16x32_bf16 v[10:13], v[228:231], v[192:195], v[10:13]
	v_mfma_f32_16x16x32_bf16 v[6:9], v[208:211], v[200:203], v[6:9]
	v_mfma_f32_16x16x32_bf16 v[2:5], v[228:231], v[200:203], v[2:5]
	s_barrier
	s_add_u32 s22, s22, 0x80000
	s_addc_u32 s23, s23, 0
	s_mov_b32 m0, s29
	v_lshl_add_u64 v[204:205], s[22:23], 0, v[132:133]
	ds_read_b128 v[158:161], v140 offset:32768
	ds_read_b128 v[162:165], v140 offset:33792
	ds_read_b128 v[166:169], v140 offset:34816
	ds_read_b128 v[170:173], v140 offset:35840
	ds_read_b128 v[174:177], v140 offset:36864
	ds_read_b128 v[192:195], v140 offset:37888
	ds_read_b128 v[196:199], v140 offset:38912
	ds_read_b128 v[200:203], v140 offset:39936
	global_load_lds_dwordx4 v[204:205], off
	v_lshl_add_u64 v[204:205], s[22:23], 0, v[130:131]
	s_mov_b32 m0, s36
	s_nop 0
	global_load_lds_dwordx4 v[204:205], off
	s_waitcnt lgkmcnt(8)
	s_barrier
	s_waitcnt lgkmcnt(0)
	v_mfma_f32_16x16x32_bf16 v[126:129], v[142:145], v[158:161], v[126:129]
	v_mfma_f32_16x16x32_bf16 v[122:125], v[150:153], v[158:161], v[122:125]
	v_mfma_f32_16x16x32_bf16 v[118:121], v[142:145], v[166:169], v[118:121]
	v_mfma_f32_16x16x32_bf16 v[114:117], v[150:153], v[166:169], v[114:117]
	v_mfma_f32_16x16x32_bf16 v[110:113], v[142:145], v[174:177], v[110:113]
	v_mfma_f32_16x16x32_bf16 v[102:105], v[150:153], v[174:177], v[102:105]
	v_mfma_f32_16x16x32_bf16 v[94:97], v[142:145], v[196:199], v[94:97]
	v_mfma_f32_16x16x32_bf16 v[86:89], v[150:153], v[196:199], v[86:89]
	v_mfma_f32_16x16x32_bf16 v[126:129], v[146:149], v[162:165], v[126:129]
	v_mfma_f32_16x16x32_bf16 v[122:125], v[154:157], v[162:165], v[122:125]
	v_mfma_f32_16x16x32_bf16 v[118:121], v[146:149], v[170:173], v[118:121]
	v_mfma_f32_16x16x32_bf16 v[114:117], v[154:157], v[170:173], v[114:117]
	v_mfma_f32_16x16x32_bf16 v[110:113], v[146:149], v[192:195], v[110:113]
	v_mfma_f32_16x16x32_bf16 v[102:105], v[154:157], v[192:195], v[102:105]
	v_mfma_f32_16x16x32_bf16 v[94:97], v[146:149], v[200:203], v[94:97]
	v_mfma_f32_16x16x32_bf16 v[86:89], v[154:157], v[200:203], v[86:89]
	s_barrier
	s_add_i32 s53, 0, 0x1c000
	s_add_i32 s22, s52, s26
	v_add_u32_e32 v141, s53, v138
	v_lshl_add_u64 v[178:179], v[178:179], 0, s[78:79]
	s_mov_b32 m0, s22
	ds_read_b128 v[204:207], v141
	ds_read_b128 v[208:211], v141 offset:1024
	ds_read_b128 v[224:227], v141 offset:2048
	ds_read_b128 v[228:231], v141 offset:3072
	global_load_lds_dwordx4 v[178:179], off
	v_lshl_add_u64 v[178:179], v[212:213], 0, s[78:79]
	s_add_i32 m0, s22, 0x2000
	s_nop 0
	global_load_lds_dwordx4 v[178:179], off
	s_mov_b32 m0, s42
	v_lshl_add_u64 v[178:179], v[232:233], 0, s[78:79]
	s_barrier
	s_waitcnt lgkmcnt(0)
	v_mfma_f32_16x16x32_bf16 v[106:109], v[204:207], v[158:161], v[106:109]
	v_mfma_f32_16x16x32_bf16 v[98:101], v[224:227], v[158:161], v[98:101]
	v_mfma_f32_16x16x32_bf16 v[90:93], v[204:207], v[166:169], v[90:93]
	v_mfma_f32_16x16x32_bf16 v[82:85], v[224:227], v[166:169], v[82:85]
	v_mfma_f32_16x16x32_bf16 v[78:81], v[204:207], v[174:177], v[78:81]
	v_mfma_f32_16x16x32_bf16 v[74:77], v[224:227], v[174:177], v[74:77]
	v_mfma_f32_16x16x32_bf16 v[70:73], v[204:207], v[196:199], v[70:73]
	v_mfma_f32_16x16x32_bf16 v[66:69], v[224:227], v[196:199], v[66:69]
	v_mfma_f32_16x16x32_bf16 v[106:109], v[208:211], v[162:165], v[106:109]
	v_mfma_f32_16x16x32_bf16 v[98:101], v[228:231], v[162:165], v[98:101]
	v_mfma_f32_16x16x32_bf16 v[90:93], v[208:211], v[170:173], v[90:93]
	v_mfma_f32_16x16x32_bf16 v[82:85], v[228:231], v[170:173], v[82:85]
	v_mfma_f32_16x16x32_bf16 v[78:81], v[208:211], v[192:195], v[78:81]
	v_mfma_f32_16x16x32_bf16 v[74:77], v[228:231], v[192:195], v[74:77]
	v_mfma_f32_16x16x32_bf16 v[70:73], v[208:211], v[200:203], v[70:73]
	v_mfma_f32_16x16x32_bf16 v[66:69], v[228:231], v[200:203], v[66:69]
	s_barrier
	ds_read_b128 v[158:161], v140 offset:49152
	ds_read_b128 v[162:165], v140 offset:50176
	ds_read_b128 v[166:169], v140 offset:51200
	ds_read_b128 v[170:173], v140 offset:52224
	ds_read_b128 v[174:177], v140 offset:53248
	ds_read_b128 v[192:195], v140 offset:54272
	ds_read_b128 v[196:199], v140 offset:55296
	ds_read_b128 v[200:203], v140 offset:56320
	global_load_lds_dwordx4 v[178:179], off
	v_lshl_add_u64 v[178:179], v[234:235], 0, s[78:79]
	s_mov_b32 m0, s43
	s_nop 0
	global_load_lds_dwordx4 v[178:179], off
	s_waitcnt vmcnt(10)
	s_barrier
	s_waitcnt lgkmcnt(0)
	v_mfma_f32_16x16x32_bf16 v[62:65], v[142:145], v[158:161], v[62:65]
	v_mfma_f32_16x16x32_bf16 v[58:61], v[150:153], v[158:161], v[58:61]
	v_mfma_f32_16x16x32_bf16 v[54:57], v[142:145], v[166:169], v[54:57]
	v_mfma_f32_16x16x32_bf16 v[50:53], v[150:153], v[166:169], v[50:53]
	v_mfma_f32_16x16x32_bf16 v[46:49], v[142:145], v[174:177], v[46:49]
	v_mfma_f32_16x16x32_bf16 v[38:41], v[150:153], v[174:177], v[38:41]
	v_mfma_f32_16x16x32_bf16 v[30:33], v[142:145], v[196:199], v[30:33]
	v_mfma_f32_16x16x32_bf16 v[22:25], v[150:153], v[196:199], v[22:25]
	v_mfma_f32_16x16x32_bf16 v[62:65], v[146:149], v[162:165], v[62:65]
	v_mfma_f32_16x16x32_bf16 v[58:61], v[154:157], v[162:165], v[58:61]
	v_mfma_f32_16x16x32_bf16 v[54:57], v[146:149], v[170:173], v[54:57]
	v_mfma_f32_16x16x32_bf16 v[50:53], v[154:157], v[170:173], v[50:53]
	v_mfma_f32_16x16x32_bf16 v[46:49], v[146:149], v[192:195], v[46:49]
	v_mfma_f32_16x16x32_bf16 v[38:41], v[154:157], v[192:195], v[38:41]
	v_mfma_f32_16x16x32_bf16 v[30:33], v[146:149], v[200:203], v[30:33]
	v_mfma_f32_16x16x32_bf16 v[22:25], v[154:157], v[200:203], v[22:25]
	s_barrier
	s_add_u32 s22, s82, 0x80080
	s_addc_u32 s23, s83, 0
	s_add_i32 s52, s53, s26
	v_lshl_add_u64 v[142:143], s[22:23], 0, v[132:133]
	s_mov_b32 m0, s52
	s_nop 0
	global_load_lds_dwordx4 v[142:143], off
	v_lshl_add_u64 v[142:143], s[22:23], 0, v[130:131]
	s_add_i32 m0, s52, 0x2000
	s_nop 0
	global_load_lds_dwordx4 v[142:143], off
	v_add_u32_e32 v141, 0x10000, v138
	ds_read_b128 v[142:145], v141
	ds_read_b128 v[146:149], v141 offset:1024
	ds_read_b128 v[150:153], v141 offset:2048
	ds_read_b128 v[154:157], v141 offset:3072
	s_add_i32 s51, s51, 2
	s_add_u32 s80, s80, 0x100
	s_addc_u32 s81, s81, 0
	s_add_u32 s49, s49, 0x100
	s_addc_u32 s50, s50, 0
	s_cmp_gt_u32 s51, 29
	s_waitcnt vmcnt(6)
	s_barrier
	v_mfma_f32_16x16x32_bf16 v[42:45], v[204:207], v[158:161], v[42:45]
	v_mfma_f32_16x16x32_bf16 v[34:37], v[224:227], v[158:161], v[34:37]
	v_mfma_f32_16x16x32_bf16 v[26:29], v[204:207], v[166:169], v[26:29]
	v_mfma_f32_16x16x32_bf16 v[18:21], v[224:227], v[166:169], v[18:21]
	v_mfma_f32_16x16x32_bf16 v[14:17], v[204:207], v[174:177], v[14:17]
	v_mfma_f32_16x16x32_bf16 v[10:13], v[224:227], v[174:177], v[10:13]
	v_mfma_f32_16x16x32_bf16 v[6:9], v[204:207], v[196:199], v[6:9]
	v_mfma_f32_16x16x32_bf16 v[2:5], v[224:227], v[196:199], v[2:5]
	v_mfma_f32_16x16x32_bf16 v[42:45], v[208:211], v[162:165], v[42:45]
	v_mfma_f32_16x16x32_bf16 v[34:37], v[228:231], v[162:165], v[34:37]
	v_mfma_f32_16x16x32_bf16 v[26:29], v[208:211], v[170:173], v[26:29]
	v_mfma_f32_16x16x32_bf16 v[18:21], v[228:231], v[170:173], v[18:21]
	v_mfma_f32_16x16x32_bf16 v[14:17], v[208:211], v[192:195], v[14:17]
	v_mfma_f32_16x16x32_bf16 v[10:13], v[228:231], v[192:195], v[10:13]
	v_mfma_f32_16x16x32_bf16 v[6:9], v[208:211], v[200:203], v[6:9]
	v_mfma_f32_16x16x32_bf16 v[2:5], v[228:231], v[200:203], v[2:5]
	s_barrier
	s_cbranch_scc0 .LBB0_240
	s_waitcnt lgkmcnt(0)
	v_readlane_b32 s48, v254, 40
	v_lshl_or_b32 v142, s45, 8, v139
	v_readlane_b32 s52, v254, 44
	v_readlane_b32 s53, v254, 45
	v_lshl_add_u32 v141, s46, 8, v1
	v_ashrrev_i32_e32 v143, 31, v142
	v_mov_b64_e32 v[144:145], s[52:53]
	s_movk_i32 s19, 0x1400
	v_mad_i64_i32 v[146:147], s[22:23], v141, s19, v[144:145]
	v_lshlrev_b64 v[142:143], 2, v[142:143]
	v_lshl_add_u64 v[146:147], v[146:147], 0, v[142:143]
	global_store_dwordx4 v[146:147], v[126:129], off
	global_store_dwordx4 v[146:147], v[122:125], off offset:64
	global_store_dwordx4 v[146:147], v[106:109], off offset:512
	global_store_dwordx4 v[146:147], v[98:101], off offset:576
	s_movk_i32 s94, 0x1400
	s_and_b64 vcc, exec, s[0:1]
	v_or_b32_e32 v98, 16, v141
	v_mad_i64_i32 v[98:99], s[22:23], v98, s19, v[144:145]
	v_lshl_add_u64 v[98:99], v[98:99], 0, v[142:143]
	global_store_dwordx4 v[98:99], v[118:121], off
	global_store_dwordx4 v[98:99], v[114:117], off offset:64
	global_store_dwordx4 v[98:99], v[90:93], off offset:512
	global_store_dwordx4 v[98:99], v[82:85], off offset:576
	s_mov_b32 s45, s18
	s_mov_b32 s46, s20
	v_or_b32_e32 v82, 32, v141
	v_mad_i64_i32 v[82:83], s[22:23], v82, s19, v[144:145]
	v_lshl_add_u64 v[82:83], v[82:83], 0, v[142:143]
	global_store_dwordx4 v[82:83], v[110:113], off
	global_store_dwordx4 v[82:83], v[102:105], off offset:64
	global_store_dwordx4 v[82:83], v[78:81], off offset:512
	global_store_dwordx4 v[82:83], v[74:77], off offset:576
	s_mov_b64 s[80:81], s[30:31]
	v_readlane_b32 s49, v254, 41
	v_or_b32_e32 v74, 48, v141
	v_mad_i64_i32 v[74:75], s[22:23], v74, s19, v[144:145]
	v_lshl_add_u64 v[74:75], v[74:75], 0, v[142:143]
	global_store_dwordx4 v[74:75], v[94:97], off
	global_store_dwordx4 v[74:75], v[86:89], off offset:64
	global_store_dwordx4 v[74:75], v[70:73], off offset:512
	global_store_dwordx4 v[74:75], v[66:69], off offset:576
	v_readlane_b32 s50, v254, 42
	v_readlane_b32 s51, v254, 43
	v_add_u32_e32 v66, 0x80, v141
	v_mad_i64_i32 v[66:67], s[22:23], v66, s19, v[144:145]
	v_lshl_add_u64 v[66:67], v[66:67], 0, v[142:143]
	global_store_dwordx4 v[66:67], v[62:65], off
	global_store_dwordx4 v[66:67], v[58:61], off offset:64
	global_store_dwordx4 v[66:67], v[42:45], off offset:512
	global_store_dwordx4 v[66:67], v[34:37], off offset:576
	v_readlane_b32 s54, v254, 46
	v_readlane_b32 s55, v254, 47
	v_add_u32_e32 v34, 0x90, v141
	v_mad_i64_i32 v[34:35], s[22:23], v34, s19, v[144:145]
	v_lshl_add_u64 v[34:35], v[34:35], 0, v[142:143]
	global_store_dwordx4 v[34:35], v[54:57], off
	global_store_dwordx4 v[34:35], v[50:53], off offset:64
	global_store_dwordx4 v[34:35], v[26:29], off offset:512
	global_store_dwordx4 v[34:35], v[18:21], off offset:576
	v_readlane_b32 s56, v254, 48
	v_readlane_b32 s57, v254, 49
	v_add_u32_e32 v18, 0xa0, v141
	v_mad_i64_i32 v[18:19], s[22:23], v18, s19, v[144:145]
	v_lshl_add_u64 v[18:19], v[18:19], 0, v[142:143]
	global_store_dwordx4 v[18:19], v[46:49], off
	global_store_dwordx4 v[18:19], v[38:41], off offset:64
	global_store_dwordx4 v[18:19], v[14:17], off offset:512
	global_store_dwordx4 v[18:19], v[10:13], off offset:576
	v_readlane_b32 s58, v254, 50
	v_readlane_b32 s59, v254, 51
	v_add_u32_e32 v10, 0xb0, v141
	v_mad_i64_i32 v[10:11], s[22:23], v10, s19, v[144:145]
	v_lshl_add_u64 v[10:11], v[10:11], 0, v[142:143]
	s_mov_b64 s[22:23], s[38:39]
	v_readlane_b32 s60, v254, 52
	v_readlane_b32 s61, v254, 53
	v_readlane_b32 s62, v254, 54
	v_readlane_b32 s63, v254, 55
	global_store_dwordx4 v[10:11], v[30:33], off
	global_store_dwordx4 v[10:11], v[22:25], off offset:64
	global_store_dwordx4 v[10:11], v[6:9], off offset:512
	global_store_dwordx4 v[10:11], v[2:5], off offset:576
	s_cbranch_vccz .LBB0_237
	s_waitcnt vmcnt(0)
	v_readlane_b32 s44, v255, 30
	s_cmpk_gt_u32 s25, 0xff
	v_readlane_b32 s45, v255, 31
	v_readlane_b32 s42, v255, 32
	s_cbranch_scc1 .LBB0_244
	s_barrier

.LBB0_357:
	s_add_u32 s22, s20, 0xfffe0080
	s_addc_u32 s23, s21, -1
	s_add_i32 s52, 0, 0x10000
	s_cmp_eq_u32 s51, 4
	s_cselect_b32 s23, s31, s23
	s_cselect_b32 s22, s47, s22
	s_cselect_b32 s85, s19, s50
	s_cselect_b32 s84, s48, s49
	v_lshl_add_u64 v[178:179], s[20:21], 0, v[138:139]
	s_add_i32 m0, s27, 0xc000
	ds_read_b128 v[162:165], v144
	ds_read_b128 v[166:169], v144 offset:1024
	ds_read_b128 v[170:173], v144 offset:2048
	ds_read_b128 v[174:177], v144 offset:3072
	ds_read_b128 v[192:195], v144 offset:4096
	ds_read_b128 v[196:199], v144 offset:5120
	ds_read_b128 v[200:203], v144 offset:6144
	ds_read_b128 v[204:207], v144 offset:7168
	global_load_lds_dwordx4 v[178:179], off
	v_lshl_add_u64 v[178:179], s[20:21], 0, v[140:141]
	s_add_i32 m0, s27, 0xe000
	s_nop 0
	global_load_lds_dwordx4 v[178:179], off
	s_waitcnt lgkmcnt(8)
	s_barrier
	s_waitcnt lgkmcnt(0)
	v_mfma_f32_16x16x32_bf16 v[126:129], v[146:149], v[162:165], v[126:129]
	v_mfma_f32_16x16x32_bf16 v[122:125], v[154:157], v[162:165], v[122:125]
	v_mfma_f32_16x16x32_bf16 v[118:121], v[146:149], v[170:173], v[118:121]
	v_mfma_f32_16x16x32_bf16 v[114:117], v[154:157], v[170:173], v[114:117]
	v_mfma_f32_16x16x32_bf16 v[102:105], v[146:149], v[192:195], v[102:105]
	v_mfma_f32_16x16x32_bf16 v[98:101], v[154:157], v[192:195], v[98:101]
	v_mfma_f32_16x16x32_bf16 v[86:89], v[146:149], v[200:203], v[86:89]
	v_mfma_f32_16x16x32_bf16 v[82:85], v[154:157], v[200:203], v[82:85]
	v_mfma_f32_16x16x32_bf16 v[126:129], v[150:153], v[166:169], v[126:129]
	v_mfma_f32_16x16x32_bf16 v[122:125], v[158:161], v[166:169], v[122:125]
	v_mfma_f32_16x16x32_bf16 v[118:121], v[150:153], v[174:177], v[118:121]
	v_mfma_f32_16x16x32_bf16 v[114:117], v[158:161], v[174:177], v[114:117]
	v_mfma_f32_16x16x32_bf16 v[102:105], v[150:153], v[196:199], v[102:105]
	v_mfma_f32_16x16x32_bf16 v[98:101], v[158:161], v[196:199], v[98:101]
	v_mfma_f32_16x16x32_bf16 v[86:89], v[150:153], v[204:207], v[86:89]
	v_mfma_f32_16x16x32_bf16 v[82:85], v[158:161], v[204:207], v[82:85]
	s_barrier
	s_add_i32 s54, 0, 0x14000
	s_add_i32 s52, s52, s26
	v_add_u32_e32 v145, s54, v142
	v_lshl_add_u64 v[178:179], s[84:85], 0, v[134:135]
	s_mov_b32 m0, s52
	ds_read_b128 v[208:211], v145
	ds_read_b128 v[224:227], v145 offset:1024
	ds_read_b128 v[228:231], v145 offset:2048
	ds_read_b128 v[232:235], v145 offset:3072
	global_load_lds_dwordx4 v[178:179], off
	v_lshl_add_u64 v[212:213], s[84:85], 0, v[130:131]
	s_add_i32 m0, s52, 0x2000
	s_nop 0
	global_load_lds_dwordx4 v[212:213], off
	s_mov_b32 m0, s27
	v_lshl_add_u64 v[236:237], s[22:23], 0, v[136:137]
	s_barrier
	s_waitcnt lgkmcnt(0)
	v_mfma_f32_16x16x32_bf16 v[110:113], v[208:211], v[162:165], v[110:113]
	v_mfma_f32_16x16x32_bf16 v[106:109], v[228:231], v[162:165], v[106:109]
	v_mfma_f32_16x16x32_bf16 v[94:97], v[208:211], v[170:173], v[94:97]
	v_mfma_f32_16x16x32_bf16 v[90:93], v[228:231], v[170:173], v[90:93]
	v_mfma_f32_16x16x32_bf16 v[78:81], v[208:211], v[192:195], v[78:81]
	v_mfma_f32_16x16x32_bf16 v[74:77], v[228:231], v[192:195], v[74:77]
	v_mfma_f32_16x16x32_bf16 v[70:73], v[208:211], v[200:203], v[70:73]
	v_mfma_f32_16x16x32_bf16 v[66:69], v[228:231], v[200:203], v[66:69]
	v_mfma_f32_16x16x32_bf16 v[110:113], v[224:227], v[166:169], v[110:113]
	v_mfma_f32_16x16x32_bf16 v[106:109], v[232:235], v[166:169], v[106:109]
	v_mfma_f32_16x16x32_bf16 v[94:97], v[224:227], v[174:177], v[94:97]
	v_mfma_f32_16x16x32_bf16 v[90:93], v[232:235], v[174:177], v[90:93]
	v_mfma_f32_16x16x32_bf16 v[78:81], v[224:227], v[196:199], v[78:81]
	v_mfma_f32_16x16x32_bf16 v[74:77], v[232:235], v[196:199], v[74:77]
	v_mfma_f32_16x16x32_bf16 v[70:73], v[224:227], v[204:207], v[70:73]
	v_mfma_f32_16x16x32_bf16 v[66:69], v[232:235], v[204:207], v[66:69]
	s_barrier
	ds_read_b128 v[162:165], v144 offset:16384
	ds_read_b128 v[166:169], v144 offset:17408
	ds_read_b128 v[170:173], v144 offset:18432
	ds_read_b128 v[174:177], v144 offset:19456
	ds_read_b128 v[192:195], v144 offset:20480
	ds_read_b128 v[196:199], v144 offset:21504
	ds_read_b128 v[200:203], v144 offset:22528
	ds_read_b128 v[204:207], v144 offset:23552
	global_load_lds_dwordx4 v[236:237], off
	v_lshl_add_u64 v[238:239], s[22:23], 0, v[132:133]
	s_mov_b32 m0, s28
	s_nop 0
	global_load_lds_dwordx4 v[238:239], off
	s_waitcnt vmcnt(10)
	s_barrier
	s_waitcnt lgkmcnt(0)
	v_mfma_f32_16x16x32_bf16 v[62:65], v[146:149], v[162:165], v[62:65]
	v_mfma_f32_16x16x32_bf16 v[58:61], v[154:157], v[162:165], v[58:61]
	v_mfma_f32_16x16x32_bf16 v[54:57], v[146:149], v[170:173], v[54:57]
	v_mfma_f32_16x16x32_bf16 v[50:53], v[154:157], v[170:173], v[50:53]
	v_mfma_f32_16x16x32_bf16 v[38:41], v[146:149], v[192:195], v[38:41]
	v_mfma_f32_16x16x32_bf16 v[34:37], v[154:157], v[192:195], v[34:37]
	v_mfma_f32_16x16x32_bf16 v[22:25], v[146:149], v[200:203], v[22:25]
	v_mfma_f32_16x16x32_bf16 v[18:21], v[154:157], v[200:203], v[18:21]
	v_mfma_f32_16x16x32_bf16 v[62:65], v[150:153], v[166:169], v[62:65]
	v_mfma_f32_16x16x32_bf16 v[58:61], v[158:161], v[166:169], v[58:61]
	v_mfma_f32_16x16x32_bf16 v[54:57], v[150:153], v[174:177], v[54:57]
	v_mfma_f32_16x16x32_bf16 v[50:53], v[158:161], v[174:177], v[50:53]
	v_mfma_f32_16x16x32_bf16 v[38:41], v[150:153], v[196:199], v[38:41]
	v_mfma_f32_16x16x32_bf16 v[34:37], v[158:161], v[196:199], v[34:37]
	v_mfma_f32_16x16x32_bf16 v[22:25], v[150:153], v[204:207], v[22:25]
	v_mfma_f32_16x16x32_bf16 v[18:21], v[158:161], v[204:207], v[18:21]
	s_barrier
	s_add_u32 s52, s84, 0x20000
	s_addc_u32 s53, s85, 0
	s_add_i32 s54, s54, s26
	v_lshl_add_u64 v[146:147], s[52:53], 0, v[134:135]
	s_mov_b32 m0, s54
	s_nop 0
	global_load_lds_dwordx4 v[146:147], off
	v_lshl_add_u64 v[146:147], s[52:53], 0, v[130:131]
	s_add_i32 m0, s54, 0x2000
	s_nop 0
	global_load_lds_dwordx4 v[146:147], off
	v_add_u32_e32 v145, 0x18000, v142
	ds_read_b128 v[146:149], v145
	ds_read_b128 v[150:153], v145 offset:1024
	ds_read_b128 v[154:157], v145 offset:2048
	ds_read_b128 v[158:161], v145 offset:3072
	s_add_i32 s52, 0, 0x18000
	s_waitcnt vmcnt(6)
	s_barrier
	v_mfma_f32_16x16x32_bf16 v[46:49], v[208:211], v[162:165], v[46:49]
	v_mfma_f32_16x16x32_bf16 v[42:45], v[228:231], v[162:165], v[42:45]
	v_mfma_f32_16x16x32_bf16 v[30:33], v[208:211], v[170:173], v[30:33]
	v_mfma_f32_16x16x32_bf16 v[26:29], v[228:231], v[170:173], v[26:29]
	v_mfma_f32_16x16x32_bf16 v[14:17], v[208:211], v[192:195], v[14:17]
	v_mfma_f32_16x16x32_bf16 v[10:13], v[228:231], v[192:195], v[10:13]
	v_mfma_f32_16x16x32_bf16 v[6:9], v[208:211], v[200:203], v[6:9]
	v_mfma_f32_16x16x32_bf16 v[2:5], v[228:231], v[200:203], v[2:5]
	v_mfma_f32_16x16x32_bf16 v[46:49], v[224:227], v[166:169], v[46:49]
	v_mfma_f32_16x16x32_bf16 v[42:45], v[232:235], v[166:169], v[42:45]
	v_mfma_f32_16x16x32_bf16 v[30:33], v[224:227], v[174:177], v[30:33]
	v_mfma_f32_16x16x32_bf16 v[26:29], v[232:235], v[174:177], v[26:29]
	v_mfma_f32_16x16x32_bf16 v[14:17], v[224:227], v[196:199], v[14:17]
	v_mfma_f32_16x16x32_bf16 v[10:13], v[232:235], v[196:199], v[10:13]
	v_mfma_f32_16x16x32_bf16 v[6:9], v[224:227], v[204:207], v[6:9]
	v_mfma_f32_16x16x32_bf16 v[2:5], v[232:235], v[204:207], v[2:5]
	s_barrier
	s_add_u32 s22, s22, 0x20000
	s_addc_u32 s23, s23, 0
	s_mov_b32 m0, s29
	v_lshl_add_u64 v[208:209], s[22:23], 0, v[136:137]
	ds_read_b128 v[162:165], v144 offset:32768
	ds_read_b128 v[166:169], v144 offset:33792
	ds_read_b128 v[170:173], v144 offset:34816
	ds_read_b128 v[174:177], v144 offset:35840
	ds_read_b128 v[192:195], v144 offset:36864
	ds_read_b128 v[196:199], v144 offset:37888
	ds_read_b128 v[200:203], v144 offset:38912
	ds_read_b128 v[204:207], v144 offset:39936
	global_load_lds_dwordx4 v[208:209], off
	v_lshl_add_u64 v[208:209], s[22:23], 0, v[132:133]
	s_mov_b32 m0, s36
	s_nop 0
	global_load_lds_dwordx4 v[208:209], off
	s_waitcnt lgkmcnt(8)
	s_barrier
	s_waitcnt lgkmcnt(0)
	v_mfma_f32_16x16x32_bf16 v[126:129], v[146:149], v[162:165], v[126:129]
	v_mfma_f32_16x16x32_bf16 v[122:125], v[154:157], v[162:165], v[122:125]
	v_mfma_f32_16x16x32_bf16 v[118:121], v[146:149], v[170:173], v[118:121]
	v_mfma_f32_16x16x32_bf16 v[114:117], v[154:157], v[170:173], v[114:117]
	v_mfma_f32_16x16x32_bf16 v[102:105], v[146:149], v[192:195], v[102:105]
	v_mfma_f32_16x16x32_bf16 v[98:101], v[154:157], v[192:195], v[98:101]
	v_mfma_f32_16x16x32_bf16 v[86:89], v[146:149], v[200:203], v[86:89]
	v_mfma_f32_16x16x32_bf16 v[82:85], v[154:157], v[200:203], v[82:85]
	v_mfma_f32_16x16x32_bf16 v[126:129], v[150:153], v[166:169], v[126:129]
	v_mfma_f32_16x16x32_bf16 v[122:125], v[158:161], v[166:169], v[122:125]
	v_mfma_f32_16x16x32_bf16 v[118:121], v[150:153], v[174:177], v[118:121]
	v_mfma_f32_16x16x32_bf16 v[114:117], v[158:161], v[174:177], v[114:117]
	v_mfma_f32_16x16x32_bf16 v[102:105], v[150:153], v[196:199], v[102:105]
	v_mfma_f32_16x16x32_bf16 v[98:101], v[158:161], v[196:199], v[98:101]
	v_mfma_f32_16x16x32_bf16 v[86:89], v[150:153], v[204:207], v[86:89]
	v_mfma_f32_16x16x32_bf16 v[82:85], v[158:161], v[204:207], v[82:85]
	s_barrier
	s_add_i32 s53, 0, 0x1c000
	s_add_i32 s22, s52, s26
	v_add_u32_e32 v145, s53, v142
	v_lshl_add_u64 v[178:179], v[178:179], 0, s[78:79]
	s_mov_b32 m0, s22
	ds_read_b128 v[208:211], v145
	ds_read_b128 v[224:227], v145 offset:1024
	ds_read_b128 v[228:231], v145 offset:2048
	ds_read_b128 v[232:235], v145 offset:3072
	global_load_lds_dwordx4 v[178:179], off
	v_lshl_add_u64 v[178:179], v[212:213], 0, s[78:79]
	s_add_i32 m0, s22, 0x2000
	s_nop 0
	global_load_lds_dwordx4 v[178:179], off
	s_mov_b32 m0, s42
	v_lshl_add_u64 v[178:179], v[236:237], 0, s[78:79]
	s_barrier
	s_waitcnt lgkmcnt(0)
	v_mfma_f32_16x16x32_bf16 v[110:113], v[208:211], v[162:165], v[110:113]
	v_mfma_f32_16x16x32_bf16 v[106:109], v[228:231], v[162:165], v[106:109]
	v_mfma_f32_16x16x32_bf16 v[94:97], v[208:211], v[170:173], v[94:97]
	v_mfma_f32_16x16x32_bf16 v[90:93], v[228:231], v[170:173], v[90:93]
	v_mfma_f32_16x16x32_bf16 v[78:81], v[208:211], v[192:195], v[78:81]
	v_mfma_f32_16x16x32_bf16 v[74:77], v[228:231], v[192:195], v[74:77]
	v_mfma_f32_16x16x32_bf16 v[70:73], v[208:211], v[200:203], v[70:73]
	v_mfma_f32_16x16x32_bf16 v[66:69], v[228:231], v[200:203], v[66:69]
	v_mfma_f32_16x16x32_bf16 v[110:113], v[224:227], v[166:169], v[110:113]
	v_mfma_f32_16x16x32_bf16 v[106:109], v[232:235], v[166:169], v[106:109]
	v_mfma_f32_16x16x32_bf16 v[94:97], v[224:227], v[174:177], v[94:97]
	v_mfma_f32_16x16x32_bf16 v[90:93], v[232:235], v[174:177], v[90:93]
	v_mfma_f32_16x16x32_bf16 v[78:81], v[224:227], v[196:199], v[78:81]
	v_mfma_f32_16x16x32_bf16 v[74:77], v[232:235], v[196:199], v[74:77]
	v_mfma_f32_16x16x32_bf16 v[70:73], v[224:227], v[204:207], v[70:73]
	v_mfma_f32_16x16x32_bf16 v[66:69], v[232:235], v[204:207], v[66:69]
	s_barrier
	ds_read_b128 v[162:165], v144 offset:49152
	ds_read_b128 v[166:169], v144 offset:50176
	ds_read_b128 v[170:173], v144 offset:51200
	ds_read_b128 v[174:177], v144 offset:52224
	ds_read_b128 v[192:195], v144 offset:53248
	ds_read_b128 v[196:199], v144 offset:54272
	ds_read_b128 v[200:203], v144 offset:55296
	ds_read_b128 v[204:207], v144 offset:56320
	global_load_lds_dwordx4 v[178:179], off
	v_lshl_add_u64 v[178:179], v[238:239], 0, s[78:79]
	s_mov_b32 m0, s43
	s_nop 0
	global_load_lds_dwordx4 v[178:179], off
	s_waitcnt vmcnt(10)
	s_barrier
	s_waitcnt lgkmcnt(0)
	v_mfma_f32_16x16x32_bf16 v[62:65], v[146:149], v[162:165], v[62:65]
	v_mfma_f32_16x16x32_bf16 v[58:61], v[154:157], v[162:165], v[58:61]
	v_mfma_f32_16x16x32_bf16 v[54:57], v[146:149], v[170:173], v[54:57]
	v_mfma_f32_16x16x32_bf16 v[50:53], v[154:157], v[170:173], v[50:53]
	v_mfma_f32_16x16x32_bf16 v[38:41], v[146:149], v[192:195], v[38:41]
	v_mfma_f32_16x16x32_bf16 v[34:37], v[154:157], v[192:195], v[34:37]
	v_mfma_f32_16x16x32_bf16 v[22:25], v[146:149], v[200:203], v[22:25]
	v_mfma_f32_16x16x32_bf16 v[18:21], v[154:157], v[200:203], v[18:21]
	v_mfma_f32_16x16x32_bf16 v[62:65], v[150:153], v[166:169], v[62:65]
	v_mfma_f32_16x16x32_bf16 v[58:61], v[158:161], v[166:169], v[58:61]
	v_mfma_f32_16x16x32_bf16 v[54:57], v[150:153], v[174:177], v[54:57]
	v_mfma_f32_16x16x32_bf16 v[50:53], v[158:161], v[174:177], v[50:53]
	v_mfma_f32_16x16x32_bf16 v[38:41], v[150:153], v[196:199], v[38:41]
	v_mfma_f32_16x16x32_bf16 v[34:37], v[158:161], v[196:199], v[34:37]
	v_mfma_f32_16x16x32_bf16 v[22:25], v[150:153], v[204:207], v[22:25]
	v_mfma_f32_16x16x32_bf16 v[18:21], v[158:161], v[204:207], v[18:21]
	s_barrier
	s_add_u32 s22, s84, 0x20080
	s_addc_u32 s23, s85, 0
	s_add_i32 s52, s53, s26
	v_lshl_add_u64 v[146:147], s[22:23], 0, v[134:135]
	s_mov_b32 m0, s52
	s_nop 0
	global_load_lds_dwordx4 v[146:147], off
	v_lshl_add_u64 v[146:147], s[22:23], 0, v[130:131]
	s_add_i32 m0, s52, 0x2000
	s_nop 0
	global_load_lds_dwordx4 v[146:147], off
	v_add_u32_e32 v145, 0x10000, v142
	ds_read_b128 v[146:149], v145
	ds_read_b128 v[150:153], v145 offset:1024
	ds_read_b128 v[154:157], v145 offset:2048
	ds_read_b128 v[158:161], v145 offset:3072
	s_add_i32 s51, s51, 2
	s_add_u32 s20, s20, 0x100
	s_addc_u32 s21, s21, 0
	s_add_u32 s49, s49, 0x100
	s_addc_u32 s50, s50, 0
	s_cmp_gt_u32 s51, 5
	s_waitcnt vmcnt(6)
	s_barrier
	v_mfma_f32_16x16x32_bf16 v[46:49], v[208:211], v[162:165], v[46:49]
	v_mfma_f32_16x16x32_bf16 v[42:45], v[228:231], v[162:165], v[42:45]
	v_mfma_f32_16x16x32_bf16 v[30:33], v[208:211], v[170:173], v[30:33]
	v_mfma_f32_16x16x32_bf16 v[26:29], v[228:231], v[170:173], v[26:29]
	v_mfma_f32_16x16x32_bf16 v[14:17], v[208:211], v[192:195], v[14:17]
	v_mfma_f32_16x16x32_bf16 v[10:13], v[228:231], v[192:195], v[10:13]
	v_mfma_f32_16x16x32_bf16 v[6:9], v[208:211], v[200:203], v[6:9]
	v_mfma_f32_16x16x32_bf16 v[2:5], v[228:231], v[200:203], v[2:5]
	v_mfma_f32_16x16x32_bf16 v[46:49], v[224:227], v[166:169], v[46:49]
	v_mfma_f32_16x16x32_bf16 v[42:45], v[232:235], v[166:169], v[42:45]
	v_mfma_f32_16x16x32_bf16 v[30:33], v[224:227], v[174:177], v[30:33]
	v_mfma_f32_16x16x32_bf16 v[26:29], v[232:235], v[174:177], v[26:29]
	v_mfma_f32_16x16x32_bf16 v[14:17], v[224:227], v[196:199], v[14:17]
	v_mfma_f32_16x16x32_bf16 v[10:13], v[232:235], v[196:199], v[10:13]
	v_mfma_f32_16x16x32_bf16 v[6:9], v[224:227], v[204:207], v[6:9]
	v_mfma_f32_16x16x32_bf16 v[2:5], v[232:235], v[204:207], v[2:5]
	s_barrier
	s_cbranch_scc0 .LBB0_357
	s_waitcnt lgkmcnt(0)
	v_lshl_add_u32 v146, s46, 8, v1
	v_lshl_or_b32 v148, s45, 8, v143
	v_ashrrev_i32_e32 v147, 31, v146
	v_readlane_b32 s48, v254, 40
	v_ashrrev_i32_e32 v149, 31, v148
	v_lshlrev_b64 v[150:151], 12, v[146:147]
	v_readlane_b32 s60, v254, 52
	v_readlane_b32 s61, v254, 53
	v_lshlrev_b64 v[148:149], 1, v[148:149]
	s_mov_b32 s19, 0x80000
	v_lshl_add_u64 v[150:151], s[60:61], 0, v[150:151]
	v_lshl_add_u64 v[150:151], v[150:151], 0, v[148:149]
	s_mov_b64 s[20:21], 0x80000
	v_cvt_pk_bf16_f32 v62, v62, v63
	v_cvt_pk_bf16_f32 v63, v64, v65
	v_cvt_pk_bf16_f32 v64, v58, v59
	v_add_co_u32_e32 v58, vcc, s19, v150
	v_cvt_pk_bf16_f32 v70, v70, v71
	v_cvt_pk_bf16_f32 v71, v72, v73
	v_cvt_pk_bf16_f32 v72, v66, v67
	v_lshl_add_u64 v[66:67], v[150:151], 0, s[20:21]
	v_addc_co_u32_e32 v59, vcc, 0, v151, vcc
	v_cvt_pk_bf16_f32 v46, v46, v47
	v_cvt_pk_bf16_f32 v47, v48, v49
	v_cvt_pk_bf16_f32 v48, v42, v43
	v_cvt_pk_bf16_f32 v49, v44, v45
	s_mov_b32 s19, 0x90000
	v_cvt_pk_bf16_f32 v110, v110, v111
	v_cvt_pk_bf16_f32 v111, v112, v113
	v_cvt_pk_bf16_f32 v112, v106, v107
	v_or_b32_e32 v106, 16, v146
	global_store_dwordx4 v[66:67], v[46:49], off offset:256
	s_mov_b64 s[20:21], 0x90000
	v_ashrrev_i32_e32 v107, 31, v106
	v_add_co_u32_e32 v48, vcc, s19, v150
	v_cvt_pk_bf16_f32 v94, v94, v95
	v_cvt_pk_bf16_f32 v95, v96, v97
	v_cvt_pk_bf16_f32 v96, v90, v91
	v_or_b32_e32 v90, 32, v146
	v_lshl_add_u64 v[46:47], v[150:151], 0, s[20:21]
	v_addc_co_u32_e32 v49, vcc, 0, v151, vcc
	v_cvt_pk_bf16_f32 v30, v30, v31
	v_cvt_pk_bf16_f32 v31, v32, v33
	v_cvt_pk_bf16_f32 v32, v26, v27
	v_cvt_pk_bf16_f32 v33, v28, v29
	s_mov_b32 s19, 0xa0000
	v_lshlrev_b64 v[106:107], 12, v[106:107]
	v_ashrrev_i32_e32 v91, 31, v90
	v_cvt_pk_bf16_f32 v78, v78, v79
	v_cvt_pk_bf16_f32 v79, v80, v81
	v_cvt_pk_bf16_f32 v80, v74, v75
	v_or_b32_e32 v74, 48, v146
	global_store_dwordx4 v[46:47], v[30:33], off offset:256
	s_mov_b64 s[20:21], 0xa0000
	v_cvt_pk_bf16_f32 v113, v108, v109
	v_add_co_u32_e32 v32, vcc, s19, v150
	v_lshl_add_u64 v[106:107], s[60:61], 0, v[106:107]
	v_lshlrev_b64 v[90:91], 12, v[90:91]
	v_ashrrev_i32_e32 v75, 31, v74
	v_lshl_add_u64 v[30:31], v[150:151], 0, s[20:21]
	v_addc_co_u32_e32 v33, vcc, 0, v151, vcc
	v_cvt_pk_bf16_f32 v14, v14, v15
	v_cvt_pk_bf16_f32 v15, v16, v17
	v_cvt_pk_bf16_f32 v16, v10, v11
	v_cvt_pk_bf16_f32 v17, v12, v13
	s_mov_b32 s19, 0xb0000
	global_store_dwordx4 v[150:151], v[110:113], off offset:256
	v_cvt_pk_bf16_f32 v97, v92, v93
	v_lshl_add_u64 v[90:91], s[60:61], 0, v[90:91]
	v_lshl_add_u64 v[110:111], v[106:107], 0, v[148:149]
	v_lshlrev_b64 v[74:75], 12, v[74:75]
	global_store_dwordx4 v[30:31], v[14:17], off offset:256
	global_store_dwordx4 v[110:111], v[94:97], off offset:256
	v_cvt_pk_bf16_f32 v81, v76, v77
	v_add_co_u32_e32 v16, vcc, s19, v150
	v_lshl_add_u64 v[94:95], v[90:91], 0, v[148:149]
	v_lshl_add_u64 v[74:75], s[60:61], 0, v[74:75]
	s_mov_b64 s[20:21], 0xb0000
	v_addc_co_u32_e32 v17, vcc, 0, v151, vcc
	v_cvt_pk_bf16_f32 v126, v126, v127
	v_cvt_pk_bf16_f32 v127, v128, v129
	v_cvt_pk_bf16_f32 v128, v122, v123
	v_cvt_pk_bf16_f32 v129, v124, v125
	v_cvt_pk_bf16_f32 v106, v118, v119
	v_cvt_pk_bf16_f32 v107, v120, v121
	v_cvt_pk_bf16_f32 v108, v114, v115
	v_cvt_pk_bf16_f32 v109, v116, v117
	v_cvt_pk_bf16_f32 v90, v102, v103
	v_cvt_pk_bf16_f32 v91, v104, v105
	v_cvt_pk_bf16_f32 v92, v98, v99
	v_cvt_pk_bf16_f32 v93, v100, v101
	global_store_dwordx4 v[94:95], v[78:81], off offset:256
	v_cvt_pk_bf16_f32 v76, v82, v83
	v_cvt_pk_bf16_f32 v77, v84, v85
	v_lshl_add_u64 v[78:79], v[74:75], 0, v[148:149]
	v_cvt_pk_bf16_f32 v74, v86, v87
	v_cvt_pk_bf16_f32 v75, v88, v89
	v_cvt_pk_bf16_f32 v73, v68, v69
	v_cvt_pk_bf16_f32 v65, v60, v61
	v_cvt_pk_bf16_f32 v42, v54, v55
	v_cvt_pk_bf16_f32 v43, v56, v57
	v_cvt_pk_bf16_f32 v44, v50, v51
	v_cvt_pk_bf16_f32 v45, v52, v53
	v_cvt_pk_bf16_f32 v26, v38, v39
	v_cvt_pk_bf16_f32 v27, v40, v41
	v_cvt_pk_bf16_f32 v28, v34, v35
	v_cvt_pk_bf16_f32 v29, v36, v37
	v_lshl_add_u64 v[14:15], v[150:151], 0, s[20:21]
	v_cvt_pk_bf16_f32 v10, v22, v23
	v_cvt_pk_bf16_f32 v11, v24, v25
	v_cvt_pk_bf16_f32 v12, v18, v19
	v_cvt_pk_bf16_f32 v13, v20, v21
	v_cvt_pk_bf16_f32 v6, v6, v7
	v_cvt_pk_bf16_f32 v7, v8, v9
	v_cvt_pk_bf16_f32 v8, v2, v3
	v_cvt_pk_bf16_f32 v9, v4, v5
	s_and_b64 vcc, exec, s[38:39]
	s_mov_b32 s45, s18
	s_mov_b32 s46, s30
	s_mov_b64 s[22:23], s[82:83]
	s_mov_b64 s[20:21], s[80:81]
	s_mov_b32 s64, 0x800000
	s_movk_i32 s65, 0x1fff
	v_readlane_b32 s49, v254, 41
	v_readlane_b32 s50, v254, 42
	v_readlane_b32 s51, v254, 43
	v_readlane_b32 s52, v254, 44
	v_readlane_b32 s53, v254, 45
	v_readlane_b32 s54, v254, 46
	v_readlane_b32 s55, v254, 47
	v_readlane_b32 s56, v254, 48
	v_readlane_b32 s57, v254, 49
	v_readlane_b32 s58, v254, 50
	v_readlane_b32 s59, v254, 51
	v_readlane_b32 s62, v254, 54
	v_readlane_b32 s63, v254, 55
	global_store_dwordx4 v[150:151], v[126:129], off
	global_store_dwordx4 v[110:111], v[106:109], off
	global_store_dwordx4 v[94:95], v[90:93], off
	global_store_dwordx4 v[78:79], v[74:77], off
	global_store_dwordx4 v[78:79], v[70:73], off offset:256
	global_store_dwordx4 v[58:59], v[62:65], off
	global_store_dwordx4 v[48:49], v[42:45], off
	global_store_dwordx4 v[32:33], v[26:29], off
	global_store_dwordx4 v[16:17], v[10:13], off
	global_store_dwordx4 v[14:15], v[6:9], off offset:256
	s_cbranch_vccz .LBB0_350
	s_waitcnt vmcnt(0)
	v_readlane_b32 s44, v255, 30
	s_mov_b32 s66, s90
	s_cmpk_gt_u32 s25, 0xff
	v_readlane_b32 s45, v255, 31
	v_readlane_b32 s42, v255, 32
	s_cbranch_scc1 .LBB0_361
	s_barrier

.LBB0_373:
	s_add_u32 s22, s20, 0xfffe0080
	s_addc_u32 s23, s21, -1
	s_add_i32 s52, 0, 0x10000
	s_cmp_eq_u32 s51, 4
	s_cselect_b32 s23, s31, s23
	s_cselect_b32 s22, s47, s22
	s_cselect_b32 s83, s19, s50
	s_cselect_b32 s82, s48, s49
	v_lshl_add_u64 v[178:179], s[20:21], 0, v[138:139]
	s_add_i32 m0, s27, 0xc000
	ds_read_b128 v[162:165], v144
	ds_read_b128 v[166:169], v144 offset:1024
	ds_read_b128 v[170:173], v144 offset:2048
	ds_read_b128 v[174:177], v144 offset:3072
	ds_read_b128 v[192:195], v144 offset:4096
	ds_read_b128 v[196:199], v144 offset:5120
	ds_read_b128 v[200:203], v144 offset:6144
	ds_read_b128 v[204:207], v144 offset:7168
	global_load_lds_dwordx4 v[178:179], off
	v_lshl_add_u64 v[178:179], s[20:21], 0, v[140:141]
	s_add_i32 m0, s27, 0xe000
	s_nop 0
	global_load_lds_dwordx4 v[178:179], off
	s_waitcnt lgkmcnt(8)
	s_barrier
	s_waitcnt lgkmcnt(0)
	v_mfma_f32_16x16x32_bf16 v[126:129], v[146:149], v[162:165], v[126:129]
	v_mfma_f32_16x16x32_bf16 v[122:125], v[154:157], v[162:165], v[122:125]
	v_mfma_f32_16x16x32_bf16 v[118:121], v[146:149], v[170:173], v[118:121]
	v_mfma_f32_16x16x32_bf16 v[114:117], v[154:157], v[170:173], v[114:117]
	v_mfma_f32_16x16x32_bf16 v[102:105], v[146:149], v[192:195], v[102:105]
	v_mfma_f32_16x16x32_bf16 v[98:101], v[154:157], v[192:195], v[98:101]
	v_mfma_f32_16x16x32_bf16 v[86:89], v[146:149], v[200:203], v[86:89]
	v_mfma_f32_16x16x32_bf16 v[82:85], v[154:157], v[200:203], v[82:85]
	v_mfma_f32_16x16x32_bf16 v[126:129], v[150:153], v[166:169], v[126:129]
	v_mfma_f32_16x16x32_bf16 v[122:125], v[158:161], v[166:169], v[122:125]
	v_mfma_f32_16x16x32_bf16 v[118:121], v[150:153], v[174:177], v[118:121]
	v_mfma_f32_16x16x32_bf16 v[114:117], v[158:161], v[174:177], v[114:117]
	v_mfma_f32_16x16x32_bf16 v[102:105], v[150:153], v[196:199], v[102:105]
	v_mfma_f32_16x16x32_bf16 v[98:101], v[158:161], v[196:199], v[98:101]
	v_mfma_f32_16x16x32_bf16 v[86:89], v[150:153], v[204:207], v[86:89]
	v_mfma_f32_16x16x32_bf16 v[82:85], v[158:161], v[204:207], v[82:85]
	s_barrier
	s_add_i32 s54, 0, 0x14000
	s_add_i32 s52, s52, s26
	v_add_u32_e32 v145, s54, v142
	v_lshl_add_u64 v[178:179], s[82:83], 0, v[134:135]
	s_mov_b32 m0, s52
	ds_read_b128 v[208:211], v145
	ds_read_b128 v[224:227], v145 offset:1024
	ds_read_b128 v[228:231], v145 offset:2048
	ds_read_b128 v[232:235], v145 offset:3072
	global_load_lds_dwordx4 v[178:179], off
	v_lshl_add_u64 v[212:213], s[82:83], 0, v[130:131]
	s_add_i32 m0, s52, 0x2000
	s_nop 0
	global_load_lds_dwordx4 v[212:213], off
	s_mov_b32 m0, s27
	v_lshl_add_u64 v[236:237], s[22:23], 0, v[136:137]
	s_barrier
	s_waitcnt lgkmcnt(0)
	v_mfma_f32_16x16x32_bf16 v[110:113], v[208:211], v[162:165], v[110:113]
	v_mfma_f32_16x16x32_bf16 v[106:109], v[228:231], v[162:165], v[106:109]
	v_mfma_f32_16x16x32_bf16 v[94:97], v[208:211], v[170:173], v[94:97]
	v_mfma_f32_16x16x32_bf16 v[90:93], v[228:231], v[170:173], v[90:93]
	v_mfma_f32_16x16x32_bf16 v[78:81], v[208:211], v[192:195], v[78:81]
	v_mfma_f32_16x16x32_bf16 v[74:77], v[228:231], v[192:195], v[74:77]
	v_mfma_f32_16x16x32_bf16 v[70:73], v[208:211], v[200:203], v[70:73]
	v_mfma_f32_16x16x32_bf16 v[66:69], v[228:231], v[200:203], v[66:69]
	v_mfma_f32_16x16x32_bf16 v[110:113], v[224:227], v[166:169], v[110:113]
	v_mfma_f32_16x16x32_bf16 v[106:109], v[232:235], v[166:169], v[106:109]
	v_mfma_f32_16x16x32_bf16 v[94:97], v[224:227], v[174:177], v[94:97]
	v_mfma_f32_16x16x32_bf16 v[90:93], v[232:235], v[174:177], v[90:93]
	v_mfma_f32_16x16x32_bf16 v[78:81], v[224:227], v[196:199], v[78:81]
	v_mfma_f32_16x16x32_bf16 v[74:77], v[232:235], v[196:199], v[74:77]
	v_mfma_f32_16x16x32_bf16 v[70:73], v[224:227], v[204:207], v[70:73]
	v_mfma_f32_16x16x32_bf16 v[66:69], v[232:235], v[204:207], v[66:69]
	s_barrier
	ds_read_b128 v[162:165], v144 offset:16384
	ds_read_b128 v[166:169], v144 offset:17408
	ds_read_b128 v[170:173], v144 offset:18432
	ds_read_b128 v[174:177], v144 offset:19456
	ds_read_b128 v[192:195], v144 offset:20480
	ds_read_b128 v[196:199], v144 offset:21504
	ds_read_b128 v[200:203], v144 offset:22528
	ds_read_b128 v[204:207], v144 offset:23552
	global_load_lds_dwordx4 v[236:237], off
	v_lshl_add_u64 v[238:239], s[22:23], 0, v[132:133]
	s_mov_b32 m0, s28
	s_nop 0
	global_load_lds_dwordx4 v[238:239], off
	s_waitcnt vmcnt(10)
	s_barrier
	s_waitcnt lgkmcnt(0)
	v_mfma_f32_16x16x32_bf16 v[62:65], v[146:149], v[162:165], v[62:65]
	v_mfma_f32_16x16x32_bf16 v[58:61], v[154:157], v[162:165], v[58:61]
	v_mfma_f32_16x16x32_bf16 v[54:57], v[146:149], v[170:173], v[54:57]
	v_mfma_f32_16x16x32_bf16 v[50:53], v[154:157], v[170:173], v[50:53]
	v_mfma_f32_16x16x32_bf16 v[38:41], v[146:149], v[192:195], v[38:41]
	v_mfma_f32_16x16x32_bf16 v[34:37], v[154:157], v[192:195], v[34:37]
	v_mfma_f32_16x16x32_bf16 v[22:25], v[146:149], v[200:203], v[22:25]
	v_mfma_f32_16x16x32_bf16 v[18:21], v[154:157], v[200:203], v[18:21]
	v_mfma_f32_16x16x32_bf16 v[62:65], v[150:153], v[166:169], v[62:65]
	v_mfma_f32_16x16x32_bf16 v[58:61], v[158:161], v[166:169], v[58:61]
	v_mfma_f32_16x16x32_bf16 v[54:57], v[150:153], v[174:177], v[54:57]
	v_mfma_f32_16x16x32_bf16 v[50:53], v[158:161], v[174:177], v[50:53]
	v_mfma_f32_16x16x32_bf16 v[38:41], v[150:153], v[196:199], v[38:41]
	v_mfma_f32_16x16x32_bf16 v[34:37], v[158:161], v[196:199], v[34:37]
	v_mfma_f32_16x16x32_bf16 v[22:25], v[150:153], v[204:207], v[22:25]
	v_mfma_f32_16x16x32_bf16 v[18:21], v[158:161], v[204:207], v[18:21]
	s_barrier
	s_add_u32 s52, s82, 0x20000
	s_addc_u32 s53, s83, 0
	s_add_i32 s54, s54, s26
	v_lshl_add_u64 v[146:147], s[52:53], 0, v[134:135]
	s_mov_b32 m0, s54
	s_nop 0
	global_load_lds_dwordx4 v[146:147], off
	v_lshl_add_u64 v[146:147], s[52:53], 0, v[130:131]
	s_add_i32 m0, s54, 0x2000
	s_nop 0
	global_load_lds_dwordx4 v[146:147], off
	v_add_u32_e32 v145, 0x18000, v142
	ds_read_b128 v[146:149], v145
	ds_read_b128 v[150:153], v145 offset:1024
	ds_read_b128 v[154:157], v145 offset:2048
	ds_read_b128 v[158:161], v145 offset:3072
	s_add_i32 s52, 0, 0x18000
	s_waitcnt vmcnt(6)
	s_barrier
	v_mfma_f32_16x16x32_bf16 v[46:49], v[208:211], v[162:165], v[46:49]
	v_mfma_f32_16x16x32_bf16 v[42:45], v[228:231], v[162:165], v[42:45]
	v_mfma_f32_16x16x32_bf16 v[30:33], v[208:211], v[170:173], v[30:33]
	v_mfma_f32_16x16x32_bf16 v[26:29], v[228:231], v[170:173], v[26:29]
	v_mfma_f32_16x16x32_bf16 v[14:17], v[208:211], v[192:195], v[14:17]
	v_mfma_f32_16x16x32_bf16 v[10:13], v[228:231], v[192:195], v[10:13]
	v_mfma_f32_16x16x32_bf16 v[6:9], v[208:211], v[200:203], v[6:9]
	v_mfma_f32_16x16x32_bf16 v[2:5], v[228:231], v[200:203], v[2:5]
	v_mfma_f32_16x16x32_bf16 v[46:49], v[224:227], v[166:169], v[46:49]
	v_mfma_f32_16x16x32_bf16 v[42:45], v[232:235], v[166:169], v[42:45]
	v_mfma_f32_16x16x32_bf16 v[30:33], v[224:227], v[174:177], v[30:33]
	v_mfma_f32_16x16x32_bf16 v[26:29], v[232:235], v[174:177], v[26:29]
	v_mfma_f32_16x16x32_bf16 v[14:17], v[224:227], v[196:199], v[14:17]
	v_mfma_f32_16x16x32_bf16 v[10:13], v[232:235], v[196:199], v[10:13]
	v_mfma_f32_16x16x32_bf16 v[6:9], v[224:227], v[204:207], v[6:9]
	v_mfma_f32_16x16x32_bf16 v[2:5], v[232:235], v[204:207], v[2:5]
	s_barrier
	s_add_u32 s22, s22, 0x20000
	s_addc_u32 s23, s23, 0
	s_mov_b32 m0, s29
	v_lshl_add_u64 v[208:209], s[22:23], 0, v[136:137]
	ds_read_b128 v[162:165], v144 offset:32768
	ds_read_b128 v[166:169], v144 offset:33792
	ds_read_b128 v[170:173], v144 offset:34816
	ds_read_b128 v[174:177], v144 offset:35840
	ds_read_b128 v[192:195], v144 offset:36864
	ds_read_b128 v[196:199], v144 offset:37888
	ds_read_b128 v[200:203], v144 offset:38912
	ds_read_b128 v[204:207], v144 offset:39936
	global_load_lds_dwordx4 v[208:209], off
	v_lshl_add_u64 v[208:209], s[22:23], 0, v[132:133]
	s_mov_b32 m0, s36
	s_nop 0
	global_load_lds_dwordx4 v[208:209], off
	s_waitcnt lgkmcnt(8)
	s_barrier
	s_waitcnt lgkmcnt(0)
	v_mfma_f32_16x16x32_bf16 v[126:129], v[146:149], v[162:165], v[126:129]
	v_mfma_f32_16x16x32_bf16 v[122:125], v[154:157], v[162:165], v[122:125]
	v_mfma_f32_16x16x32_bf16 v[118:121], v[146:149], v[170:173], v[118:121]
	v_mfma_f32_16x16x32_bf16 v[114:117], v[154:157], v[170:173], v[114:117]
	v_mfma_f32_16x16x32_bf16 v[102:105], v[146:149], v[192:195], v[102:105]
	v_mfma_f32_16x16x32_bf16 v[98:101], v[154:157], v[192:195], v[98:101]
	v_mfma_f32_16x16x32_bf16 v[86:89], v[146:149], v[200:203], v[86:89]
	v_mfma_f32_16x16x32_bf16 v[82:85], v[154:157], v[200:203], v[82:85]
	v_mfma_f32_16x16x32_bf16 v[126:129], v[150:153], v[166:169], v[126:129]
	v_mfma_f32_16x16x32_bf16 v[122:125], v[158:161], v[166:169], v[122:125]
	v_mfma_f32_16x16x32_bf16 v[118:121], v[150:153], v[174:177], v[118:121]
	v_mfma_f32_16x16x32_bf16 v[114:117], v[158:161], v[174:177], v[114:117]
	v_mfma_f32_16x16x32_bf16 v[102:105], v[150:153], v[196:199], v[102:105]
	v_mfma_f32_16x16x32_bf16 v[98:101], v[158:161], v[196:199], v[98:101]
	v_mfma_f32_16x16x32_bf16 v[86:89], v[150:153], v[204:207], v[86:89]
	v_mfma_f32_16x16x32_bf16 v[82:85], v[158:161], v[204:207], v[82:85]
	s_barrier
	s_add_i32 s53, 0, 0x1c000
	s_add_i32 s22, s52, s26
	v_add_u32_e32 v145, s53, v142
	v_lshl_add_u64 v[178:179], v[178:179], 0, s[78:79]
	s_mov_b32 m0, s22
	ds_read_b128 v[208:211], v145
	ds_read_b128 v[224:227], v145 offset:1024
	ds_read_b128 v[228:231], v145 offset:2048
	ds_read_b128 v[232:235], v145 offset:3072
	global_load_lds_dwordx4 v[178:179], off
	v_lshl_add_u64 v[178:179], v[212:213], 0, s[78:79]
	s_add_i32 m0, s22, 0x2000
	s_nop 0
	global_load_lds_dwordx4 v[178:179], off
	s_mov_b32 m0, s42
	v_lshl_add_u64 v[178:179], v[236:237], 0, s[78:79]
	s_barrier
	s_waitcnt lgkmcnt(0)
	v_mfma_f32_16x16x32_bf16 v[110:113], v[208:211], v[162:165], v[110:113]
	v_mfma_f32_16x16x32_bf16 v[106:109], v[228:231], v[162:165], v[106:109]
	v_mfma_f32_16x16x32_bf16 v[94:97], v[208:211], v[170:173], v[94:97]
	v_mfma_f32_16x16x32_bf16 v[90:93], v[228:231], v[170:173], v[90:93]
	v_mfma_f32_16x16x32_bf16 v[78:81], v[208:211], v[192:195], v[78:81]
	v_mfma_f32_16x16x32_bf16 v[74:77], v[228:231], v[192:195], v[74:77]
	v_mfma_f32_16x16x32_bf16 v[70:73], v[208:211], v[200:203], v[70:73]
	v_mfma_f32_16x16x32_bf16 v[66:69], v[228:231], v[200:203], v[66:69]
	v_mfma_f32_16x16x32_bf16 v[110:113], v[224:227], v[166:169], v[110:113]
	v_mfma_f32_16x16x32_bf16 v[106:109], v[232:235], v[166:169], v[106:109]
	v_mfma_f32_16x16x32_bf16 v[94:97], v[224:227], v[174:177], v[94:97]
	v_mfma_f32_16x16x32_bf16 v[90:93], v[232:235], v[174:177], v[90:93]
	v_mfma_f32_16x16x32_bf16 v[78:81], v[224:227], v[196:199], v[78:81]
	v_mfma_f32_16x16x32_bf16 v[74:77], v[232:235], v[196:199], v[74:77]
	v_mfma_f32_16x16x32_bf16 v[70:73], v[224:227], v[204:207], v[70:73]
	v_mfma_f32_16x16x32_bf16 v[66:69], v[232:235], v[204:207], v[66:69]
	s_barrier
	ds_read_b128 v[162:165], v144 offset:49152
	ds_read_b128 v[166:169], v144 offset:50176
	ds_read_b128 v[170:173], v144 offset:51200
	ds_read_b128 v[174:177], v144 offset:52224
	ds_read_b128 v[192:195], v144 offset:53248
	ds_read_b128 v[196:199], v144 offset:54272
	ds_read_b128 v[200:203], v144 offset:55296
	ds_read_b128 v[204:207], v144 offset:56320
	global_load_lds_dwordx4 v[178:179], off
	v_lshl_add_u64 v[178:179], v[238:239], 0, s[78:79]
	s_mov_b32 m0, s43
	s_nop 0
	global_load_lds_dwordx4 v[178:179], off
	s_waitcnt vmcnt(10)
	s_barrier
	s_waitcnt lgkmcnt(0)
	v_mfma_f32_16x16x32_bf16 v[62:65], v[146:149], v[162:165], v[62:65]
	v_mfma_f32_16x16x32_bf16 v[58:61], v[154:157], v[162:165], v[58:61]
	v_mfma_f32_16x16x32_bf16 v[54:57], v[146:149], v[170:173], v[54:57]
	v_mfma_f32_16x16x32_bf16 v[50:53], v[154:157], v[170:173], v[50:53]
	v_mfma_f32_16x16x32_bf16 v[38:41], v[146:149], v[192:195], v[38:41]
	v_mfma_f32_16x16x32_bf16 v[34:37], v[154:157], v[192:195], v[34:37]
	v_mfma_f32_16x16x32_bf16 v[22:25], v[146:149], v[200:203], v[22:25]
	v_mfma_f32_16x16x32_bf16 v[18:21], v[154:157], v[200:203], v[18:21]
	v_mfma_f32_16x16x32_bf16 v[62:65], v[150:153], v[166:169], v[62:65]
	v_mfma_f32_16x16x32_bf16 v[58:61], v[158:161], v[166:169], v[58:61]
	v_mfma_f32_16x16x32_bf16 v[54:57], v[150:153], v[174:177], v[54:57]
	v_mfma_f32_16x16x32_bf16 v[50:53], v[158:161], v[174:177], v[50:53]
	v_mfma_f32_16x16x32_bf16 v[38:41], v[150:153], v[196:199], v[38:41]
	v_mfma_f32_16x16x32_bf16 v[34:37], v[158:161], v[196:199], v[34:37]
	v_mfma_f32_16x16x32_bf16 v[22:25], v[150:153], v[204:207], v[22:25]
	v_mfma_f32_16x16x32_bf16 v[18:21], v[158:161], v[204:207], v[18:21]
	s_barrier
	s_add_u32 s22, s82, 0x20080
	s_addc_u32 s23, s83, 0
	s_add_i32 s52, s53, s26
	v_lshl_add_u64 v[146:147], s[22:23], 0, v[134:135]
	s_mov_b32 m0, s52
	s_nop 0
	global_load_lds_dwordx4 v[146:147], off
	v_lshl_add_u64 v[146:147], s[22:23], 0, v[130:131]
	s_add_i32 m0, s52, 0x2000
	s_nop 0
	global_load_lds_dwordx4 v[146:147], off
	v_add_u32_e32 v145, 0x10000, v142
	ds_read_b128 v[146:149], v145
	ds_read_b128 v[150:153], v145 offset:1024
	ds_read_b128 v[154:157], v145 offset:2048
	ds_read_b128 v[158:161], v145 offset:3072
	s_add_i32 s51, s51, 2
	s_add_u32 s20, s20, 0x100
	s_addc_u32 s21, s21, 0
	s_add_u32 s49, s49, 0x100
	s_addc_u32 s50, s50, 0
	s_cmp_gt_u32 s51, 5
	s_waitcnt vmcnt(6)
	s_barrier
	v_mfma_f32_16x16x32_bf16 v[46:49], v[208:211], v[162:165], v[46:49]
	v_mfma_f32_16x16x32_bf16 v[42:45], v[228:231], v[162:165], v[42:45]
	v_mfma_f32_16x16x32_bf16 v[30:33], v[208:211], v[170:173], v[30:33]
	v_mfma_f32_16x16x32_bf16 v[26:29], v[228:231], v[170:173], v[26:29]
	v_mfma_f32_16x16x32_bf16 v[14:17], v[208:211], v[192:195], v[14:17]
	v_mfma_f32_16x16x32_bf16 v[10:13], v[228:231], v[192:195], v[10:13]
	v_mfma_f32_16x16x32_bf16 v[6:9], v[208:211], v[200:203], v[6:9]
	v_mfma_f32_16x16x32_bf16 v[2:5], v[228:231], v[200:203], v[2:5]
	v_mfma_f32_16x16x32_bf16 v[46:49], v[224:227], v[166:169], v[46:49]
	v_mfma_f32_16x16x32_bf16 v[42:45], v[232:235], v[166:169], v[42:45]
	v_mfma_f32_16x16x32_bf16 v[30:33], v[224:227], v[174:177], v[30:33]
	v_mfma_f32_16x16x32_bf16 v[26:29], v[232:235], v[174:177], v[26:29]
	v_mfma_f32_16x16x32_bf16 v[14:17], v[224:227], v[196:199], v[14:17]
	v_mfma_f32_16x16x32_bf16 v[10:13], v[232:235], v[196:199], v[10:13]
	v_mfma_f32_16x16x32_bf16 v[6:9], v[224:227], v[204:207], v[6:9]
	v_mfma_f32_16x16x32_bf16 v[2:5], v[232:235], v[204:207], v[2:5]
	s_barrier
	s_cbranch_scc0 .LBB0_373
	s_waitcnt lgkmcnt(0)
	v_lshl_add_u32 v146, s46, 8, v1
	v_lshl_or_b32 v148, s45, 8, v143
	v_ashrrev_i32_e32 v147, 31, v146
	v_readlane_b32 s48, v254, 40
	v_ashrrev_i32_e32 v149, 31, v148
	v_lshlrev_b64 v[150:151], 14, v[146:147]
	v_readlane_b32 s62, v254, 54
	v_readlane_b32 s63, v254, 55
	v_lshlrev_b64 v[148:149], 1, v[148:149]
	s_mov_b32 s19, 0x200000
	v_lshl_add_u64 v[150:151], s[62:63], 0, v[150:151]
	v_lshl_add_u64 v[150:151], v[150:151], 0, v[148:149]
	s_mov_b64 s[20:21], 0x200000
	v_cvt_pk_bf16_f32 v62, v62, v63
	v_cvt_pk_bf16_f32 v63, v64, v65
	v_cvt_pk_bf16_f32 v64, v58, v59
	v_add_co_u32_e32 v58, vcc, s19, v150
	v_cvt_pk_bf16_f32 v70, v70, v71
	v_cvt_pk_bf16_f32 v71, v72, v73
	v_cvt_pk_bf16_f32 v72, v66, v67
	v_lshl_add_u64 v[66:67], v[150:151], 0, s[20:21]
	v_addc_co_u32_e32 v59, vcc, 0, v151, vcc
	v_cvt_pk_bf16_f32 v46, v46, v47
	v_cvt_pk_bf16_f32 v47, v48, v49
	v_cvt_pk_bf16_f32 v48, v42, v43
	v_cvt_pk_bf16_f32 v49, v44, v45
	s_mov_b32 s19, 0x240000
	v_cvt_pk_bf16_f32 v110, v110, v111
	v_cvt_pk_bf16_f32 v111, v112, v113
	v_cvt_pk_bf16_f32 v112, v106, v107
	v_or_b32_e32 v106, 16, v146
	global_store_dwordx4 v[66:67], v[46:49], off offset:256
	s_mov_b64 s[20:21], 0x240000
	v_ashrrev_i32_e32 v107, 31, v106
	v_add_co_u32_e32 v48, vcc, s19, v150
	v_cvt_pk_bf16_f32 v94, v94, v95
	v_cvt_pk_bf16_f32 v95, v96, v97
	v_cvt_pk_bf16_f32 v96, v90, v91
	v_or_b32_e32 v90, 32, v146
	v_lshl_add_u64 v[46:47], v[150:151], 0, s[20:21]
	v_addc_co_u32_e32 v49, vcc, 0, v151, vcc
	v_cvt_pk_bf16_f32 v30, v30, v31
	v_cvt_pk_bf16_f32 v31, v32, v33
	v_cvt_pk_bf16_f32 v32, v26, v27
	v_cvt_pk_bf16_f32 v33, v28, v29
	s_mov_b32 s19, 0x280000
	v_lshlrev_b64 v[106:107], 14, v[106:107]
	v_ashrrev_i32_e32 v91, 31, v90
	v_cvt_pk_bf16_f32 v78, v78, v79
	v_cvt_pk_bf16_f32 v79, v80, v81
	v_cvt_pk_bf16_f32 v80, v74, v75
	v_or_b32_e32 v74, 48, v146
	global_store_dwordx4 v[46:47], v[30:33], off offset:256
	s_mov_b64 s[20:21], 0x280000
	v_cvt_pk_bf16_f32 v113, v108, v109
	v_add_co_u32_e32 v32, vcc, s19, v150
	v_lshl_add_u64 v[106:107], s[62:63], 0, v[106:107]
	v_lshlrev_b64 v[90:91], 14, v[90:91]
	v_ashrrev_i32_e32 v75, 31, v74
	v_lshl_add_u64 v[30:31], v[150:151], 0, s[20:21]
	v_addc_co_u32_e32 v33, vcc, 0, v151, vcc
	v_cvt_pk_bf16_f32 v14, v14, v15
	v_cvt_pk_bf16_f32 v15, v16, v17
	v_cvt_pk_bf16_f32 v16, v10, v11
	v_cvt_pk_bf16_f32 v17, v12, v13
	s_mov_b32 s19, 0x2c0000
	global_store_dwordx4 v[150:151], v[110:113], off offset:256
	v_cvt_pk_bf16_f32 v97, v92, v93
	v_lshl_add_u64 v[90:91], s[62:63], 0, v[90:91]
	v_lshl_add_u64 v[110:111], v[106:107], 0, v[148:149]
	v_lshlrev_b64 v[74:75], 14, v[74:75]
	global_store_dwordx4 v[30:31], v[14:17], off offset:256
	global_store_dwordx4 v[110:111], v[94:97], off offset:256
	v_cvt_pk_bf16_f32 v81, v76, v77
	v_add_co_u32_e32 v16, vcc, s19, v150
	v_lshl_add_u64 v[94:95], v[90:91], 0, v[148:149]
	v_lshl_add_u64 v[74:75], s[62:63], 0, v[74:75]
	s_mov_b64 s[20:21], 0x2c0000
	v_addc_co_u32_e32 v17, vcc, 0, v151, vcc
	v_cvt_pk_bf16_f32 v126, v126, v127
	v_cvt_pk_bf16_f32 v127, v128, v129
	v_cvt_pk_bf16_f32 v128, v122, v123
	v_cvt_pk_bf16_f32 v129, v124, v125
	v_cvt_pk_bf16_f32 v106, v118, v119
	v_cvt_pk_bf16_f32 v107, v120, v121
	v_cvt_pk_bf16_f32 v108, v114, v115
	v_cvt_pk_bf16_f32 v109, v116, v117
	v_cvt_pk_bf16_f32 v90, v102, v103
	v_cvt_pk_bf16_f32 v91, v104, v105
	v_cvt_pk_bf16_f32 v92, v98, v99
	v_cvt_pk_bf16_f32 v93, v100, v101
	global_store_dwordx4 v[94:95], v[78:81], off offset:256
	v_cvt_pk_bf16_f32 v76, v82, v83
	v_cvt_pk_bf16_f32 v77, v84, v85
	v_lshl_add_u64 v[78:79], v[74:75], 0, v[148:149]
	v_cvt_pk_bf16_f32 v74, v86, v87
	v_cvt_pk_bf16_f32 v75, v88, v89
	v_cvt_pk_bf16_f32 v73, v68, v69
	v_cvt_pk_bf16_f32 v65, v60, v61
	v_cvt_pk_bf16_f32 v42, v54, v55
	v_cvt_pk_bf16_f32 v43, v56, v57
	v_cvt_pk_bf16_f32 v44, v50, v51
	v_cvt_pk_bf16_f32 v45, v52, v53
	v_cvt_pk_bf16_f32 v26, v38, v39
	v_cvt_pk_bf16_f32 v27, v40, v41
	v_cvt_pk_bf16_f32 v28, v34, v35
	v_cvt_pk_bf16_f32 v29, v36, v37
	v_lshl_add_u64 v[14:15], v[150:151], 0, s[20:21]
	v_cvt_pk_bf16_f32 v10, v22, v23
	v_cvt_pk_bf16_f32 v11, v24, v25
	v_cvt_pk_bf16_f32 v12, v18, v19
	v_cvt_pk_bf16_f32 v13, v20, v21
	v_cvt_pk_bf16_f32 v6, v6, v7
	v_cvt_pk_bf16_f32 v7, v8, v9
	v_cvt_pk_bf16_f32 v8, v2, v3
	v_cvt_pk_bf16_f32 v9, v4, v5
	s_and_b64 vcc, exec, s[0:1]
	s_mov_b32 s45, s18
	s_mov_b32 s46, s30
	s_mov_b64 s[22:23], s[80:81]
	s_mov_b64 s[20:21], s[38:39]
	s_mov_b32 s64, 0x800000
	s_movk_i32 s65, 0x1fff
	v_readlane_b32 s49, v254, 41
	v_readlane_b32 s50, v254, 42
	v_readlane_b32 s51, v254, 43
	v_readlane_b32 s52, v254, 44
	v_readlane_b32 s53, v254, 45
	v_readlane_b32 s54, v254, 46
	v_readlane_b32 s55, v254, 47
	v_readlane_b32 s56, v254, 48
	v_readlane_b32 s57, v254, 49
	v_readlane_b32 s58, v254, 50
	v_readlane_b32 s59, v254, 51
	v_readlane_b32 s60, v254, 52
	v_readlane_b32 s61, v254, 53
	global_store_dwordx4 v[150:151], v[126:129], off
	global_store_dwordx4 v[110:111], v[106:109], off
	global_store_dwordx4 v[94:95], v[90:93], off
	global_store_dwordx4 v[78:79], v[74:77], off
	global_store_dwordx4 v[78:79], v[70:73], off offset:256
	global_store_dwordx4 v[58:59], v[62:65], off
	global_store_dwordx4 v[48:49], v[42:45], off
	global_store_dwordx4 v[32:33], v[26:29], off
	global_store_dwordx4 v[16:17], v[10:13], off
	global_store_dwordx4 v[14:15], v[6:9], off offset:256
	s_cbranch_vccz .LBB0_366
	s_waitcnt vmcnt(0)
	v_readlane_b32 s44, v255, 30
	s_mov_b32 s66, s90
	s_cmpk_gt_u32 s25, 0xff
	v_readlane_b32 s45, v255, 31
	v_readlane_b32 s42, v255, 32
	s_cbranch_scc1 .LBB0_377
	s_barrier

.LBB0_386:
	s_add_u32 s20, s18, 0xfffe0080
	s_addc_u32 s21, s19, -1
	s_add_i32 s50, 0, 0x10000
	s_cmp_eq_u32 s49, 4
	s_cselect_b32 s23, s44, s21
	s_cselect_b32 s22, s45, s20
	s_cselect_b32 s21, s39, s48
	s_cselect_b32 s20, s46, s47
	v_lshl_add_u64 v[178:179], s[18:19], 0, v[146:147]
	s_add_i32 m0, s90, 0xc000
	ds_read_b128 v[162:165], v156
	ds_read_b128 v[166:169], v156 offset:1024
	ds_read_b128 v[170:173], v156 offset:2048
	ds_read_b128 v[174:177], v156 offset:3072
	ds_read_b128 v[192:195], v156 offset:4096
	ds_read_b128 v[196:199], v156 offset:5120
	ds_read_b128 v[200:203], v156 offset:6144
	ds_read_b128 v[204:207], v156 offset:7168
	global_load_lds_dwordx4 v[178:179], off
	v_lshl_add_u64 v[178:179], s[18:19], 0, v[148:149]
	s_add_i32 m0, s90, 0xe000
	s_nop 0
	global_load_lds_dwordx4 v[178:179], off
	s_waitcnt lgkmcnt(8)
	s_barrier
	s_waitcnt lgkmcnt(0)
	v_mfma_f32_16x16x32_bf16 v[126:129], v[130:133], v[162:165], v[126:129]
	v_mfma_f32_16x16x32_bf16 v[122:125], v[150:153], v[162:165], v[122:125]
	v_mfma_f32_16x16x32_bf16 v[118:121], v[130:133], v[170:173], v[118:121]
	v_mfma_f32_16x16x32_bf16 v[110:113], v[150:153], v[170:173], v[110:113]
	v_mfma_f32_16x16x32_bf16 v[102:105], v[130:133], v[192:195], v[102:105]
	v_mfma_f32_16x16x32_bf16 v[94:97], v[150:153], v[192:195], v[94:97]
	v_mfma_f32_16x16x32_bf16 v[86:89], v[130:133], v[200:203], v[86:89]
	v_mfma_f32_16x16x32_bf16 v[78:81], v[150:153], v[200:203], v[78:81]
	v_mfma_f32_16x16x32_bf16 v[126:129], v[134:137], v[166:169], v[126:129]
	v_mfma_f32_16x16x32_bf16 v[122:125], v[158:161], v[166:169], v[122:125]
	v_mfma_f32_16x16x32_bf16 v[118:121], v[134:137], v[174:177], v[118:121]
	v_mfma_f32_16x16x32_bf16 v[110:113], v[158:161], v[174:177], v[110:113]
	v_mfma_f32_16x16x32_bf16 v[102:105], v[134:137], v[196:199], v[102:105]
	v_mfma_f32_16x16x32_bf16 v[94:97], v[158:161], v[196:199], v[94:97]
	v_mfma_f32_16x16x32_bf16 v[86:89], v[134:137], v[204:207], v[86:89]
	v_mfma_f32_16x16x32_bf16 v[78:81], v[158:161], v[204:207], v[78:81]
	s_barrier
	s_add_i32 s52, 0, 0x14000
	s_add_i32 s50, s50, s36
	v_add_u32_e32 v157, s52, v154
	v_lshl_add_u64 v[178:179], s[20:21], 0, v[142:143]
	s_mov_b32 m0, s50
	ds_read_b128 v[208:211], v157
	ds_read_b128 v[224:227], v157 offset:1024
	ds_read_b128 v[228:231], v157 offset:2048
	ds_read_b128 v[232:235], v157 offset:3072
	global_load_lds_dwordx4 v[178:179], off
	v_lshl_add_u64 v[212:213], s[20:21], 0, v[138:139]
	s_add_i32 m0, s50, 0x2000
	s_nop 0
	global_load_lds_dwordx4 v[212:213], off
	s_mov_b32 m0, s90
	v_lshl_add_u64 v[236:237], s[22:23], 0, v[144:145]
	s_barrier
	s_waitcnt lgkmcnt(0)
	v_mfma_f32_16x16x32_bf16 v[114:117], v[208:211], v[162:165], v[114:117]
	v_mfma_f32_16x16x32_bf16 v[106:109], v[228:231], v[162:165], v[106:109]
	v_mfma_f32_16x16x32_bf16 v[98:101], v[208:211], v[170:173], v[98:101]
	v_mfma_f32_16x16x32_bf16 v[90:93], v[228:231], v[170:173], v[90:93]
	v_mfma_f32_16x16x32_bf16 v[82:85], v[208:211], v[192:195], v[82:85]
	v_mfma_f32_16x16x32_bf16 v[74:77], v[228:231], v[192:195], v[74:77]
	v_mfma_f32_16x16x32_bf16 v[70:73], v[208:211], v[200:203], v[70:73]
	v_mfma_f32_16x16x32_bf16 v[66:69], v[228:231], v[200:203], v[66:69]
	v_mfma_f32_16x16x32_bf16 v[114:117], v[224:227], v[166:169], v[114:117]
	v_mfma_f32_16x16x32_bf16 v[106:109], v[232:235], v[166:169], v[106:109]
	v_mfma_f32_16x16x32_bf16 v[98:101], v[224:227], v[174:177], v[98:101]
	v_mfma_f32_16x16x32_bf16 v[90:93], v[232:235], v[174:177], v[90:93]
	v_mfma_f32_16x16x32_bf16 v[82:85], v[224:227], v[196:199], v[82:85]
	v_mfma_f32_16x16x32_bf16 v[74:77], v[232:235], v[196:199], v[74:77]
	v_mfma_f32_16x16x32_bf16 v[70:73], v[224:227], v[204:207], v[70:73]
	v_mfma_f32_16x16x32_bf16 v[66:69], v[232:235], v[204:207], v[66:69]
	s_barrier
	ds_read_b128 v[162:165], v156 offset:16384
	ds_read_b128 v[166:169], v156 offset:17408
	ds_read_b128 v[170:173], v156 offset:18432
	ds_read_b128 v[174:177], v156 offset:19456
	ds_read_b128 v[192:195], v156 offset:20480
	ds_read_b128 v[196:199], v156 offset:21504
	ds_read_b128 v[200:203], v156 offset:22528
	ds_read_b128 v[204:207], v156 offset:23552
	global_load_lds_dwordx4 v[236:237], off
	v_lshl_add_u64 v[238:239], s[22:23], 0, v[140:141]
	s_mov_b32 m0, s91
	s_nop 0
	global_load_lds_dwordx4 v[238:239], off
	s_waitcnt vmcnt(10)
	s_barrier
	s_waitcnt lgkmcnt(0)
	v_mfma_f32_16x16x32_bf16 v[62:65], v[130:133], v[162:165], v[62:65]
	v_mfma_f32_16x16x32_bf16 v[58:61], v[150:153], v[162:165], v[58:61]
	v_mfma_f32_16x16x32_bf16 v[54:57], v[130:133], v[170:173], v[54:57]
	v_mfma_f32_16x16x32_bf16 v[46:49], v[150:153], v[170:173], v[46:49]
	v_mfma_f32_16x16x32_bf16 v[38:41], v[130:133], v[192:195], v[38:41]
	v_mfma_f32_16x16x32_bf16 v[30:33], v[150:153], v[192:195], v[30:33]
	v_mfma_f32_16x16x32_bf16 v[22:25], v[130:133], v[200:203], v[22:25]
	v_mfma_f32_16x16x32_bf16 v[14:17], v[150:153], v[200:203], v[14:17]
	v_mfma_f32_16x16x32_bf16 v[62:65], v[134:137], v[166:169], v[62:65]
	v_mfma_f32_16x16x32_bf16 v[58:61], v[158:161], v[166:169], v[58:61]
	v_mfma_f32_16x16x32_bf16 v[54:57], v[134:137], v[174:177], v[54:57]
	v_mfma_f32_16x16x32_bf16 v[46:49], v[158:161], v[174:177], v[46:49]
	v_mfma_f32_16x16x32_bf16 v[38:41], v[134:137], v[196:199], v[38:41]
	v_mfma_f32_16x16x32_bf16 v[30:33], v[158:161], v[196:199], v[30:33]
	v_mfma_f32_16x16x32_bf16 v[22:25], v[134:137], v[204:207], v[22:25]
	v_mfma_f32_16x16x32_bf16 v[14:17], v[158:161], v[204:207], v[14:17]
	s_barrier
	s_add_u32 s50, s20, 0x20000
	s_addc_u32 s51, s21, 0
	s_add_i32 s52, s52, s36
	v_lshl_add_u64 v[130:131], s[50:51], 0, v[142:143]
	s_mov_b32 m0, s52
	s_nop 0
	global_load_lds_dwordx4 v[130:131], off
	v_lshl_add_u64 v[130:131], s[50:51], 0, v[138:139]
	s_add_i32 m0, s52, 0x2000
	s_nop 0
	global_load_lds_dwordx4 v[130:131], off
	v_add_u32_e32 v157, 0x18000, v154
	ds_read_b128 v[130:133], v157
	ds_read_b128 v[134:137], v157 offset:1024
	ds_read_b128 v[150:153], v157 offset:2048
	ds_read_b128 v[158:161], v157 offset:3072
	s_add_i32 s50, 0, 0x18000
	s_waitcnt vmcnt(6)
	s_barrier
	v_mfma_f32_16x16x32_bf16 v[50:53], v[208:211], v[162:165], v[50:53]
	v_mfma_f32_16x16x32_bf16 v[42:45], v[228:231], v[162:165], v[42:45]
	v_mfma_f32_16x16x32_bf16 v[34:37], v[208:211], v[170:173], v[34:37]
	v_mfma_f32_16x16x32_bf16 v[26:29], v[228:231], v[170:173], v[26:29]
	v_mfma_f32_16x16x32_bf16 v[18:21], v[208:211], v[192:195], v[18:21]
	v_mfma_f32_16x16x32_bf16 v[10:13], v[228:231], v[192:195], v[10:13]
	v_mfma_f32_16x16x32_bf16 v[6:9], v[208:211], v[200:203], v[6:9]
	v_mfma_f32_16x16x32_bf16 v[2:5], v[228:231], v[200:203], v[2:5]
	v_mfma_f32_16x16x32_bf16 v[50:53], v[224:227], v[166:169], v[50:53]
	v_mfma_f32_16x16x32_bf16 v[42:45], v[232:235], v[166:169], v[42:45]
	v_mfma_f32_16x16x32_bf16 v[34:37], v[224:227], v[174:177], v[34:37]
	v_mfma_f32_16x16x32_bf16 v[26:29], v[232:235], v[174:177], v[26:29]
	v_mfma_f32_16x16x32_bf16 v[18:21], v[224:227], v[196:199], v[18:21]
	v_mfma_f32_16x16x32_bf16 v[10:13], v[232:235], v[196:199], v[10:13]
	v_mfma_f32_16x16x32_bf16 v[6:9], v[224:227], v[204:207], v[6:9]
	v_mfma_f32_16x16x32_bf16 v[2:5], v[232:235], v[204:207], v[2:5]
	s_barrier
	s_add_u32 s22, s22, 0x20000
	s_addc_u32 s23, s23, 0
	s_mov_b32 m0, s42
	v_lshl_add_u64 v[208:209], s[22:23], 0, v[144:145]
	ds_read_b128 v[162:165], v156 offset:32768
	ds_read_b128 v[166:169], v156 offset:33792
	ds_read_b128 v[170:173], v156 offset:34816
	ds_read_b128 v[174:177], v156 offset:35840
	ds_read_b128 v[192:195], v156 offset:36864
	ds_read_b128 v[196:199], v156 offset:37888
	ds_read_b128 v[200:203], v156 offset:38912
	ds_read_b128 v[204:207], v156 offset:39936
	global_load_lds_dwordx4 v[208:209], off
	v_lshl_add_u64 v[208:209], s[22:23], 0, v[140:141]
	s_mov_b32 m0, s43
	s_nop 0
	global_load_lds_dwordx4 v[208:209], off
	s_waitcnt lgkmcnt(8)
	s_barrier
	s_waitcnt lgkmcnt(0)
	v_mfma_f32_16x16x32_bf16 v[126:129], v[130:133], v[162:165], v[126:129]
	v_mfma_f32_16x16x32_bf16 v[122:125], v[150:153], v[162:165], v[122:125]
	v_mfma_f32_16x16x32_bf16 v[118:121], v[130:133], v[170:173], v[118:121]
	v_mfma_f32_16x16x32_bf16 v[110:113], v[150:153], v[170:173], v[110:113]
	v_mfma_f32_16x16x32_bf16 v[102:105], v[130:133], v[192:195], v[102:105]
	v_mfma_f32_16x16x32_bf16 v[94:97], v[150:153], v[192:195], v[94:97]
	v_mfma_f32_16x16x32_bf16 v[86:89], v[130:133], v[200:203], v[86:89]
	v_mfma_f32_16x16x32_bf16 v[78:81], v[150:153], v[200:203], v[78:81]
	v_mfma_f32_16x16x32_bf16 v[126:129], v[134:137], v[166:169], v[126:129]
	v_mfma_f32_16x16x32_bf16 v[122:125], v[158:161], v[166:169], v[122:125]
	v_mfma_f32_16x16x32_bf16 v[118:121], v[134:137], v[174:177], v[118:121]
	v_mfma_f32_16x16x32_bf16 v[110:113], v[158:161], v[174:177], v[110:113]
	v_mfma_f32_16x16x32_bf16 v[102:105], v[134:137], v[196:199], v[102:105]
	v_mfma_f32_16x16x32_bf16 v[94:97], v[158:161], v[196:199], v[94:97]
	v_mfma_f32_16x16x32_bf16 v[86:89], v[134:137], v[204:207], v[86:89]
	v_mfma_f32_16x16x32_bf16 v[78:81], v[158:161], v[204:207], v[78:81]
	s_barrier
	s_add_i32 s22, 0, 0x1c000
	s_add_i32 s23, s50, s36
	v_add_u32_e32 v157, s22, v154
	v_lshl_add_u64 v[178:179], v[178:179], 0, s[78:79]
	s_mov_b32 m0, s23
	ds_read_b128 v[208:211], v157
	ds_read_b128 v[224:227], v157 offset:1024
	ds_read_b128 v[228:231], v157 offset:2048
	ds_read_b128 v[232:235], v157 offset:3072
	global_load_lds_dwordx4 v[178:179], off
	v_lshl_add_u64 v[178:179], v[212:213], 0, s[78:79]
	s_add_i32 m0, s23, 0x2000
	s_nop 0
	global_load_lds_dwordx4 v[178:179], off
	s_mov_b32 m0, s25
	v_lshl_add_u64 v[178:179], v[236:237], 0, s[78:79]
	s_barrier
	s_waitcnt lgkmcnt(0)
	v_mfma_f32_16x16x32_bf16 v[114:117], v[208:211], v[162:165], v[114:117]
	v_mfma_f32_16x16x32_bf16 v[106:109], v[228:231], v[162:165], v[106:109]
	v_mfma_f32_16x16x32_bf16 v[98:101], v[208:211], v[170:173], v[98:101]
	v_mfma_f32_16x16x32_bf16 v[90:93], v[228:231], v[170:173], v[90:93]
	v_mfma_f32_16x16x32_bf16 v[82:85], v[208:211], v[192:195], v[82:85]
	v_mfma_f32_16x16x32_bf16 v[74:77], v[228:231], v[192:195], v[74:77]
	v_mfma_f32_16x16x32_bf16 v[70:73], v[208:211], v[200:203], v[70:73]
	v_mfma_f32_16x16x32_bf16 v[66:69], v[228:231], v[200:203], v[66:69]
	v_mfma_f32_16x16x32_bf16 v[114:117], v[224:227], v[166:169], v[114:117]
	v_mfma_f32_16x16x32_bf16 v[106:109], v[232:235], v[166:169], v[106:109]
	v_mfma_f32_16x16x32_bf16 v[98:101], v[224:227], v[174:177], v[98:101]
	v_mfma_f32_16x16x32_bf16 v[90:93], v[232:235], v[174:177], v[90:93]
	v_mfma_f32_16x16x32_bf16 v[82:85], v[224:227], v[196:199], v[82:85]
	v_mfma_f32_16x16x32_bf16 v[74:77], v[232:235], v[196:199], v[74:77]
	v_mfma_f32_16x16x32_bf16 v[70:73], v[224:227], v[204:207], v[70:73]
	v_mfma_f32_16x16x32_bf16 v[66:69], v[232:235], v[204:207], v[66:69]
	s_barrier
	ds_read_b128 v[162:165], v156 offset:49152
	ds_read_b128 v[166:169], v156 offset:50176
	ds_read_b128 v[170:173], v156 offset:51200
	ds_read_b128 v[174:177], v156 offset:52224
	ds_read_b128 v[192:195], v156 offset:53248
	ds_read_b128 v[196:199], v156 offset:54272
	ds_read_b128 v[200:203], v156 offset:55296
	ds_read_b128 v[204:207], v156 offset:56320
	global_load_lds_dwordx4 v[178:179], off
	v_lshl_add_u64 v[178:179], v[238:239], 0, s[78:79]
	s_mov_b32 m0, s26
	s_nop 0
	global_load_lds_dwordx4 v[178:179], off
	s_waitcnt vmcnt(10)
	s_barrier
	s_waitcnt lgkmcnt(0)
	v_mfma_f32_16x16x32_bf16 v[62:65], v[130:133], v[162:165], v[62:65]
	v_mfma_f32_16x16x32_bf16 v[58:61], v[150:153], v[162:165], v[58:61]
	v_mfma_f32_16x16x32_bf16 v[54:57], v[130:133], v[170:173], v[54:57]
	v_mfma_f32_16x16x32_bf16 v[46:49], v[150:153], v[170:173], v[46:49]
	v_mfma_f32_16x16x32_bf16 v[38:41], v[130:133], v[192:195], v[38:41]
	v_mfma_f32_16x16x32_bf16 v[30:33], v[150:153], v[192:195], v[30:33]
	v_mfma_f32_16x16x32_bf16 v[22:25], v[130:133], v[200:203], v[22:25]
	v_mfma_f32_16x16x32_bf16 v[14:17], v[150:153], v[200:203], v[14:17]
	v_mfma_f32_16x16x32_bf16 v[62:65], v[134:137], v[166:169], v[62:65]
	v_mfma_f32_16x16x32_bf16 v[58:61], v[158:161], v[166:169], v[58:61]
	v_mfma_f32_16x16x32_bf16 v[54:57], v[134:137], v[174:177], v[54:57]
	v_mfma_f32_16x16x32_bf16 v[46:49], v[158:161], v[174:177], v[46:49]
	v_mfma_f32_16x16x32_bf16 v[38:41], v[134:137], v[196:199], v[38:41]
	v_mfma_f32_16x16x32_bf16 v[30:33], v[158:161], v[196:199], v[30:33]
	v_mfma_f32_16x16x32_bf16 v[22:25], v[134:137], v[204:207], v[22:25]
	v_mfma_f32_16x16x32_bf16 v[14:17], v[158:161], v[204:207], v[14:17]
	s_barrier
	s_add_u32 s20, s20, 0x20080
	s_addc_u32 s21, s21, 0
	s_add_i32 s22, s22, s36
	v_lshl_add_u64 v[130:131], s[20:21], 0, v[142:143]
	s_mov_b32 m0, s22
	s_nop 0
	global_load_lds_dwordx4 v[130:131], off
	v_lshl_add_u64 v[130:131], s[20:21], 0, v[138:139]
	s_add_i32 m0, s22, 0x2000
	s_nop 0
	global_load_lds_dwordx4 v[130:131], off
	v_add_u32_e32 v157, 0x10000, v154
	ds_read_b128 v[130:133], v157
	ds_read_b128 v[134:137], v157 offset:1024
	ds_read_b128 v[150:153], v157 offset:2048
	ds_read_b128 v[158:161], v157 offset:3072
	s_add_i32 s49, s49, 2
	s_add_u32 s18, s18, 0x100
	s_addc_u32 s19, s19, 0
	s_add_u32 s47, s47, 0x100
	s_addc_u32 s48, s48, 0
	s_cmp_gt_u32 s49, 5
	s_waitcnt vmcnt(6)
	s_barrier
	v_mfma_f32_16x16x32_bf16 v[50:53], v[208:211], v[162:165], v[50:53]
	v_mfma_f32_16x16x32_bf16 v[42:45], v[228:231], v[162:165], v[42:45]
	v_mfma_f32_16x16x32_bf16 v[34:37], v[208:211], v[170:173], v[34:37]
	v_mfma_f32_16x16x32_bf16 v[26:29], v[228:231], v[170:173], v[26:29]
	v_mfma_f32_16x16x32_bf16 v[18:21], v[208:211], v[192:195], v[18:21]
	v_mfma_f32_16x16x32_bf16 v[10:13], v[228:231], v[192:195], v[10:13]
	v_mfma_f32_16x16x32_bf16 v[6:9], v[208:211], v[200:203], v[6:9]
	v_mfma_f32_16x16x32_bf16 v[2:5], v[228:231], v[200:203], v[2:5]
	v_mfma_f32_16x16x32_bf16 v[50:53], v[224:227], v[166:169], v[50:53]
	v_mfma_f32_16x16x32_bf16 v[42:45], v[232:235], v[166:169], v[42:45]
	v_mfma_f32_16x16x32_bf16 v[34:37], v[224:227], v[174:177], v[34:37]
	v_mfma_f32_16x16x32_bf16 v[26:29], v[232:235], v[174:177], v[26:29]
	v_mfma_f32_16x16x32_bf16 v[18:21], v[224:227], v[196:199], v[18:21]
	v_mfma_f32_16x16x32_bf16 v[10:13], v[232:235], v[196:199], v[10:13]
	v_mfma_f32_16x16x32_bf16 v[6:9], v[224:227], v[204:207], v[6:9]
	v_mfma_f32_16x16x32_bf16 v[2:5], v[232:235], v[204:207], v[2:5]
	s_barrier
	s_cbranch_scc0 .LBB0_386
	s_waitcnt lgkmcnt(0)
	v_lshl_add_u32 v164, s29, 8, v1
	v_lshl_or_b32 v150, s28, 8, v155
	s_mov_b64 s[18:19], -1
	s_cmp_lt_i32 s28, 8
	v_or_b32_e32 v163, 16, v164
	v_or_b32_e32 v162, 32, v164
	v_or_b32_e32 v161, 48, v164
	v_add_u32_e32 v160, 0x80, v164
	v_add_u32_e32 v159, 0x90, v164
	v_add_u32_e32 v158, 0xa0, v164
	v_add_u32_e32 v157, 0xb0, v164
	s_cbranch_scc1 .LBB0_389
	v_lshlrev_b32_e32 v130, 7, v164
	v_readlane_b32 s4, v255, 4
	v_and_b32_e32 v132, 0x3e780, v130
	v_mov_b32_e32 v133, v0
	v_readlane_b32 s5, v255, 5
	v_readlane_b32 s6, v255, 6
	v_readlane_b32 s7, v255, 7
	v_lshlrev_b32_e32 v130, 1, v150
	v_lshl_add_u64 v[134:135], s[4:5], 0, v[132:133]
	v_and_b32_e32 v130, 0x70, v130
	v_mov_b32_e32 v131, v0
	v_lshl_add_u64 v[132:133], s[6:7], 0, v[132:133]
	v_lshl_add_u64 v[152:153], v[132:133], 0, v[130:131]
	v_lshl_add_u64 v[136:137], v[134:135], 0, v[130:131]
	global_load_dwordx4 v[170:173], v[152:153], off
	global_load_dwordx4 v[166:169], v[136:137], off
	v_readlane_b32 s8, v255, 8
	v_readlane_b32 s9, v255, 9
	v_mov_b32_e32 v151, v0
	v_lshlrev_b64 v[134:135], 1, v[150:151]
	v_mov_b64_e32 v[132:133], s[8:9]
	v_mad_i64_i32 v[174:175], s[18:19], v164, s24, v[132:133]
	v_lshl_add_u64 v[174:175], v[174:175], 0, v[134:135]
	v_readlane_b32 s10, v255, 10
	v_readlane_b32 s11, v255, 11
	s_waitcnt vmcnt(0)
	v_pk_mul_f32 v[172:173], v[172:173], s[86:87] op_sel_hi:[1,0]
	v_pk_mul_f32 v[170:171], v[170:171], s[86:87] op_sel_hi:[1,0]
	v_pk_mul_f32 v[168:169], v[168:169], s[86:87] op_sel_hi:[1,0]
	v_pk_mul_f32 v[166:167], v[166:167], s[86:87] op_sel_hi:[1,0]
	v_pk_mul_f32 v[176:177], v[124:125], v[172:173]
	v_pk_mul_f32 v[178:179], v[122:123], v[170:171]
	v_pk_mul_f32 v[172:173], v[128:129], v[172:173]
	v_pk_mul_f32 v[170:171], v[126:127], v[170:171]
	v_pk_fma_f32 v[176:177], v[128:129], v[168:169], v[176:177] neg_lo:[0,0,1] neg_hi:[0,0,1]
	v_pk_fma_f32 v[178:179], v[126:127], v[166:167], v[178:179] neg_lo:[0,0,1] neg_hi:[0,0,1]
	v_pk_fma_f32 v[172:173], v[124:125], v[168:169], v[172:173]
	v_pk_fma_f32 v[168:169], v[122:123], v[166:167], v[170:171]
	v_cvt_pk_bf16_f32 v166, v178, v179
	v_cvt_pk_bf16_f32 v167, v176, v177
	v_cvt_pk_bf16_f32 v168, v168, v169
	v_cvt_pk_bf16_f32 v169, v172, v173
	global_store_dwordx4 v[174:175], v[166:169], off
	global_load_dwordx4 v[166:169], v[136:137], off
	s_nop 0
	global_load_dwordx4 v[170:173], v[152:153], off
	v_lshlrev_b32_e32 v136, 7, v163
	v_mov_b32_e32 v137, v0
	v_and_b32_e32 v136, 0x3ef80, v136
	v_lshl_add_u64 v[152:153], s[4:5], 0, v[136:137]
	v_lshl_add_u64 v[136:137], s[6:7], 0, v[136:137]
	v_lshl_add_u64 v[136:137], v[136:137], 0, v[130:131]
	v_lshl_add_u64 v[152:153], v[152:153], 0, v[130:131]
	s_waitcnt vmcnt(0)
	v_pk_mul_f32 v[168:169], v[168:169], s[86:87] op_sel_hi:[1,0]
	v_pk_mul_f32 v[172:173], v[172:173], s[86:87] op_sel_hi:[1,0]
	v_pk_mul_f32 v[170:171], v[170:171], s[86:87] op_sel_hi:[1,0]
	v_pk_mul_f32 v[166:167], v[166:167], s[86:87] op_sel_hi:[1,0]
	v_pk_mul_f32 v[176:177], v[108:109], v[172:173]
	v_pk_mul_f32 v[178:179], v[106:107], v[170:171]
	v_pk_mul_f32 v[172:173], v[116:117], v[172:173]
	v_pk_mul_f32 v[170:171], v[114:115], v[170:171]
	v_pk_fma_f32 v[176:177], v[116:117], v[168:169], v[176:177] neg_lo:[0,0,1] neg_hi:[0,0,1]
	v_pk_fma_f32 v[178:179], v[114:115], v[166:167], v[178:179] neg_lo:[0,0,1] neg_hi:[0,0,1]
	v_pk_fma_f32 v[172:173], v[108:109], v[168:169], v[172:173]
	v_pk_fma_f32 v[168:169], v[106:107], v[166:167], v[170:171]
	v_cvt_pk_bf16_f32 v166, v178, v179
	v_cvt_pk_bf16_f32 v167, v176, v177
	v_cvt_pk_bf16_f32 v168, v168, v169
	v_cvt_pk_bf16_f32 v169, v172, v173
	global_store_dwordx4 v[174:175], v[166:169], off offset:256
	global_load_dwordx4 v[170:173], v[136:137], off
	v_mad_i64_i32 v[174:175], s[18:19], v163, s24, v[132:133]
	global_load_dwordx4 v[166:169], v[152:153], off
	v_lshl_add_u64 v[174:175], v[174:175], 0, v[134:135]
	s_waitcnt vmcnt(0)
	v_pk_mul_f32 v[172:173], v[172:173], s[86:87] op_sel_hi:[1,0]
	v_pk_mul_f32 v[170:171], v[170:171], s[86:87] op_sel_hi:[1,0]
	v_pk_mul_f32 v[176:177], v[112:113], v[172:173]
	v_pk_mul_f32 v[168:169], v[168:169], s[86:87] op_sel_hi:[1,0]
	v_pk_mul_f32 v[166:167], v[166:167], s[86:87] op_sel_hi:[1,0]
	v_pk_mul_f32 v[178:179], v[110:111], v[170:171]
	v_pk_mul_f32 v[172:173], v[120:121], v[172:173]
	v_pk_mul_f32 v[170:171], v[118:119], v[170:171]
	v_pk_fma_f32 v[176:177], v[120:121], v[168:169], v[176:177] neg_lo:[0,0,1] neg_hi:[0,0,1]
	v_pk_fma_f32 v[178:179], v[118:119], v[166:167], v[178:179] neg_lo:[0,0,1] neg_hi:[0,0,1]
	v_pk_fma_f32 v[172:173], v[112:113], v[168:169], v[172:173]
	v_pk_fma_f32 v[168:169], v[110:111], v[166:167], v[170:171]
	v_cvt_pk_bf16_f32 v166, v178, v179
	v_cvt_pk_bf16_f32 v167, v176, v177
	v_cvt_pk_bf16_f32 v168, v168, v169
	v_cvt_pk_bf16_f32 v169, v172, v173
	global_store_dwordx4 v[174:175], v[166:169], off
	global_load_dwordx4 v[166:169], v[152:153], off
	s_nop 0
	global_load_dwordx4 v[170:173], v[136:137], off
	v_lshlrev_b32_e32 v136, 7, v162
	v_mov_b32_e32 v137, v0
	v_and_b32_e32 v136, 0x3f780, v136
	v_lshl_add_u64 v[152:153], s[4:5], 0, v[136:137]
	v_lshl_add_u64 v[136:137], s[6:7], 0, v[136:137]
	v_lshl_add_u64 v[136:137], v[136:137], 0, v[130:131]
	v_lshl_add_u64 v[152:153], v[152:153], 0, v[130:131]
	s_waitcnt vmcnt(0)
	v_pk_mul_f32 v[168:169], v[168:169], s[86:87] op_sel_hi:[1,0]
	v_pk_mul_f32 v[172:173], v[172:173], s[86:87] op_sel_hi:[1,0]
	v_pk_mul_f32 v[170:171], v[170:171], s[86:87] op_sel_hi:[1,0]
	v_pk_mul_f32 v[166:167], v[166:167], s[86:87] op_sel_hi:[1,0]
	v_pk_mul_f32 v[176:177], v[92:93], v[172:173]
	v_pk_mul_f32 v[178:179], v[90:91], v[170:171]
	v_pk_mul_f32 v[172:173], v[100:101], v[172:173]
	v_pk_mul_f32 v[170:171], v[98:99], v[170:171]
	v_pk_fma_f32 v[176:177], v[100:101], v[168:169], v[176:177] neg_lo:[0,0,1] neg_hi:[0,0,1]
	v_pk_fma_f32 v[178:179], v[98:99], v[166:167], v[178:179] neg_lo:[0,0,1] neg_hi:[0,0,1]
	v_pk_fma_f32 v[172:173], v[92:93], v[168:169], v[172:173]
	v_pk_fma_f32 v[168:169], v[90:91], v[166:167], v[170:171]
	v_cvt_pk_bf16_f32 v166, v178, v179
	v_cvt_pk_bf16_f32 v167, v176, v177
	v_cvt_pk_bf16_f32 v168, v168, v169
	v_cvt_pk_bf16_f32 v169, v172, v173
	global_store_dwordx4 v[174:175], v[166:169], off offset:256
	global_load_dwordx4 v[170:173], v[136:137], off
	v_mad_i64_i32 v[174:175], s[18:19], v162, s24, v[132:133]
	global_load_dwordx4 v[166:169], v[152:153], off
	v_lshl_add_u64 v[174:175], v[174:175], 0, v[134:135]
	s_waitcnt vmcnt(0)
	v_pk_mul_f32 v[172:173], v[172:173], s[86:87] op_sel_hi:[1,0]
	v_pk_mul_f32 v[170:171], v[170:171], s[86:87] op_sel_hi:[1,0]
	v_pk_mul_f32 v[176:177], v[96:97], v[172:173]
	v_pk_mul_f32 v[168:169], v[168:169], s[86:87] op_sel_hi:[1,0]
	v_pk_mul_f32 v[166:167], v[166:167], s[86:87] op_sel_hi:[1,0]
	v_pk_mul_f32 v[178:179], v[94:95], v[170:171]
	v_pk_mul_f32 v[172:173], v[104:105], v[172:173]
	v_pk_mul_f32 v[170:171], v[102:103], v[170:171]
	v_pk_fma_f32 v[176:177], v[104:105], v[168:169], v[176:177] neg_lo:[0,0,1] neg_hi:[0,0,1]
	v_pk_fma_f32 v[178:179], v[102:103], v[166:167], v[178:179] neg_lo:[0,0,1] neg_hi:[0,0,1]
	v_pk_fma_f32 v[172:173], v[96:97], v[168:169], v[172:173]
	v_pk_fma_f32 v[168:169], v[94:95], v[166:167], v[170:171]
	v_cvt_pk_bf16_f32 v166, v178, v179
	v_cvt_pk_bf16_f32 v167, v176, v177
	v_cvt_pk_bf16_f32 v168, v168, v169
	v_cvt_pk_bf16_f32 v169, v172, v173
	global_store_dwordx4 v[174:175], v[166:169], off
	global_load_dwordx4 v[166:169], v[152:153], off
	s_nop 0
	global_load_dwordx4 v[170:173], v[136:137], off
	v_lshlrev_b32_e32 v136, 7, v161
	v_mov_b32_e32 v137, v0
	v_and_b32_e32 v136, 0x3ff80, v136
	v_lshl_add_u64 v[152:153], s[4:5], 0, v[136:137]
	v_lshl_add_u64 v[136:137], s[6:7], 0, v[136:137]
	v_lshl_add_u64 v[136:137], v[136:137], 0, v[130:131]
	v_lshl_add_u64 v[152:153], v[152:153], 0, v[130:131]
	s_waitcnt vmcnt(0)
	v_pk_mul_f32 v[168:169], v[168:169], s[86:87] op_sel_hi:[1,0]
	v_pk_mul_f32 v[172:173], v[172:173], s[86:87] op_sel_hi:[1,0]
	v_pk_mul_f32 v[170:171], v[170:171], s[86:87] op_sel_hi:[1,0]
	v_pk_mul_f32 v[166:167], v[166:167], s[86:87] op_sel_hi:[1,0]
	v_pk_mul_f32 v[176:177], v[76:77], v[172:173]
	v_pk_mul_f32 v[178:179], v[74:75], v[170:171]
	v_pk_mul_f32 v[172:173], v[84:85], v[172:173]
	v_pk_mul_f32 v[170:171], v[82:83], v[170:171]
	v_pk_fma_f32 v[176:177], v[84:85], v[168:169], v[176:177] neg_lo:[0,0,1] neg_hi:[0,0,1]
	v_pk_fma_f32 v[178:179], v[82:83], v[166:167], v[178:179] neg_lo:[0,0,1] neg_hi:[0,0,1]
	v_pk_fma_f32 v[172:173], v[76:77], v[168:169], v[172:173]
	v_pk_fma_f32 v[168:169], v[74:75], v[166:167], v[170:171]
	v_cvt_pk_bf16_f32 v166, v178, v179
	v_cvt_pk_bf16_f32 v167, v176, v177
	v_cvt_pk_bf16_f32 v168, v168, v169
	v_cvt_pk_bf16_f32 v169, v172, v173
	global_store_dwordx4 v[174:175], v[166:169], off offset:256
	global_load_dwordx4 v[170:173], v[136:137], off
	v_mad_i64_i32 v[174:175], s[18:19], v161, s24, v[132:133]
	global_load_dwordx4 v[166:169], v[152:153], off
	v_lshl_add_u64 v[174:175], v[174:175], 0, v[134:135]
	s_waitcnt vmcnt(0)
	v_pk_mul_f32 v[172:173], v[172:173], s[86:87] op_sel_hi:[1,0]
	v_pk_mul_f32 v[170:171], v[170:171], s[86:87] op_sel_hi:[1,0]
	v_pk_mul_f32 v[176:177], v[80:81], v[172:173]
	v_pk_mul_f32 v[168:169], v[168:169], s[86:87] op_sel_hi:[1,0]
	v_pk_mul_f32 v[166:167], v[166:167], s[86:87] op_sel_hi:[1,0]
	v_pk_mul_f32 v[178:179], v[78:79], v[170:171]
	v_pk_mul_f32 v[172:173], v[88:89], v[172:173]
	v_pk_mul_f32 v[170:171], v[86:87], v[170:171]
	v_pk_fma_f32 v[176:177], v[88:89], v[168:169], v[176:177] neg_lo:[0,0,1] neg_hi:[0,0,1]
	v_pk_fma_f32 v[178:179], v[86:87], v[166:167], v[178:179] neg_lo:[0,0,1] neg_hi:[0,0,1]
	v_pk_fma_f32 v[172:173], v[80:81], v[168:169], v[172:173]
	v_pk_fma_f32 v[168:169], v[78:79], v[166:167], v[170:171]
	v_cvt_pk_bf16_f32 v166, v178, v179
	v_cvt_pk_bf16_f32 v167, v176, v177
	v_cvt_pk_bf16_f32 v168, v168, v169
	v_cvt_pk_bf16_f32 v169, v172, v173
	global_store_dwordx4 v[174:175], v[166:169], off
	global_load_dwordx4 v[166:169], v[152:153], off
	s_nop 0
	global_load_dwordx4 v[170:173], v[136:137], off
	v_lshlrev_b32_e32 v136, 7, v160
	v_mov_b32_e32 v137, v0
	v_and_b32_e32 v136, 0x3e780, v136
	v_lshl_add_u64 v[152:153], s[4:5], 0, v[136:137]
	v_lshl_add_u64 v[136:137], s[6:7], 0, v[136:137]
	v_lshl_add_u64 v[136:137], v[136:137], 0, v[130:131]
	v_lshl_add_u64 v[152:153], v[152:153], 0, v[130:131]
	s_waitcnt vmcnt(0)
	v_pk_mul_f32 v[168:169], v[168:169], s[86:87] op_sel_hi:[1,0]
	v_pk_mul_f32 v[172:173], v[172:173], s[86:87] op_sel_hi:[1,0]
	v_pk_mul_f32 v[170:171], v[170:171], s[86:87] op_sel_hi:[1,0]
	v_pk_mul_f32 v[166:167], v[166:167], s[86:87] op_sel_hi:[1,0]
	v_pk_mul_f32 v[176:177], v[68:69], v[172:173]
	v_pk_mul_f32 v[178:179], v[66:67], v[170:171]
	v_pk_mul_f32 v[172:173], v[72:73], v[172:173]
	v_pk_mul_f32 v[170:171], v[70:71], v[170:171]
	v_pk_fma_f32 v[176:177], v[72:73], v[168:169], v[176:177] neg_lo:[0,0,1] neg_hi:[0,0,1]
	v_pk_fma_f32 v[178:179], v[70:71], v[166:167], v[178:179] neg_lo:[0,0,1] neg_hi:[0,0,1]
	v_pk_fma_f32 v[172:173], v[68:69], v[168:169], v[172:173]
	v_pk_fma_f32 v[168:169], v[66:67], v[166:167], v[170:171]
	v_cvt_pk_bf16_f32 v166, v178, v179
	v_cvt_pk_bf16_f32 v167, v176, v177
	v_cvt_pk_bf16_f32 v168, v168, v169
	v_cvt_pk_bf16_f32 v169, v172, v173
	global_store_dwordx4 v[174:175], v[166:169], off offset:256
	global_load_dwordx4 v[170:173], v[136:137], off
	v_mad_i64_i32 v[174:175], s[18:19], v160, s24, v[132:133]
	global_load_dwordx4 v[166:169], v[152:153], off
	v_lshl_add_u64 v[174:175], v[174:175], 0, v[134:135]
	s_waitcnt vmcnt(0)
	v_pk_mul_f32 v[172:173], v[172:173], s[86:87] op_sel_hi:[1,0]
	v_pk_mul_f32 v[170:171], v[170:171], s[86:87] op_sel_hi:[1,0]
	v_pk_mul_f32 v[176:177], v[60:61], v[172:173]
	v_pk_mul_f32 v[168:169], v[168:169], s[86:87] op_sel_hi:[1,0]
	v_pk_mul_f32 v[166:167], v[166:167], s[86:87] op_sel_hi:[1,0]
	v_pk_mul_f32 v[178:179], v[58:59], v[170:171]
	v_pk_mul_f32 v[172:173], v[64:65], v[172:173]
	v_pk_mul_f32 v[170:171], v[62:63], v[170:171]
	v_pk_fma_f32 v[176:177], v[64:65], v[168:169], v[176:177] neg_lo:[0,0,1] neg_hi:[0,0,1]
	v_pk_fma_f32 v[178:179], v[62:63], v[166:167], v[178:179] neg_lo:[0,0,1] neg_hi:[0,0,1]
	v_pk_fma_f32 v[172:173], v[60:61], v[168:169], v[172:173]
	v_pk_fma_f32 v[168:169], v[58:59], v[166:167], v[170:171]
	v_cvt_pk_bf16_f32 v166, v178, v179
	v_cvt_pk_bf16_f32 v167, v176, v177
	v_cvt_pk_bf16_f32 v168, v168, v169
	v_cvt_pk_bf16_f32 v169, v172, v173
	global_store_dwordx4 v[174:175], v[166:169], off
	global_load_dwordx4 v[166:169], v[152:153], off
	s_nop 0
	global_load_dwordx4 v[170:173], v[136:137], off
	v_lshlrev_b32_e32 v136, 7, v159
	v_mov_b32_e32 v137, v0
	v_and_b32_e32 v136, 0x3ef80, v136
	v_lshl_add_u64 v[152:153], s[4:5], 0, v[136:137]
	v_lshl_add_u64 v[136:137], s[6:7], 0, v[136:137]
	v_lshl_add_u64 v[136:137], v[136:137], 0, v[130:131]
	v_lshl_add_u64 v[152:153], v[152:153], 0, v[130:131]
	s_waitcnt vmcnt(0)
	v_pk_mul_f32 v[168:169], v[168:169], s[86:87] op_sel_hi:[1,0]
	v_pk_mul_f32 v[172:173], v[172:173], s[86:87] op_sel_hi:[1,0]
	v_pk_mul_f32 v[170:171], v[170:171], s[86:87] op_sel_hi:[1,0]
	v_pk_mul_f32 v[166:167], v[166:167], s[86:87] op_sel_hi:[1,0]
	v_pk_mul_f32 v[176:177], v[44:45], v[172:173]
	v_pk_mul_f32 v[178:179], v[42:43], v[170:171]
	v_pk_mul_f32 v[172:173], v[52:53], v[172:173]
	v_pk_mul_f32 v[170:171], v[50:51], v[170:171]
	v_pk_fma_f32 v[176:177], v[52:53], v[168:169], v[176:177] neg_lo:[0,0,1] neg_hi:[0,0,1]
	v_pk_fma_f32 v[178:179], v[50:51], v[166:167], v[178:179] neg_lo:[0,0,1] neg_hi:[0,0,1]
	v_pk_fma_f32 v[172:173], v[44:45], v[168:169], v[172:173]
	v_pk_fma_f32 v[168:169], v[42:43], v[166:167], v[170:171]
	v_cvt_pk_bf16_f32 v166, v178, v179
	v_cvt_pk_bf16_f32 v167, v176, v177
	v_cvt_pk_bf16_f32 v168, v168, v169
	v_cvt_pk_bf16_f32 v169, v172, v173
	global_store_dwordx4 v[174:175], v[166:169], off offset:256
	global_load_dwordx4 v[170:173], v[136:137], off
	v_mad_i64_i32 v[174:175], s[18:19], v159, s24, v[132:133]
	global_load_dwordx4 v[166:169], v[152:153], off
	v_lshl_add_u64 v[174:175], v[174:175], 0, v[134:135]
	s_waitcnt vmcnt(0)
	v_pk_mul_f32 v[172:173], v[172:173], s[86:87] op_sel_hi:[1,0]
	v_pk_mul_f32 v[170:171], v[170:171], s[86:87] op_sel_hi:[1,0]
	v_pk_mul_f32 v[176:177], v[48:49], v[172:173]
	v_pk_mul_f32 v[168:169], v[168:169], s[86:87] op_sel_hi:[1,0]
	v_pk_mul_f32 v[166:167], v[166:167], s[86:87] op_sel_hi:[1,0]
	v_pk_mul_f32 v[178:179], v[46:47], v[170:171]
	v_pk_mul_f32 v[172:173], v[56:57], v[172:173]
	v_pk_mul_f32 v[170:171], v[54:55], v[170:171]
	v_pk_fma_f32 v[176:177], v[56:57], v[168:169], v[176:177] neg_lo:[0,0,1] neg_hi:[0,0,1]
	v_pk_fma_f32 v[178:179], v[54:55], v[166:167], v[178:179] neg_lo:[0,0,1] neg_hi:[0,0,1]
	v_pk_fma_f32 v[172:173], v[48:49], v[168:169], v[172:173]
	v_pk_fma_f32 v[168:169], v[46:47], v[166:167], v[170:171]
	v_cvt_pk_bf16_f32 v166, v178, v179
	v_cvt_pk_bf16_f32 v167, v176, v177
	v_cvt_pk_bf16_f32 v168, v168, v169
	v_cvt_pk_bf16_f32 v169, v172, v173
	global_store_dwordx4 v[174:175], v[166:169], off
	global_load_dwordx4 v[166:169], v[152:153], off
	s_nop 0
	global_load_dwordx4 v[170:173], v[136:137], off
	v_lshlrev_b32_e32 v136, 7, v158
	v_mov_b32_e32 v137, v0
	v_and_b32_e32 v136, 0x3f780, v136
	v_lshl_add_u64 v[152:153], s[4:5], 0, v[136:137]
	v_lshl_add_u64 v[136:137], s[6:7], 0, v[136:137]
	v_lshl_add_u64 v[136:137], v[136:137], 0, v[130:131]
	v_lshl_add_u64 v[152:153], v[152:153], 0, v[130:131]
	s_waitcnt vmcnt(0)
	v_pk_mul_f32 v[168:169], v[168:169], s[86:87] op_sel_hi:[1,0]
	v_pk_mul_f32 v[172:173], v[172:173], s[86:87] op_sel_hi:[1,0]
	v_pk_mul_f32 v[170:171], v[170:171], s[86:87] op_sel_hi:[1,0]
	v_pk_mul_f32 v[166:167], v[166:167], s[86:87] op_sel_hi:[1,0]
	v_pk_mul_f32 v[176:177], v[28:29], v[172:173]
	v_pk_mul_f32 v[178:179], v[26:27], v[170:171]
	v_pk_mul_f32 v[172:173], v[36:37], v[172:173]
	v_pk_mul_f32 v[170:171], v[34:35], v[170:171]
	v_pk_fma_f32 v[176:177], v[36:37], v[168:169], v[176:177] neg_lo:[0,0,1] neg_hi:[0,0,1]
	v_pk_fma_f32 v[178:179], v[34:35], v[166:167], v[178:179] neg_lo:[0,0,1] neg_hi:[0,0,1]
	v_pk_fma_f32 v[172:173], v[28:29], v[168:169], v[172:173]
	v_pk_fma_f32 v[168:169], v[26:27], v[166:167], v[170:171]
	v_cvt_pk_bf16_f32 v166, v178, v179
	v_cvt_pk_bf16_f32 v167, v176, v177
	v_cvt_pk_bf16_f32 v168, v168, v169
	v_cvt_pk_bf16_f32 v169, v172, v173
	global_store_dwordx4 v[174:175], v[166:169], off offset:256
	global_load_dwordx4 v[170:173], v[136:137], off
	v_mad_i64_i32 v[174:175], s[18:19], v158, s24, v[132:133]
	global_load_dwordx4 v[166:169], v[152:153], off
	v_lshl_add_u64 v[174:175], v[174:175], 0, v[134:135]
	s_waitcnt vmcnt(0)
	v_pk_mul_f32 v[172:173], v[172:173], s[86:87] op_sel_hi:[1,0]
	v_pk_mul_f32 v[170:171], v[170:171], s[86:87] op_sel_hi:[1,0]
	v_pk_mul_f32 v[176:177], v[32:33], v[172:173]
	v_pk_mul_f32 v[168:169], v[168:169], s[86:87] op_sel_hi:[1,0]
	v_pk_mul_f32 v[166:167], v[166:167], s[86:87] op_sel_hi:[1,0]
	v_pk_mul_f32 v[178:179], v[30:31], v[170:171]
	v_pk_mul_f32 v[172:173], v[40:41], v[172:173]
	v_pk_mul_f32 v[170:171], v[38:39], v[170:171]
	v_pk_fma_f32 v[176:177], v[40:41], v[168:169], v[176:177] neg_lo:[0,0,1] neg_hi:[0,0,1]
	v_pk_fma_f32 v[178:179], v[38:39], v[166:167], v[178:179] neg_lo:[0,0,1] neg_hi:[0,0,1]
	v_pk_fma_f32 v[172:173], v[32:33], v[168:169], v[172:173]
	v_pk_fma_f32 v[168:169], v[30:31], v[166:167], v[170:171]
	v_cvt_pk_bf16_f32 v166, v178, v179
	v_cvt_pk_bf16_f32 v167, v176, v177
	v_cvt_pk_bf16_f32 v168, v168, v169
	v_cvt_pk_bf16_f32 v169, v172, v173
	global_store_dwordx4 v[174:175], v[166:169], off
	global_load_dwordx4 v[166:169], v[152:153], off
	s_nop 0
	global_load_dwordx4 v[170:173], v[136:137], off
	v_lshlrev_b32_e32 v136, 7, v157
	v_mov_b32_e32 v137, v0
	v_and_b32_e32 v136, 0x3ff80, v136
	v_lshl_add_u64 v[152:153], s[4:5], 0, v[136:137]
	v_lshl_add_u64 v[176:177], v[152:153], 0, v[130:131]
	v_lshl_add_u64 v[136:137], s[6:7], 0, v[136:137]
	v_lshl_add_u64 v[136:137], v[136:137], 0, v[130:131]
	v_mad_i64_i32 v[130:131], s[18:19], v157, s24, v[132:133]
	s_mov_b64 s[18:19], 0
	s_waitcnt vmcnt(0)
	v_pk_mul_f32 v[152:153], v[168:169], s[86:87] op_sel_hi:[1,0]
	v_pk_mul_f32 v[168:169], v[172:173], s[86:87] op_sel_hi:[1,0]
	v_pk_mul_f32 v[170:171], v[170:171], s[86:87] op_sel_hi:[1,0]
	v_pk_mul_f32 v[166:167], v[166:167], s[86:87] op_sel_hi:[1,0]
	v_pk_mul_f32 v[172:173], v[12:13], v[168:169]
	v_pk_mul_f32 v[178:179], v[10:11], v[170:171]
	v_pk_mul_f32 v[168:169], v[20:21], v[168:169]
	v_pk_mul_f32 v[170:171], v[18:19], v[170:171]
	v_pk_fma_f32 v[172:173], v[20:21], v[152:153], v[172:173] neg_lo:[0,0,1] neg_hi:[0,0,1]
	v_pk_fma_f32 v[178:179], v[18:19], v[166:167], v[178:179] neg_lo:[0,0,1] neg_hi:[0,0,1]
	v_pk_fma_f32 v[152:153], v[12:13], v[152:153], v[168:169]
	v_pk_fma_f32 v[168:169], v[10:11], v[166:167], v[170:171]
	v_cvt_pk_bf16_f32 v166, v178, v179
	v_cvt_pk_bf16_f32 v167, v172, v173
	v_cvt_pk_bf16_f32 v168, v168, v169
	v_cvt_pk_bf16_f32 v169, v152, v153
	global_store_dwordx4 v[174:175], v[166:169], off offset:256
	global_load_dwordx4 v[166:169], v[176:177], off
	v_lshl_add_u64 v[152:153], v[130:131], 0, v[134:135]
	global_load_dwordx4 v[170:173], v[136:137], off
	s_waitcnt vmcnt(0)
	v_pk_mul_f32 v[132:133], v[166:167], s[86:87] op_sel_hi:[1,0]
	v_pk_mul_f32 v[130:131], v[168:169], s[86:87] op_sel_hi:[1,0]
	v_pk_mul_f32 v[134:135], v[172:173], s[86:87] op_sel_hi:[1,0]
	v_pk_mul_f32 v[166:167], v[170:171], s[86:87] op_sel_hi:[1,0]
	v_pk_mul_f32 v[168:169], v[16:17], v[134:135]
	v_pk_mul_f32 v[170:171], v[14:15], v[166:167]
	v_pk_mul_f32 v[134:135], v[24:25], v[134:135]
	v_pk_mul_f32 v[166:167], v[22:23], v[166:167]
	v_pk_fma_f32 v[168:169], v[24:25], v[130:131], v[168:169] neg_lo:[0,0,1] neg_hi:[0,0,1]
	v_pk_fma_f32 v[170:171], v[22:23], v[132:133], v[170:171] neg_lo:[0,0,1] neg_hi:[0,0,1]
	v_pk_fma_f32 v[134:135], v[16:17], v[130:131], v[134:135]
	v_pk_fma_f32 v[132:133], v[14:15], v[132:133], v[166:167]
	v_cvt_pk_bf16_f32 v130, v170, v171
	v_cvt_pk_bf16_f32 v131, v168, v169
	v_cvt_pk_bf16_f32 v132, v132, v133
	v_cvt_pk_bf16_f32 v133, v134, v135
	global_store_dwordx4 v[152:153], v[130:133], off
	global_load_dwordx4 v[130:133], v[176:177], off
	s_nop 0
	global_load_dwordx4 v[134:137], v[136:137], off
	s_waitcnt vmcnt(0)
	v_pk_mul_f32 v[166:167], v[132:133], s[86:87] op_sel_hi:[1,0]
	v_pk_mul_f32 v[168:169], v[130:131], s[86:87] op_sel_hi:[1,0]
	v_pk_mul_f32 v[130:131], v[136:137], s[86:87] op_sel_hi:[1,0]
	v_pk_mul_f32 v[132:133], v[134:135], s[86:87] op_sel_hi:[1,0]
	v_pk_mul_f32 v[134:135], v[4:5], v[130:131]
	v_pk_mul_f32 v[136:137], v[2:3], v[132:133]
	v_pk_mul_f32 v[170:171], v[8:9], v[130:131]
	v_pk_mul_f32 v[172:173], v[6:7], v[132:133]
	v_pk_fma_f32 v[132:133], v[8:9], v[166:167], v[134:135] neg_lo:[0,0,1] neg_hi:[0,0,1]
	v_pk_fma_f32 v[130:131], v[6:7], v[168:169], v[136:137] neg_lo:[0,0,1] neg_hi:[0,0,1]
	v_pk_fma_f32 v[136:137], v[4:5], v[166:167], v[170:171]
	v_pk_fma_f32 v[134:135], v[2:3], v[168:169], v[172:173]

.LBB0_526:
	s_add_u32 s20, s18, 0xfff80080
	s_addc_u32 s21, s19, -1
	s_add_i32 s56, 0, 0x10000
	s_cmp_eq_u32 s55, 28
	s_cselect_b32 s23, s39, s21
	s_cselect_b32 s22, s51, s20
	s_cselect_b32 s21, s31, s54
	s_cselect_b32 s20, s52, s53
	v_lshl_add_u64 v[152:153], s[18:19], 0, v[140:141]
	s_add_i32 m0, s29, 0xc000
	ds_read_b128 v[164:167], v154
	ds_read_b128 v[168:171], v154 offset:1024
	ds_read_b128 v[172:175], v154 offset:2048
	ds_read_b128 v[176:179], v154 offset:3072
	ds_read_b128 v[192:195], v154 offset:4096
	ds_read_b128 v[196:199], v154 offset:5120
	ds_read_b128 v[200:203], v154 offset:6144
	ds_read_b128 v[204:207], v154 offset:7168
	global_load_lds_dwordx4 v[152:153], off
	v_lshl_add_u64 v[152:153], s[18:19], 0, v[142:143]
	s_add_i32 m0, s29, 0xe000
	s_nop 0
	global_load_lds_dwordx4 v[152:153], off
	s_waitcnt lgkmcnt(8)
	s_barrier
	s_waitcnt lgkmcnt(0)
	v_mfma_f32_16x16x32_bf16 v[126:129], v[144:147], v[164:167], v[126:129]
	v_mfma_f32_16x16x32_bf16 v[122:125], v[156:159], v[164:167], v[122:125]
	v_mfma_f32_16x16x32_bf16 v[118:121], v[144:147], v[172:175], v[118:121]
	v_mfma_f32_16x16x32_bf16 v[114:117], v[156:159], v[172:175], v[114:117]
	v_mfma_f32_16x16x32_bf16 v[102:105], v[144:147], v[192:195], v[102:105]
	v_mfma_f32_16x16x32_bf16 v[98:101], v[156:159], v[192:195], v[98:101]
	v_mfma_f32_16x16x32_bf16 v[86:89], v[144:147], v[200:203], v[86:89]
	v_mfma_f32_16x16x32_bf16 v[82:85], v[156:159], v[200:203], v[82:85]
	v_mfma_f32_16x16x32_bf16 v[126:129], v[148:151], v[168:171], v[126:129]
	v_mfma_f32_16x16x32_bf16 v[122:125], v[160:163], v[168:171], v[122:125]
	v_mfma_f32_16x16x32_bf16 v[118:121], v[148:151], v[176:179], v[118:121]
	v_mfma_f32_16x16x32_bf16 v[114:117], v[160:163], v[176:179], v[114:117]
	v_mfma_f32_16x16x32_bf16 v[102:105], v[148:151], v[196:199], v[102:105]
	v_mfma_f32_16x16x32_bf16 v[98:101], v[160:163], v[196:199], v[98:101]
	v_mfma_f32_16x16x32_bf16 v[86:89], v[148:151], v[204:207], v[86:89]
	v_mfma_f32_16x16x32_bf16 v[82:85], v[160:163], v[204:207], v[82:85]
	s_barrier
	s_add_i32 s58, 0, 0x14000
	v_add_u32_e32 v152, s58, v139
	s_add_i32 s56, s56, s28
	ds_read_b128 v[208:211], v152
	ds_read_b128 v[224:227], v152 offset:1024
	ds_read_b128 v[228:231], v152 offset:2048
	ds_read_b128 v[232:235], v152 offset:3072
	v_lshl_add_u64 v[152:153], s[20:21], 0, v[134:135]
	s_mov_b32 m0, s56
	v_lshl_add_u64 v[212:213], s[20:21], 0, v[130:131]
	global_load_lds_dwordx4 v[152:153], off
	s_add_i32 m0, s56, 0x2000
	s_nop 0
	global_load_lds_dwordx4 v[212:213], off
	s_mov_b32 m0, s29
	v_lshl_add_u64 v[236:237], s[22:23], 0, v[136:137]
	s_barrier
	s_waitcnt lgkmcnt(0)
	v_mfma_f32_16x16x32_bf16 v[110:113], v[208:211], v[164:167], v[110:113]
	v_mfma_f32_16x16x32_bf16 v[106:109], v[228:231], v[164:167], v[106:109]
	v_mfma_f32_16x16x32_bf16 v[94:97], v[208:211], v[172:175], v[94:97]
	v_mfma_f32_16x16x32_bf16 v[90:93], v[228:231], v[172:175], v[90:93]
	v_mfma_f32_16x16x32_bf16 v[78:81], v[208:211], v[192:195], v[78:81]
	v_mfma_f32_16x16x32_bf16 v[74:77], v[228:231], v[192:195], v[74:77]
	v_mfma_f32_16x16x32_bf16 v[70:73], v[208:211], v[200:203], v[70:73]
	v_mfma_f32_16x16x32_bf16 v[66:69], v[228:231], v[200:203], v[66:69]
	v_mfma_f32_16x16x32_bf16 v[110:113], v[224:227], v[168:171], v[110:113]
	v_mfma_f32_16x16x32_bf16 v[106:109], v[232:235], v[168:171], v[106:109]
	v_mfma_f32_16x16x32_bf16 v[94:97], v[224:227], v[176:179], v[94:97]
	v_mfma_f32_16x16x32_bf16 v[90:93], v[232:235], v[176:179], v[90:93]
	v_mfma_f32_16x16x32_bf16 v[78:81], v[224:227], v[196:199], v[78:81]
	v_mfma_f32_16x16x32_bf16 v[74:77], v[232:235], v[196:199], v[74:77]
	v_mfma_f32_16x16x32_bf16 v[70:73], v[224:227], v[204:207], v[70:73]
	v_mfma_f32_16x16x32_bf16 v[66:69], v[232:235], v[204:207], v[66:69]
	s_barrier
	ds_read_b128 v[164:167], v154 offset:16384
	ds_read_b128 v[168:171], v154 offset:17408
	ds_read_b128 v[172:175], v154 offset:18432
	ds_read_b128 v[176:179], v154 offset:19456
	ds_read_b128 v[192:195], v154 offset:20480
	ds_read_b128 v[196:199], v154 offset:21504
	ds_read_b128 v[200:203], v154 offset:22528
	ds_read_b128 v[204:207], v154 offset:23552
	global_load_lds_dwordx4 v[236:237], off
	v_lshl_add_u64 v[238:239], s[22:23], 0, v[132:133]
	s_mov_b32 m0, s44
	s_nop 0
	global_load_lds_dwordx4 v[238:239], off
	s_waitcnt vmcnt(10)
	s_barrier
	s_waitcnt lgkmcnt(0)
	v_mfma_f32_16x16x32_bf16 v[62:65], v[144:147], v[164:167], v[62:65]
	v_mfma_f32_16x16x32_bf16 v[58:61], v[156:159], v[164:167], v[58:61]
	v_mfma_f32_16x16x32_bf16 v[54:57], v[144:147], v[172:175], v[54:57]
	v_mfma_f32_16x16x32_bf16 v[50:53], v[156:159], v[172:175], v[50:53]
	v_mfma_f32_16x16x32_bf16 v[38:41], v[144:147], v[192:195], v[38:41]
	v_mfma_f32_16x16x32_bf16 v[34:37], v[156:159], v[192:195], v[34:37]
	v_mfma_f32_16x16x32_bf16 v[22:25], v[144:147], v[200:203], v[22:25]
	v_mfma_f32_16x16x32_bf16 v[18:21], v[156:159], v[200:203], v[18:21]
	v_mfma_f32_16x16x32_bf16 v[62:65], v[148:151], v[168:171], v[62:65]
	v_mfma_f32_16x16x32_bf16 v[58:61], v[160:163], v[168:171], v[58:61]
	v_mfma_f32_16x16x32_bf16 v[54:57], v[148:151], v[176:179], v[54:57]
	v_mfma_f32_16x16x32_bf16 v[50:53], v[160:163], v[176:179], v[50:53]
	v_mfma_f32_16x16x32_bf16 v[38:41], v[148:151], v[196:199], v[38:41]
	v_mfma_f32_16x16x32_bf16 v[34:37], v[160:163], v[196:199], v[34:37]
	v_mfma_f32_16x16x32_bf16 v[22:25], v[148:151], v[204:207], v[22:25]
	v_mfma_f32_16x16x32_bf16 v[18:21], v[160:163], v[204:207], v[18:21]
	s_barrier
	s_add_u32 s56, s20, 0x80000
	s_addc_u32 s57, s21, 0
	s_add_i32 s58, s58, s28
	v_lshl_add_u64 v[144:145], s[56:57], 0, v[134:135]
	s_mov_b32 m0, s58
	s_nop 0
	global_load_lds_dwordx4 v[144:145], off
	v_lshl_add_u64 v[144:145], s[56:57], 0, v[130:131]
	s_add_i32 m0, s58, 0x2000
	s_nop 0
	global_load_lds_dwordx4 v[144:145], off
	v_add_u32_e32 v155, 0x18000, v139
	ds_read_b128 v[144:147], v155
	ds_read_b128 v[148:151], v155 offset:1024
	ds_read_b128 v[156:159], v155 offset:2048
	ds_read_b128 v[160:163], v155 offset:3072
	s_add_i32 s56, 0, 0x18000
	s_waitcnt vmcnt(6)
	s_barrier
	v_mfma_f32_16x16x32_bf16 v[46:49], v[208:211], v[164:167], v[46:49]
	v_mfma_f32_16x16x32_bf16 v[42:45], v[228:231], v[164:167], v[42:45]
	v_mfma_f32_16x16x32_bf16 v[30:33], v[208:211], v[172:175], v[30:33]
	v_mfma_f32_16x16x32_bf16 v[26:29], v[228:231], v[172:175], v[26:29]
	v_mfma_f32_16x16x32_bf16 v[14:17], v[208:211], v[192:195], v[14:17]
	v_mfma_f32_16x16x32_bf16 v[10:13], v[228:231], v[192:195], v[10:13]
	v_mfma_f32_16x16x32_bf16 v[6:9], v[208:211], v[200:203], v[6:9]
	v_mfma_f32_16x16x32_bf16 v[2:5], v[228:231], v[200:203], v[2:5]
	v_mfma_f32_16x16x32_bf16 v[46:49], v[224:227], v[168:171], v[46:49]
	v_mfma_f32_16x16x32_bf16 v[42:45], v[232:235], v[168:171], v[42:45]
	v_mfma_f32_16x16x32_bf16 v[30:33], v[224:227], v[176:179], v[30:33]
	v_mfma_f32_16x16x32_bf16 v[26:29], v[232:235], v[176:179], v[26:29]
	v_mfma_f32_16x16x32_bf16 v[14:17], v[224:227], v[196:199], v[14:17]
	v_mfma_f32_16x16x32_bf16 v[10:13], v[232:235], v[196:199], v[10:13]
	v_mfma_f32_16x16x32_bf16 v[6:9], v[224:227], v[204:207], v[6:9]
	v_mfma_f32_16x16x32_bf16 v[2:5], v[232:235], v[204:207], v[2:5]
	s_barrier
	s_add_u32 s22, s22, 0x80000
	s_addc_u32 s23, s23, 0
	s_mov_b32 m0, s45
	v_lshl_add_u64 v[208:209], s[22:23], 0, v[136:137]
	ds_read_b128 v[164:167], v154 offset:32768
	ds_read_b128 v[168:171], v154 offset:33792
	ds_read_b128 v[172:175], v154 offset:34816
	ds_read_b128 v[176:179], v154 offset:35840
	ds_read_b128 v[192:195], v154 offset:36864
	ds_read_b128 v[196:199], v154 offset:37888
	ds_read_b128 v[200:203], v154 offset:38912
	ds_read_b128 v[204:207], v154 offset:39936
	global_load_lds_dwordx4 v[208:209], off
	v_lshl_add_u64 v[208:209], s[22:23], 0, v[132:133]
	s_mov_b32 m0, s46
	s_nop 0
	global_load_lds_dwordx4 v[208:209], off
	s_waitcnt lgkmcnt(8)
	s_barrier
	s_waitcnt lgkmcnt(0)
	v_mfma_f32_16x16x32_bf16 v[126:129], v[144:147], v[164:167], v[126:129]
	v_mfma_f32_16x16x32_bf16 v[122:125], v[156:159], v[164:167], v[122:125]
	v_mfma_f32_16x16x32_bf16 v[118:121], v[144:147], v[172:175], v[118:121]
	v_mfma_f32_16x16x32_bf16 v[114:117], v[156:159], v[172:175], v[114:117]
	v_mfma_f32_16x16x32_bf16 v[102:105], v[144:147], v[192:195], v[102:105]
	v_mfma_f32_16x16x32_bf16 v[98:101], v[156:159], v[192:195], v[98:101]
	v_mfma_f32_16x16x32_bf16 v[86:89], v[144:147], v[200:203], v[86:89]
	v_mfma_f32_16x16x32_bf16 v[82:85], v[156:159], v[200:203], v[82:85]
	v_mfma_f32_16x16x32_bf16 v[126:129], v[148:151], v[168:171], v[126:129]
	v_mfma_f32_16x16x32_bf16 v[122:125], v[160:163], v[168:171], v[122:125]
	v_mfma_f32_16x16x32_bf16 v[118:121], v[148:151], v[176:179], v[118:121]
	v_mfma_f32_16x16x32_bf16 v[114:117], v[160:163], v[176:179], v[114:117]
	v_mfma_f32_16x16x32_bf16 v[102:105], v[148:151], v[196:199], v[102:105]
	v_mfma_f32_16x16x32_bf16 v[98:101], v[160:163], v[196:199], v[98:101]
	v_mfma_f32_16x16x32_bf16 v[86:89], v[148:151], v[204:207], v[86:89]
	v_mfma_f32_16x16x32_bf16 v[82:85], v[160:163], v[204:207], v[82:85]
	s_barrier
	s_add_i32 s22, 0, 0x1c000
	s_add_i32 s23, s56, s28
	v_add_u32_e32 v155, s22, v139
	v_lshl_add_u64 v[152:153], v[152:153], 0, s[78:79]
	s_mov_b32 m0, s23
	ds_read_b128 v[208:211], v155
	ds_read_b128 v[224:227], v155 offset:1024
	ds_read_b128 v[228:231], v155 offset:2048
	ds_read_b128 v[232:235], v155 offset:3072
	global_load_lds_dwordx4 v[152:153], off
	v_lshl_add_u64 v[152:153], v[212:213], 0, s[78:79]
	s_add_i32 m0, s23, 0x2000
	s_nop 0
	global_load_lds_dwordx4 v[152:153], off
	s_mov_b32 m0, s47
	v_lshl_add_u64 v[152:153], v[236:237], 0, s[78:79]
	s_barrier
	s_waitcnt lgkmcnt(0)
	v_mfma_f32_16x16x32_bf16 v[110:113], v[208:211], v[164:167], v[110:113]
	v_mfma_f32_16x16x32_bf16 v[106:109], v[228:231], v[164:167], v[106:109]
	v_mfma_f32_16x16x32_bf16 v[94:97], v[208:211], v[172:175], v[94:97]
	v_mfma_f32_16x16x32_bf16 v[90:93], v[228:231], v[172:175], v[90:93]
	v_mfma_f32_16x16x32_bf16 v[78:81], v[208:211], v[192:195], v[78:81]
	v_mfma_f32_16x16x32_bf16 v[74:77], v[228:231], v[192:195], v[74:77]
	v_mfma_f32_16x16x32_bf16 v[70:73], v[208:211], v[200:203], v[70:73]
	v_mfma_f32_16x16x32_bf16 v[66:69], v[228:231], v[200:203], v[66:69]
	v_mfma_f32_16x16x32_bf16 v[110:113], v[224:227], v[168:171], v[110:113]
	v_mfma_f32_16x16x32_bf16 v[106:109], v[232:235], v[168:171], v[106:109]
	v_mfma_f32_16x16x32_bf16 v[94:97], v[224:227], v[176:179], v[94:97]
	v_mfma_f32_16x16x32_bf16 v[90:93], v[232:235], v[176:179], v[90:93]
	v_mfma_f32_16x16x32_bf16 v[78:81], v[224:227], v[196:199], v[78:81]
	v_mfma_f32_16x16x32_bf16 v[74:77], v[232:235], v[196:199], v[74:77]
	v_mfma_f32_16x16x32_bf16 v[70:73], v[224:227], v[204:207], v[70:73]
	v_mfma_f32_16x16x32_bf16 v[66:69], v[232:235], v[204:207], v[66:69]
	s_barrier
	ds_read_b128 v[164:167], v154 offset:49152
	ds_read_b128 v[168:171], v154 offset:50176
	ds_read_b128 v[172:175], v154 offset:51200
	ds_read_b128 v[176:179], v154 offset:52224
	ds_read_b128 v[192:195], v154 offset:53248
	ds_read_b128 v[196:199], v154 offset:54272
	ds_read_b128 v[200:203], v154 offset:55296
	ds_read_b128 v[204:207], v154 offset:56320
	global_load_lds_dwordx4 v[152:153], off
	v_lshl_add_u64 v[152:153], v[238:239], 0, s[78:79]
	s_mov_b32 m0, s48
	s_nop 0
	global_load_lds_dwordx4 v[152:153], off
	s_waitcnt vmcnt(10)
	s_barrier
	s_waitcnt lgkmcnt(0)
	v_mfma_f32_16x16x32_bf16 v[62:65], v[144:147], v[164:167], v[62:65]
	v_mfma_f32_16x16x32_bf16 v[58:61], v[156:159], v[164:167], v[58:61]
	v_mfma_f32_16x16x32_bf16 v[54:57], v[144:147], v[172:175], v[54:57]
	v_mfma_f32_16x16x32_bf16 v[50:53], v[156:159], v[172:175], v[50:53]
	v_mfma_f32_16x16x32_bf16 v[38:41], v[144:147], v[192:195], v[38:41]
	v_mfma_f32_16x16x32_bf16 v[34:37], v[156:159], v[192:195], v[34:37]
	v_mfma_f32_16x16x32_bf16 v[22:25], v[144:147], v[200:203], v[22:25]
	v_mfma_f32_16x16x32_bf16 v[18:21], v[156:159], v[200:203], v[18:21]
	v_mfma_f32_16x16x32_bf16 v[62:65], v[148:151], v[168:171], v[62:65]
	v_mfma_f32_16x16x32_bf16 v[58:61], v[160:163], v[168:171], v[58:61]
	v_mfma_f32_16x16x32_bf16 v[54:57], v[148:151], v[176:179], v[54:57]
	v_mfma_f32_16x16x32_bf16 v[50:53], v[160:163], v[176:179], v[50:53]
	v_mfma_f32_16x16x32_bf16 v[38:41], v[148:151], v[196:199], v[38:41]
	v_mfma_f32_16x16x32_bf16 v[34:37], v[160:163], v[196:199], v[34:37]
	v_mfma_f32_16x16x32_bf16 v[22:25], v[148:151], v[204:207], v[22:25]
	v_mfma_f32_16x16x32_bf16 v[18:21], v[160:163], v[204:207], v[18:21]
	s_barrier
	s_add_u32 s20, s20, 0x80080
	s_addc_u32 s21, s21, 0
	s_add_i32 s22, s22, s28
	v_lshl_add_u64 v[144:145], s[20:21], 0, v[134:135]
	s_mov_b32 m0, s22
	s_nop 0
	global_load_lds_dwordx4 v[144:145], off
	v_lshl_add_u64 v[144:145], s[20:21], 0, v[130:131]
	s_add_i32 m0, s22, 0x2000
	s_nop 0
	global_load_lds_dwordx4 v[144:145], off
	v_add_u32_e32 v152, 0x10000, v139
	ds_read_b128 v[144:147], v152
	ds_read_b128 v[148:151], v152 offset:1024
	ds_read_b128 v[156:159], v152 offset:2048
	ds_read_b128 v[160:163], v152 offset:3072
	s_add_i32 s55, s55, 2
	s_add_u32 s18, s18, 0x100
	s_addc_u32 s19, s19, 0
	s_add_u32 s53, s53, 0x100
	s_addc_u32 s54, s54, 0
	s_cmp_gt_u32 s55, 29
	s_waitcnt vmcnt(6)
	s_barrier
	v_mfma_f32_16x16x32_bf16 v[46:49], v[208:211], v[164:167], v[46:49]
	v_mfma_f32_16x16x32_bf16 v[42:45], v[228:231], v[164:167], v[42:45]
	v_mfma_f32_16x16x32_bf16 v[30:33], v[208:211], v[172:175], v[30:33]
	v_mfma_f32_16x16x32_bf16 v[26:29], v[228:231], v[172:175], v[26:29]
	v_mfma_f32_16x16x32_bf16 v[14:17], v[208:211], v[192:195], v[14:17]
	v_mfma_f32_16x16x32_bf16 v[10:13], v[228:231], v[192:195], v[10:13]
	v_mfma_f32_16x16x32_bf16 v[6:9], v[208:211], v[200:203], v[6:9]
	v_mfma_f32_16x16x32_bf16 v[2:5], v[228:231], v[200:203], v[2:5]
	v_mfma_f32_16x16x32_bf16 v[46:49], v[224:227], v[168:171], v[46:49]
	v_mfma_f32_16x16x32_bf16 v[42:45], v[232:235], v[168:171], v[42:45]
	v_mfma_f32_16x16x32_bf16 v[30:33], v[224:227], v[176:179], v[30:33]
	v_mfma_f32_16x16x32_bf16 v[26:29], v[232:235], v[176:179], v[26:29]
	v_mfma_f32_16x16x32_bf16 v[14:17], v[224:227], v[196:199], v[14:17]
	v_mfma_f32_16x16x32_bf16 v[10:13], v[232:235], v[196:199], v[10:13]
	v_mfma_f32_16x16x32_bf16 v[6:9], v[224:227], v[204:207], v[6:9]
	v_mfma_f32_16x16x32_bf16 v[2:5], v[232:235], v[204:207], v[2:5]
	s_barrier
	s_cbranch_scc0 .LBB0_526
	s_waitcnt lgkmcnt(0)
	v_lshl_add_u32 v152, s36, 8, v1
	v_or_b32_e32 v150, 16, v152
	v_or_b32_e32 v148, 32, v152
	v_or_b32_e32 v146, 48, v152
	s_mov_b64 s[18:19], -1
	s_cmp_lt_i32 s50, 8
	v_ashrrev_i32_e32 v153, 31, v152
	v_lshlrev_b32_e32 v144, 1, v138
	v_ashrrev_i32_e32 v151, 31, v150
	v_ashrrev_i32_e32 v149, 31, v148
	v_ashrrev_i32_e32 v147, 31, v146
	s_cbranch_scc1 .LBB0_529
	s_lshl_b32 s18, s50, 7
	s_add_i32 s36, s18, 0xfffffc00
	v_lshlrev_b64 v[156:157], 12, v[152:153]
	v_lshl_add_u64 v[156:157], s[72:73], 0, v[156:157]
	s_lshl_b64 s[18:19], s[36:37], 1
	v_lshl_add_u64 v[156:157], v[156:157], 0, s[18:19]
	v_mov_b32_e32 v145, v0
	v_lshl_add_u64 v[160:161], v[156:157], 0, v[144:145]
	v_pk_mul_f32 v[158:159], v[128:129], v[112:113]
	v_pk_mul_f32 v[156:157], v[126:127], v[110:111]
	v_pk_mul_f32 v[162:163], v[124:125], v[108:109]
	v_pk_mul_f32 v[164:165], v[122:123], v[106:107]
	v_cvt_pk_bf16_f32 v156, v156, v157
	v_cvt_pk_bf16_f32 v157, v158, v159
	v_cvt_pk_bf16_f32 v158, v164, v165
	v_cvt_pk_bf16_f32 v159, v162, v163
	global_store_dwordx4 v[160:161], v[156:159], off
	v_pk_mul_f32 v[164:165], v[116:117], v[92:93]
	v_pk_mul_f32 v[166:167], v[114:115], v[90:91]
	v_lshlrev_b64 v[156:157], 12, v[150:151]
	v_lshl_add_u64 v[156:157], s[72:73], 0, v[156:157]
	v_lshl_add_u64 v[156:157], v[156:157], 0, s[18:19]
	v_lshl_add_u64 v[162:163], v[156:157], 0, v[144:145]
	v_pk_mul_f32 v[158:159], v[120:121], v[96:97]
	v_pk_mul_f32 v[156:157], v[118:119], v[94:95]
	s_nop 0
	v_cvt_pk_bf16_f32 v156, v156, v157
	v_cvt_pk_bf16_f32 v157, v158, v159
	v_cvt_pk_bf16_f32 v158, v166, v167
	v_cvt_pk_bf16_f32 v159, v164, v165
	global_store_dwordx4 v[162:163], v[156:159], off
	v_pk_mul_f32 v[164:165], v[100:101], v[76:77]
	v_pk_mul_f32 v[166:167], v[98:99], v[74:75]
	v_lshlrev_b64 v[156:157], 12, v[148:149]
	v_lshl_add_u64 v[156:157], s[72:73], 0, v[156:157]
	v_lshl_add_u64 v[156:157], v[156:157], 0, s[18:19]
	v_lshl_add_u64 v[162:163], v[156:157], 0, v[144:145]
	v_pk_mul_f32 v[158:159], v[104:105], v[80:81]
	v_pk_mul_f32 v[156:157], v[102:103], v[78:79]
	s_nop 0
	v_cvt_pk_bf16_f32 v156, v156, v157
	v_cvt_pk_bf16_f32 v157, v158, v159
	v_cvt_pk_bf16_f32 v158, v166, v167
	v_cvt_pk_bf16_f32 v159, v164, v165
	global_store_dwordx4 v[162:163], v[156:159], off
	v_pk_mul_f32 v[164:165], v[84:85], v[68:69]
	v_pk_mul_f32 v[166:167], v[82:83], v[66:67]
	v_lshlrev_b64 v[156:157], 12, v[146:147]
	v_lshl_add_u64 v[156:157], s[72:73], 0, v[156:157]
	v_lshl_add_u64 v[156:157], v[156:157], 0, s[18:19]
	v_lshl_add_u64 v[162:163], v[156:157], 0, v[144:145]
	v_pk_mul_f32 v[158:159], v[88:89], v[72:73]
	v_pk_mul_f32 v[156:157], v[86:87], v[70:71]
	s_mov_b32 s18, 0x80000
	v_cvt_pk_bf16_f32 v156, v156, v157
	v_cvt_pk_bf16_f32 v157, v158, v159
	v_cvt_pk_bf16_f32 v158, v166, v167
	v_cvt_pk_bf16_f32 v159, v164, v165
	global_store_dwordx4 v[162:163], v[156:159], off
	v_pk_mul_f32 v[162:163], v[60:61], v[44:45]
	v_pk_mul_f32 v[164:165], v[58:59], v[42:43]
	v_pk_mul_f32 v[158:159], v[64:65], v[48:49]
	v_pk_mul_f32 v[156:157], v[62:63], v[46:47]
	s_nop 0
	v_cvt_pk_bf16_f32 v156, v156, v157
	v_cvt_pk_bf16_f32 v157, v158, v159
	v_cvt_pk_bf16_f32 v159, v162, v163
	v_add_co_u32_e32 v162, vcc, s18, v160
	v_cvt_pk_bf16_f32 v158, v164, v165
	s_nop 0
	v_addc_co_u32_e32 v163, vcc, 0, v161, vcc
	global_store_dwordx4 v[162:163], v[156:159], off
	v_pk_mul_f32 v[162:163], v[52:53], v[28:29]
	s_mov_b32 s18, 0x90000
	v_pk_mul_f32 v[158:159], v[56:57], v[32:33]
	v_pk_mul_f32 v[156:157], v[54:55], v[30:31]
	v_pk_mul_f32 v[164:165], v[50:51], v[26:27]
	v_cvt_pk_bf16_f32 v156, v156, v157
	v_cvt_pk_bf16_f32 v157, v158, v159
	v_cvt_pk_bf16_f32 v159, v162, v163
	v_add_co_u32_e32 v162, vcc, s18, v160
	v_cvt_pk_bf16_f32 v158, v164, v165
	s_nop 0
	v_addc_co_u32_e32 v163, vcc, 0, v161, vcc
	global_store_dwordx4 v[162:163], v[156:159], off
	v_pk_mul_f32 v[162:163], v[36:37], v[12:13]
	s_mov_b32 s18, 0xa0000
	v_pk_mul_f32 v[158:159], v[40:41], v[16:17]
	v_pk_mul_f32 v[156:157], v[38:39], v[14:15]
	v_pk_mul_f32 v[164:165], v[34:35], v[10:11]
	v_cvt_pk_bf16_f32 v156, v156, v157
	v_cvt_pk_bf16_f32 v157, v158, v159
	v_cvt_pk_bf16_f32 v159, v162, v163
	v_add_co_u32_e32 v162, vcc, s18, v160
	v_cvt_pk_bf16_f32 v158, v164, v165
	s_nop 0
	v_addc_co_u32_e32 v163, vcc, 0, v161, vcc
	global_store_dwordx4 v[162:163], v[156:159], off
	v_pk_mul_f32 v[162:163], v[20:21], v[4:5]
	v_pk_mul_f32 v[164:165], v[18:19], v[2:3]
	v_pk_mul_f32 v[158:159], v[24:25], v[8:9]
	v_pk_mul_f32 v[156:157], v[22:23], v[6:7]
	v_add_co_u32_e32 v160, vcc, 0xb0000, v160
	v_cvt_pk_bf16_f32 v156, v156, v157
	v_cvt_pk_bf16_f32 v157, v158, v159
	v_cvt_pk_bf16_f32 v158, v164, v165
	v_cvt_pk_bf16_f32 v159, v162, v163
	v_addc_co_u32_e32 v161, vcc, 0, v161, vcc
	s_mov_b64 s[18:19], 0
	global_store_dwordx4 v[160:161], v[156:159], off

.LBB0_649:
	s_add_u32 s18, s38, vcc_lo
	s_addc_u32 s19, s39, vcc_hi
	s_add_u32 s18, s18, 0x100
	s_addc_u32 s19, s19, 0
	s_add_u32 s57, s50, vcc_lo
	s_addc_u32 s58, s51, vcc_hi
	s_add_i32 s59, 0, 0x10000
	s_cmpk_eq_i32 vcc_lo, 0xf00
	s_cselect_b32 s23, s52, s19
	s_cselect_b32 s22, s53, s18
	s_cselect_b32 s19, s54, s58
	s_cselect_b32 s18, s55, s57
	v_lshl_add_u64 v[162:163], v[142:143], 0, vcc
	s_add_i32 m0, s28, 0xc000
	ds_read_b128 v[170:173], v148
	ds_read_b128 v[174:177], v148 offset:1024
	ds_read_b128 v[192:195], v148 offset:2048
	ds_read_b128 v[196:199], v148 offset:3072
	ds_read_b128 v[200:203], v148 offset:4096
	ds_read_b128 v[204:207], v148 offset:5120
	ds_read_b128 v[208:211], v148 offset:6144
	ds_read_b128 v[224:227], v148 offset:7168
	global_load_lds_dwordx4 v[162:163], off
	v_lshl_add_u64 v[162:163], v[144:145], 0, vcc
	s_add_i32 m0, s28, 0xe000
	s_nop 0
	global_load_lds_dwordx4 v[162:163], off
	s_waitcnt lgkmcnt(8)
	s_barrier
	s_waitcnt lgkmcnt(0)
	v_mfma_f32_16x16x32_bf16 v[90:93], v[150:153], v[170:173], v[90:93]
	v_mfma_f32_16x16x32_bf16 v[94:97], v[158:161], v[170:173], v[94:97]
	v_mfma_f32_16x16x32_bf16 v[102:105], v[150:153], v[192:195], v[102:105]
	v_mfma_f32_16x16x32_bf16 v[106:109], v[158:161], v[192:195], v[106:109]
	v_mfma_f32_16x16x32_bf16 v[114:117], v[150:153], v[200:203], v[114:117]
	v_mfma_f32_16x16x32_bf16 v[118:121], v[158:161], v[200:203], v[118:121]
	v_mfma_f32_16x16x32_bf16 v[122:125], v[150:153], v[208:211], v[122:125]
	v_mfma_f32_16x16x32_bf16 v[126:129], v[158:161], v[208:211], v[126:129]
	v_mfma_f32_16x16x32_bf16 v[90:93], v[154:157], v[174:177], v[90:93]
	v_mfma_f32_16x16x32_bf16 v[94:97], v[166:169], v[174:177], v[94:97]
	v_mfma_f32_16x16x32_bf16 v[102:105], v[154:157], v[196:199], v[102:105]
	v_mfma_f32_16x16x32_bf16 v[106:109], v[166:169], v[196:199], v[106:109]
	v_mfma_f32_16x16x32_bf16 v[114:117], v[154:157], v[204:207], v[114:117]
	v_mfma_f32_16x16x32_bf16 v[118:121], v[166:169], v[204:207], v[118:121]
	v_mfma_f32_16x16x32_bf16 v[122:125], v[154:157], v[224:227], v[122:125]
	v_mfma_f32_16x16x32_bf16 v[126:129], v[166:169], v[224:227], v[126:129]
	s_barrier
	s_add_i32 s57, 0, 0x14000
	s_add_i32 s58, s59, s85
	v_add_u32_e32 v149, s57, v147
	v_lshl_add_u64 v[162:163], s[18:19], 0, v[134:135]
	s_mov_b32 m0, s58
	ds_read_b128 v[228:231], v149
	ds_read_b128 v[232:235], v149 offset:1024
	ds_read_b128 v[236:239], v149 offset:2048
	ds_read_b128 v[240:243], v149 offset:3072
	global_load_lds_dwordx4 v[162:163], off
	v_lshl_add_u64 v[178:179], s[18:19], 0, v[130:131]
	s_add_i32 m0, s58, 0x2000
	s_nop 0
	global_load_lds_dwordx4 v[178:179], off
	s_mov_b32 m0, s28
	v_lshl_add_u64 v[212:213], s[22:23], 0, v[136:137]
	s_barrier
	s_waitcnt lgkmcnt(0)
	v_mfma_f32_16x16x32_bf16 v[10:13], v[228:231], v[170:173], v[10:13]
	v_mfma_f32_16x16x32_bf16 v[14:17], v[236:239], v[170:173], v[14:17]
	v_mfma_f32_16x16x32_bf16 v[26:29], v[228:231], v[192:195], v[26:29]
	v_mfma_f32_16x16x32_bf16 v[38:41], v[236:239], v[192:195], v[38:41]
	v_mfma_f32_16x16x32_bf16 v[58:61], v[228:231], v[200:203], v[58:61]
	v_mfma_f32_16x16x32_bf16 v[62:65], v[236:239], v[200:203], v[62:65]
	v_mfma_f32_16x16x32_bf16 v[74:77], v[228:231], v[208:211], v[74:77]
	v_mfma_f32_16x16x32_bf16 v[78:81], v[236:239], v[208:211], v[78:81]
	v_mfma_f32_16x16x32_bf16 v[10:13], v[232:235], v[174:177], v[10:13]
	v_mfma_f32_16x16x32_bf16 v[14:17], v[240:243], v[174:177], v[14:17]
	v_mfma_f32_16x16x32_bf16 v[26:29], v[232:235], v[196:199], v[26:29]
	v_mfma_f32_16x16x32_bf16 v[38:41], v[240:243], v[196:199], v[38:41]
	v_mfma_f32_16x16x32_bf16 v[58:61], v[232:235], v[204:207], v[58:61]
	v_mfma_f32_16x16x32_bf16 v[62:65], v[240:243], v[204:207], v[62:65]
	v_mfma_f32_16x16x32_bf16 v[74:77], v[232:235], v[224:227], v[74:77]
	v_mfma_f32_16x16x32_bf16 v[78:81], v[240:243], v[224:227], v[78:81]
	s_barrier
	ds_read_b128 v[170:173], v148 offset:16384
	ds_read_b128 v[174:177], v148 offset:17408
	ds_read_b128 v[192:195], v148 offset:18432
	ds_read_b128 v[196:199], v148 offset:19456
	ds_read_b128 v[200:203], v148 offset:20480
	ds_read_b128 v[204:207], v148 offset:21504
	ds_read_b128 v[208:211], v148 offset:22528
	ds_read_b128 v[224:227], v148 offset:23552
	global_load_lds_dwordx4 v[212:213], off
	v_lshl_add_u64 v[244:245], s[22:23], 0, v[132:133]
	s_mov_b32 m0, s29
	s_nop 0
	global_load_lds_dwordx4 v[244:245], off
	s_waitcnt vmcnt(10)
	s_barrier
	s_waitcnt lgkmcnt(0)
	v_mfma_f32_16x16x32_bf16 v[110:113], v[150:153], v[170:173], v[110:113]
	v_mfma_f32_16x16x32_bf16 v[98:101], v[158:161], v[170:173], v[98:101]
	v_mfma_f32_16x16x32_bf16 v[82:85], v[150:153], v[192:195], v[82:85]
	v_mfma_f32_16x16x32_bf16 v[66:69], v[158:161], v[192:195], v[66:69]
	v_mfma_f32_16x16x32_bf16 v[50:53], v[150:153], v[200:203], v[50:53]
	v_mfma_f32_16x16x32_bf16 v[42:45], v[158:161], v[200:203], v[42:45]
	v_mfma_f32_16x16x32_bf16 v[30:33], v[150:153], v[208:211], v[30:33]
	v_mfma_f32_16x16x32_bf16 v[18:21], v[158:161], v[208:211], v[18:21]
	v_mfma_f32_16x16x32_bf16 v[110:113], v[154:157], v[174:177], v[110:113]
	v_mfma_f32_16x16x32_bf16 v[98:101], v[166:169], v[174:177], v[98:101]
	v_mfma_f32_16x16x32_bf16 v[82:85], v[154:157], v[196:199], v[82:85]
	v_mfma_f32_16x16x32_bf16 v[66:69], v[166:169], v[196:199], v[66:69]
	v_mfma_f32_16x16x32_bf16 v[50:53], v[154:157], v[204:207], v[50:53]
	v_mfma_f32_16x16x32_bf16 v[42:45], v[166:169], v[204:207], v[42:45]
	v_mfma_f32_16x16x32_bf16 v[30:33], v[154:157], v[224:227], v[30:33]
	v_mfma_f32_16x16x32_bf16 v[18:21], v[166:169], v[224:227], v[18:21]
	s_barrier
	s_add_u32 s58, s18, 0x80000
	s_addc_u32 s59, s19, 0
	s_add_i32 s57, s57, s85
	v_lshl_add_u64 v[150:151], s[58:59], 0, v[134:135]
	s_mov_b32 m0, s57
	s_nop 0
	global_load_lds_dwordx4 v[150:151], off
	v_lshl_add_u64 v[150:151], s[58:59], 0, v[130:131]
	s_add_i32 m0, s57, 0x2000
	s_nop 0
	global_load_lds_dwordx4 v[150:151], off
	v_add_u32_e32 v149, 0x18000, v147
	ds_read_b128 v[150:153], v149
	ds_read_b128 v[154:157], v149 offset:1024
	ds_read_b128 v[158:161], v149 offset:2048
	ds_read_b128 v[166:169], v149 offset:3072
	s_add_i32 s57, 0, 0x18000
	s_waitcnt vmcnt(6)
	s_barrier
	v_mfma_f32_16x16x32_bf16 v[86:89], v[228:231], v[170:173], v[86:89]
	v_mfma_f32_16x16x32_bf16 v[70:73], v[236:239], v[170:173], v[70:73]
	v_mfma_f32_16x16x32_bf16 v[54:57], v[228:231], v[192:195], v[54:57]
	v_mfma_f32_16x16x32_bf16 v[46:49], v[236:239], v[192:195], v[46:49]
	v_mfma_f32_16x16x32_bf16 v[34:37], v[228:231], v[200:203], v[34:37]
	v_mfma_f32_16x16x32_bf16 v[22:25], v[236:239], v[200:203], v[22:25]
	v_mfma_f32_16x16x32_bf16 v[6:9], v[228:231], v[208:211], v[6:9]
	v_mfma_f32_16x16x32_bf16 v[2:5], v[236:239], v[208:211], v[2:5]
	v_mfma_f32_16x16x32_bf16 v[86:89], v[232:235], v[174:177], v[86:89]
	v_mfma_f32_16x16x32_bf16 v[70:73], v[240:243], v[174:177], v[70:73]
	v_mfma_f32_16x16x32_bf16 v[54:57], v[232:235], v[196:199], v[54:57]
	v_mfma_f32_16x16x32_bf16 v[46:49], v[240:243], v[196:199], v[46:49]
	v_mfma_f32_16x16x32_bf16 v[34:37], v[232:235], v[204:207], v[34:37]
	v_mfma_f32_16x16x32_bf16 v[22:25], v[240:243], v[204:207], v[22:25]
	v_mfma_f32_16x16x32_bf16 v[6:9], v[232:235], v[224:227], v[6:9]
	v_mfma_f32_16x16x32_bf16 v[2:5], v[240:243], v[224:227], v[2:5]
	s_barrier
	s_add_u32 s22, s22, 0x80000
	s_addc_u32 s23, s23, 0
	s_mov_b32 m0, s97
	v_lshl_add_u64 v[228:229], s[22:23], 0, v[136:137]
	ds_read_b128 v[170:173], v148 offset:32768
	ds_read_b128 v[174:177], v148 offset:33792
	ds_read_b128 v[192:195], v148 offset:34816
	ds_read_b128 v[196:199], v148 offset:35840
	ds_read_b128 v[200:203], v148 offset:36864
	ds_read_b128 v[204:207], v148 offset:37888
	ds_read_b128 v[208:211], v148 offset:38912
	ds_read_b128 v[224:227], v148 offset:39936
	global_load_lds_dwordx4 v[228:229], off
	v_lshl_add_u64 v[228:229], s[22:23], 0, v[132:133]
	s_mov_b32 m0, s44
	s_nop 0
	global_load_lds_dwordx4 v[228:229], off
	s_waitcnt lgkmcnt(8)
	s_barrier
	s_waitcnt lgkmcnt(0)
	v_mfma_f32_16x16x32_bf16 v[90:93], v[150:153], v[170:173], v[90:93]
	v_mfma_f32_16x16x32_bf16 v[94:97], v[158:161], v[170:173], v[94:97]
	v_mfma_f32_16x16x32_bf16 v[102:105], v[150:153], v[192:195], v[102:105]
	v_mfma_f32_16x16x32_bf16 v[106:109], v[158:161], v[192:195], v[106:109]
	v_mfma_f32_16x16x32_bf16 v[114:117], v[150:153], v[200:203], v[114:117]
	v_mfma_f32_16x16x32_bf16 v[118:121], v[158:161], v[200:203], v[118:121]
	v_mfma_f32_16x16x32_bf16 v[122:125], v[150:153], v[208:211], v[122:125]
	v_mfma_f32_16x16x32_bf16 v[126:129], v[158:161], v[208:211], v[126:129]
	v_mfma_f32_16x16x32_bf16 v[90:93], v[154:157], v[174:177], v[90:93]
	v_mfma_f32_16x16x32_bf16 v[94:97], v[166:169], v[174:177], v[94:97]
	v_mfma_f32_16x16x32_bf16 v[102:105], v[154:157], v[196:199], v[102:105]
	v_mfma_f32_16x16x32_bf16 v[106:109], v[166:169], v[196:199], v[106:109]
	v_mfma_f32_16x16x32_bf16 v[114:117], v[154:157], v[204:207], v[114:117]
	v_mfma_f32_16x16x32_bf16 v[118:121], v[166:169], v[204:207], v[118:121]
	v_mfma_f32_16x16x32_bf16 v[122:125], v[154:157], v[224:227], v[122:125]
	v_mfma_f32_16x16x32_bf16 v[126:129], v[166:169], v[224:227], v[126:129]
	s_barrier
	s_add_i32 s22, 0, 0x1c000
	s_add_i32 s23, s57, s85
	v_add_u32_e32 v149, s22, v147
	v_lshl_add_u64 v[162:163], v[162:163], 0, s[78:79]
	s_mov_b32 m0, s23
	ds_read_b128 v[228:231], v149
	ds_read_b128 v[232:235], v149 offset:1024
	ds_read_b128 v[236:239], v149 offset:2048
	ds_read_b128 v[240:243], v149 offset:3072
	global_load_lds_dwordx4 v[162:163], off
	v_lshl_add_u64 v[162:163], v[178:179], 0, s[78:79]
	s_add_i32 m0, s23, 0x2000
	s_nop 0
	global_load_lds_dwordx4 v[162:163], off
	s_mov_b32 m0, s46
	v_lshl_add_u64 v[162:163], v[212:213], 0, s[78:79]
	s_barrier
	s_waitcnt lgkmcnt(0)
	v_mfma_f32_16x16x32_bf16 v[10:13], v[228:231], v[170:173], v[10:13]
	v_mfma_f32_16x16x32_bf16 v[14:17], v[236:239], v[170:173], v[14:17]
	v_mfma_f32_16x16x32_bf16 v[26:29], v[228:231], v[192:195], v[26:29]
	v_mfma_f32_16x16x32_bf16 v[38:41], v[236:239], v[192:195], v[38:41]
	v_mfma_f32_16x16x32_bf16 v[58:61], v[228:231], v[200:203], v[58:61]
	v_mfma_f32_16x16x32_bf16 v[62:65], v[236:239], v[200:203], v[62:65]
	v_mfma_f32_16x16x32_bf16 v[74:77], v[228:231], v[208:211], v[74:77]
	v_mfma_f32_16x16x32_bf16 v[78:81], v[236:239], v[208:211], v[78:81]
	v_mfma_f32_16x16x32_bf16 v[10:13], v[232:235], v[174:177], v[10:13]
	v_mfma_f32_16x16x32_bf16 v[14:17], v[240:243], v[174:177], v[14:17]
	v_mfma_f32_16x16x32_bf16 v[26:29], v[232:235], v[196:199], v[26:29]
	v_mfma_f32_16x16x32_bf16 v[38:41], v[240:243], v[196:199], v[38:41]
	v_mfma_f32_16x16x32_bf16 v[58:61], v[232:235], v[204:207], v[58:61]
	v_mfma_f32_16x16x32_bf16 v[62:65], v[240:243], v[204:207], v[62:65]
	v_mfma_f32_16x16x32_bf16 v[74:77], v[232:235], v[224:227], v[74:77]
	v_mfma_f32_16x16x32_bf16 v[78:81], v[240:243], v[224:227], v[78:81]
	s_barrier
	ds_read_b128 v[170:173], v148 offset:49152
	ds_read_b128 v[174:177], v148 offset:50176
	ds_read_b128 v[192:195], v148 offset:51200
	ds_read_b128 v[196:199], v148 offset:52224
	ds_read_b128 v[200:203], v148 offset:53248
	ds_read_b128 v[204:207], v148 offset:54272
	ds_read_b128 v[208:211], v148 offset:55296
	ds_read_b128 v[224:227], v148 offset:56320
	global_load_lds_dwordx4 v[162:163], off
	v_lshl_add_u64 v[162:163], v[244:245], 0, s[78:79]
	s_mov_b32 m0, s47
	s_nop 0
	global_load_lds_dwordx4 v[162:163], off
	s_waitcnt vmcnt(10)
	s_barrier
	s_waitcnt lgkmcnt(0)
	v_mfma_f32_16x16x32_bf16 v[110:113], v[150:153], v[170:173], v[110:113]
	v_mfma_f32_16x16x32_bf16 v[98:101], v[158:161], v[170:173], v[98:101]
	v_mfma_f32_16x16x32_bf16 v[82:85], v[150:153], v[192:195], v[82:85]
	v_mfma_f32_16x16x32_bf16 v[66:69], v[158:161], v[192:195], v[66:69]
	v_mfma_f32_16x16x32_bf16 v[50:53], v[150:153], v[200:203], v[50:53]
	v_mfma_f32_16x16x32_bf16 v[42:45], v[158:161], v[200:203], v[42:45]
	v_mfma_f32_16x16x32_bf16 v[30:33], v[150:153], v[208:211], v[30:33]
	v_mfma_f32_16x16x32_bf16 v[18:21], v[158:161], v[208:211], v[18:21]
	v_mfma_f32_16x16x32_bf16 v[110:113], v[154:157], v[174:177], v[110:113]
	v_mfma_f32_16x16x32_bf16 v[98:101], v[166:169], v[174:177], v[98:101]
	v_mfma_f32_16x16x32_bf16 v[82:85], v[154:157], v[196:199], v[82:85]
	v_mfma_f32_16x16x32_bf16 v[66:69], v[166:169], v[196:199], v[66:69]
	v_mfma_f32_16x16x32_bf16 v[50:53], v[154:157], v[204:207], v[50:53]
	v_mfma_f32_16x16x32_bf16 v[42:45], v[166:169], v[204:207], v[42:45]
	v_mfma_f32_16x16x32_bf16 v[30:33], v[154:157], v[224:227], v[30:33]
	v_mfma_f32_16x16x32_bf16 v[18:21], v[166:169], v[224:227], v[18:21]
	s_barrier
	s_add_u32 s18, s18, 0x80080
	s_addc_u32 s19, s19, 0
	s_add_i32 s22, s22, s85
	v_lshl_add_u64 v[150:151], s[18:19], 0, v[134:135]
	s_mov_b32 m0, s22
	s_nop 0
	global_load_lds_dwordx4 v[150:151], off
	v_lshl_add_u64 v[150:151], s[18:19], 0, v[130:131]
	s_add_i32 m0, s22, 0x2000
	s_nop 0
	global_load_lds_dwordx4 v[150:151], off
	v_add_u32_e32 v149, 0x10000, v147
	ds_read_b128 v[150:153], v149
	ds_read_b128 v[154:157], v149 offset:1024
	ds_read_b128 v[158:161], v149 offset:2048
	ds_read_b128 v[166:169], v149 offset:3072
	s_add_i32 s56, s56, 2
	s_add_u32 vcc_lo, vcc_lo, 0x100
	s_addc_u32 vcc_hi, vcc_hi, 0
	s_cmp_gt_u32 s56, 29
	s_waitcnt vmcnt(6)
	s_barrier
	v_mfma_f32_16x16x32_bf16 v[86:89], v[228:231], v[170:173], v[86:89]
	v_mfma_f32_16x16x32_bf16 v[70:73], v[236:239], v[170:173], v[70:73]
	v_mfma_f32_16x16x32_bf16 v[54:57], v[228:231], v[192:195], v[54:57]
	v_mfma_f32_16x16x32_bf16 v[46:49], v[236:239], v[192:195], v[46:49]
	v_mfma_f32_16x16x32_bf16 v[34:37], v[228:231], v[200:203], v[34:37]
	v_mfma_f32_16x16x32_bf16 v[22:25], v[236:239], v[200:203], v[22:25]
	v_mfma_f32_16x16x32_bf16 v[6:9], v[228:231], v[208:211], v[6:9]
	v_mfma_f32_16x16x32_bf16 v[2:5], v[236:239], v[208:211], v[2:5]
	v_mfma_f32_16x16x32_bf16 v[86:89], v[232:235], v[174:177], v[86:89]
	v_mfma_f32_16x16x32_bf16 v[70:73], v[240:243], v[174:177], v[70:73]
	v_mfma_f32_16x16x32_bf16 v[54:57], v[232:235], v[196:199], v[54:57]
	v_mfma_f32_16x16x32_bf16 v[46:49], v[240:243], v[196:199], v[46:49]
	v_mfma_f32_16x16x32_bf16 v[34:37], v[232:235], v[204:207], v[34:37]
	v_mfma_f32_16x16x32_bf16 v[22:25], v[240:243], v[204:207], v[22:25]
	v_mfma_f32_16x16x32_bf16 v[6:9], v[232:235], v[224:227], v[6:9]
	v_mfma_f32_16x16x32_bf16 v[2:5], v[240:243], v[224:227], v[2:5]
	s_barrier
	s_cbranch_scc0 .LBB0_649
	s_waitcnt lgkmcnt(0)
	s_add_u32 s18, s50, 0xffffff00
	s_addc_u32 s19, s51, -1
	s_andn2_b64 vcc, exec, s[42:43]
	s_cbranch_vccnz .LBB0_652
	v_mov_b32_e32 v2, 0
	s_mov_b32 s84, s80
	s_mov_b32 s25, s82
	s_mov_b64 s[38:39], s[20:21]
	s_mov_b32 s48, s49
	v_mov_b32_e32 v3, v2
	v_mov_b32_e32 v4, v2
	v_mov_b32_e32 v5, v2
	v_mov_b32_e32 v6, v2
	v_mov_b32_e32 v7, v2
	v_mov_b32_e32 v8, v2
	v_mov_b32_e32 v9, v2
	v_mov_b32_e32 v22, v2
	v_mov_b32_e32 v23, v2
	v_mov_b32_e32 v24, v2
	v_mov_b32_e32 v25, v2
	v_mov_b32_e32 v34, v2
	v_mov_b32_e32 v35, v2
	v_mov_b32_e32 v36, v2
	v_mov_b32_e32 v37, v2
	v_mov_b32_e32 v46, v2
	v_mov_b32_e32 v47, v2
	v_mov_b32_e32 v48, v2
	v_mov_b32_e32 v49, v2
	v_mov_b32_e32 v54, v2
	v_mov_b32_e32 v55, v2
	v_mov_b32_e32 v56, v2
	v_mov_b32_e32 v57, v2
	v_mov_b32_e32 v70, v2
	v_mov_b32_e32 v71, v2
	v_mov_b32_e32 v72, v2
	v_mov_b32_e32 v73, v2
	v_mov_b32_e32 v86, v2
	v_mov_b32_e32 v87, v2
	v_mov_b32_e32 v88, v2
	v_mov_b32_e32 v89, v2
	v_mov_b32_e32 v18, v2
	v_mov_b32_e32 v19, v2
	v_mov_b32_e32 v20, v2
	v_mov_b32_e32 v21, v2
	v_mov_b32_e32 v30, v2
	v_mov_b32_e32 v31, v2
	v_mov_b32_e32 v32, v2
	v_mov_b32_e32 v33, v2
	v_mov_b32_e32 v42, v2
	v_mov_b32_e32 v43, v2
	v_mov_b32_e32 v44, v2
	v_mov_b32_e32 v45, v2
	v_mov_b32_e32 v50, v2
	v_mov_b32_e32 v51, v2
	v_mov_b32_e32 v52, v2
	v_mov_b32_e32 v53, v2
	v_mov_b32_e32 v66, v2
	v_mov_b32_e32 v67, v2
	v_mov_b32_e32 v68, v2
	v_mov_b32_e32 v69, v2
	v_mov_b32_e32 v82, v2
	v_mov_b32_e32 v83, v2
	v_mov_b32_e32 v84, v2
	v_mov_b32_e32 v85, v2
	v_mov_b32_e32 v98, v2
	v_mov_b32_e32 v99, v2
	v_mov_b32_e32 v100, v2
	v_mov_b32_e32 v101, v2
	v_mov_b32_e32 v110, v2
	v_mov_b32_e32 v111, v2
	v_mov_b32_e32 v112, v2
	v_mov_b32_e32 v113, v2
	v_mov_b32_e32 v78, v2
	v_mov_b32_e32 v79, v2
	v_mov_b32_e32 v80, v2
	v_mov_b32_e32 v81, v2
	v_mov_b32_e32 v74, v2
	v_mov_b32_e32 v75, v2
	v_mov_b32_e32 v76, v2
	v_mov_b32_e32 v77, v2
	v_mov_b32_e32 v62, v2
	v_mov_b32_e32 v63, v2
	v_mov_b32_e32 v64, v2
	v_mov_b32_e32 v65, v2
	v_mov_b32_e32 v58, v2
	v_mov_b32_e32 v59, v2
	v_mov_b32_e32 v60, v2
	v_mov_b32_e32 v61, v2
	v_mov_b32_e32 v38, v2
	v_mov_b32_e32 v39, v2
	v_mov_b32_e32 v40, v2
	v_mov_b32_e32 v41, v2
	v_mov_b32_e32 v26, v2
	v_mov_b32_e32 v27, v2
	v_mov_b32_e32 v28, v2
	v_mov_b32_e32 v29, v2
	v_mov_b32_e32 v14, v2
	v_mov_b32_e32 v15, v2
	v_mov_b32_e32 v16, v2
	v_mov_b32_e32 v17, v2
	v_mov_b32_e32 v10, v2
	v_mov_b32_e32 v11, v2
	v_mov_b32_e32 v12, v2
	v_mov_b32_e32 v13, v2
	v_mov_b32_e32 v126, v2
	v_mov_b32_e32 v127, v2
	v_mov_b32_e32 v128, v2
	v_mov_b32_e32 v129, v2
	v_mov_b32_e32 v122, v2
	v_mov_b32_e32 v123, v2
	v_mov_b32_e32 v124, v2
	v_mov_b32_e32 v125, v2
	v_mov_b32_e32 v118, v2
	v_mov_b32_e32 v119, v2
	v_mov_b32_e32 v120, v2
	v_mov_b32_e32 v121, v2
	v_mov_b32_e32 v114, v2
	v_mov_b32_e32 v115, v2
	v_mov_b32_e32 v116, v2
	v_mov_b32_e32 v117, v2
	v_mov_b32_e32 v106, v2
	v_mov_b32_e32 v107, v2
	v_mov_b32_e32 v108, v2
	v_mov_b32_e32 v109, v2
	v_mov_b32_e32 v102, v2
	v_mov_b32_e32 v103, v2
	v_mov_b32_e32 v104, v2
	v_mov_b32_e32 v105, v2
	v_mov_b32_e32 v94, v2
	v_mov_b32_e32 v95, v2
	v_mov_b32_e32 v96, v2
	v_mov_b32_e32 v97, v2
	v_mov_b32_e32 v90, v2
	v_mov_b32_e32 v91, v2
	v_mov_b32_e32 v92, v2
	v_mov_b32_e32 v93, v2
	s_andn2_b64 vcc, exec, s[0:1]
	s_cbranch_vccnz .LBB0_653
	s_branch .LBB0_654

.LBB0_749:
	s_add_u32 s20, s18, 0xfff80080
	s_addc_u32 s21, s19, -1
	s_add_i32 s58, 0, 0x10000
	s_cmp_eq_u32 s57, 28
	s_cselect_b32 s23, s39, s21
	s_cselect_b32 s22, s53, s20
	s_cselect_b32 s21, s31, s56
	s_cselect_b32 s20, s54, s55
	v_lshl_add_u64 v[212:213], s[18:19], 0, v[154:155]
	s_add_i32 m0, s44, 0xc000
	ds_read_b128 v[176:179], v158
	ds_read_b128 v[192:195], v158 offset:1024
	ds_read_b128 v[196:199], v158 offset:2048
	ds_read_b128 v[200:203], v158 offset:3072
	ds_read_b128 v[204:207], v158 offset:4096
	ds_read_b128 v[208:211], v158 offset:5120
	ds_read_b128 v[224:227], v158 offset:6144
	ds_read_b128 v[228:231], v158 offset:7168
	global_load_lds_dwordx4 v[212:213], off
	v_lshl_add_u64 v[212:213], s[18:19], 0, v[156:157]
	s_add_i32 m0, s44, 0xe000
	s_nop 0
	global_load_lds_dwordx4 v[212:213], off
	s_waitcnt lgkmcnt(8)
	s_barrier
	s_waitcnt lgkmcnt(0)
	v_mfma_f32_16x16x32_bf16 v[126:129], v[160:163], v[176:179], v[126:129]
	v_mfma_f32_16x16x32_bf16 v[122:125], v[168:171], v[176:179], v[122:125]
	v_mfma_f32_16x16x32_bf16 v[110:113], v[160:163], v[196:199], v[110:113]
	v_mfma_f32_16x16x32_bf16 v[106:109], v[168:171], v[196:199], v[106:109]
	v_mfma_f32_16x16x32_bf16 v[94:97], v[160:163], v[204:207], v[94:97]
	v_mfma_f32_16x16x32_bf16 v[90:93], v[168:171], v[204:207], v[90:93]
	v_mfma_f32_16x16x32_bf16 v[78:81], v[160:163], v[224:227], v[78:81]
	v_mfma_f32_16x16x32_bf16 v[74:77], v[168:171], v[224:227], v[74:77]
	v_mfma_f32_16x16x32_bf16 v[126:129], v[164:167], v[192:195], v[126:129]
	v_mfma_f32_16x16x32_bf16 v[122:125], v[172:175], v[192:195], v[122:125]
	v_mfma_f32_16x16x32_bf16 v[110:113], v[164:167], v[200:203], v[110:113]
	v_mfma_f32_16x16x32_bf16 v[106:109], v[172:175], v[200:203], v[106:109]
	v_mfma_f32_16x16x32_bf16 v[94:97], v[164:167], v[208:211], v[94:97]
	v_mfma_f32_16x16x32_bf16 v[90:93], v[172:175], v[208:211], v[90:93]
	v_mfma_f32_16x16x32_bf16 v[78:81], v[164:167], v[228:231], v[78:81]
	v_mfma_f32_16x16x32_bf16 v[74:77], v[172:175], v[228:231], v[74:77]
	s_barrier
	s_add_i32 s82, 0, 0x14000
	s_add_i32 s58, s58, s29
	v_add_u32_e32 v159, s82, v1
	v_lshl_add_u64 v[212:213], s[20:21], 0, v[134:135]
	s_mov_b32 m0, s58
	ds_read_b128 v[232:235], v159
	ds_read_b128 v[236:239], v159 offset:1024
	ds_read_b128 v[240:243], v159 offset:2048
	ds_read_b128 v[244:247], v159 offset:3072
	global_load_lds_dwordx4 v[212:213], off
	v_lshl_add_u64 v[248:249], s[20:21], 0, v[130:131]
	s_add_i32 m0, s58, 0x2000
	s_nop 0
	global_load_lds_dwordx4 v[248:249], off
	s_mov_b32 m0, s44
	v_lshl_add_u64 v[250:251], s[22:23], 0, v[136:137]
	s_barrier
	s_waitcnt lgkmcnt(0)
	v_mfma_f32_16x16x32_bf16 v[118:121], v[232:235], v[176:179], v[118:121]
	v_mfma_f32_16x16x32_bf16 v[114:117], v[240:243], v[176:179], v[114:117]
	v_mfma_f32_16x16x32_bf16 v[102:105], v[232:235], v[196:199], v[102:105]
	v_mfma_f32_16x16x32_bf16 v[98:101], v[240:243], v[196:199], v[98:101]
	v_mfma_f32_16x16x32_bf16 v[86:89], v[232:235], v[204:207], v[86:89]
	v_mfma_f32_16x16x32_bf16 v[82:85], v[240:243], v[204:207], v[82:85]
	v_mfma_f32_16x16x32_bf16 v[70:73], v[232:235], v[224:227], v[70:73]
	v_mfma_f32_16x16x32_bf16 v[66:69], v[240:243], v[224:227], v[66:69]
	v_mfma_f32_16x16x32_bf16 v[118:121], v[236:239], v[192:195], v[118:121]
	v_mfma_f32_16x16x32_bf16 v[114:117], v[244:247], v[192:195], v[114:117]
	v_mfma_f32_16x16x32_bf16 v[102:105], v[236:239], v[200:203], v[102:105]
	v_mfma_f32_16x16x32_bf16 v[98:101], v[244:247], v[200:203], v[98:101]
	v_mfma_f32_16x16x32_bf16 v[86:89], v[236:239], v[208:211], v[86:89]
	v_mfma_f32_16x16x32_bf16 v[82:85], v[244:247], v[208:211], v[82:85]
	v_mfma_f32_16x16x32_bf16 v[70:73], v[236:239], v[228:231], v[70:73]
	v_mfma_f32_16x16x32_bf16 v[66:69], v[244:247], v[228:231], v[66:69]
	s_barrier
	ds_read_b128 v[176:179], v158 offset:16384
	ds_read_b128 v[192:195], v158 offset:17408
	ds_read_b128 v[196:199], v158 offset:18432
	ds_read_b128 v[200:203], v158 offset:19456
	ds_read_b128 v[204:207], v158 offset:20480
	ds_read_b128 v[208:211], v158 offset:21504
	ds_read_b128 v[224:227], v158 offset:22528
	ds_read_b128 v[228:231], v158 offset:23552
	global_load_lds_dwordx4 v[250:251], off
	v_lshl_add_u64 v[222:223], s[22:23], 0, v[132:133]
	s_mov_b32 m0, s45
	s_nop 0
	global_load_lds_dwordx4 v[222:223], off
	s_waitcnt vmcnt(10)
	s_barrier
	s_waitcnt lgkmcnt(0)
	v_mfma_f32_16x16x32_bf16 v[62:65], v[160:163], v[176:179], v[62:65]
	v_mfma_f32_16x16x32_bf16 v[58:61], v[168:171], v[176:179], v[58:61]
	v_mfma_f32_16x16x32_bf16 v[46:49], v[160:163], v[196:199], v[46:49]
	v_mfma_f32_16x16x32_bf16 v[42:45], v[168:171], v[196:199], v[42:45]
	v_mfma_f32_16x16x32_bf16 v[30:33], v[160:163], v[204:207], v[30:33]
	v_mfma_f32_16x16x32_bf16 v[26:29], v[168:171], v[204:207], v[26:29]
	v_mfma_f32_16x16x32_bf16 v[14:17], v[160:163], v[224:227], v[14:17]
	v_mfma_f32_16x16x32_bf16 v[10:13], v[168:171], v[224:227], v[10:13]
	v_mfma_f32_16x16x32_bf16 v[62:65], v[164:167], v[192:195], v[62:65]
	v_mfma_f32_16x16x32_bf16 v[58:61], v[172:175], v[192:195], v[58:61]
	v_mfma_f32_16x16x32_bf16 v[46:49], v[164:167], v[200:203], v[46:49]
	v_mfma_f32_16x16x32_bf16 v[42:45], v[172:175], v[200:203], v[42:45]
	v_mfma_f32_16x16x32_bf16 v[30:33], v[164:167], v[208:211], v[30:33]
	v_mfma_f32_16x16x32_bf16 v[26:29], v[172:175], v[208:211], v[26:29]
	v_mfma_f32_16x16x32_bf16 v[14:17], v[164:167], v[228:231], v[14:17]
	v_mfma_f32_16x16x32_bf16 v[10:13], v[172:175], v[228:231], v[10:13]
	s_barrier
	s_add_u32 s58, s20, 0x80000
	s_addc_u32 s59, s21, 0
	s_add_i32 s82, s82, s29
	v_lshl_add_u64 v[160:161], s[58:59], 0, v[134:135]
	s_mov_b32 m0, s82
	s_nop 0
	global_load_lds_dwordx4 v[160:161], off
	v_lshl_add_u64 v[160:161], s[58:59], 0, v[130:131]
	s_add_i32 m0, s82, 0x2000
	s_nop 0
	global_load_lds_dwordx4 v[160:161], off
	v_add_u32_e32 v159, 0x18000, v1
	ds_read_b128 v[160:163], v159
	ds_read_b128 v[164:167], v159 offset:1024
	ds_read_b128 v[168:171], v159 offset:2048
	ds_read_b128 v[172:175], v159 offset:3072
	s_add_i32 s58, 0, 0x18000
	s_waitcnt vmcnt(6)
	s_barrier
	v_mfma_f32_16x16x32_bf16 v[54:57], v[232:235], v[176:179], v[54:57]
	v_mfma_f32_16x16x32_bf16 v[50:53], v[240:243], v[176:179], v[50:53]
	v_mfma_f32_16x16x32_bf16 v[38:41], v[232:235], v[196:199], v[38:41]
	v_mfma_f32_16x16x32_bf16 v[34:37], v[240:243], v[196:199], v[34:37]
	v_mfma_f32_16x16x32_bf16 v[22:25], v[232:235], v[204:207], v[22:25]
	v_mfma_f32_16x16x32_bf16 v[18:21], v[240:243], v[204:207], v[18:21]
	v_mfma_f32_16x16x32_bf16 v[6:9], v[232:235], v[224:227], v[6:9]
	v_mfma_f32_16x16x32_bf16 v[2:5], v[240:243], v[224:227], v[2:5]
	v_mfma_f32_16x16x32_bf16 v[54:57], v[236:239], v[192:195], v[54:57]
	v_mfma_f32_16x16x32_bf16 v[50:53], v[244:247], v[192:195], v[50:53]
	v_mfma_f32_16x16x32_bf16 v[38:41], v[236:239], v[200:203], v[38:41]
	v_mfma_f32_16x16x32_bf16 v[34:37], v[244:247], v[200:203], v[34:37]
	v_mfma_f32_16x16x32_bf16 v[22:25], v[236:239], v[208:211], v[22:25]
	v_mfma_f32_16x16x32_bf16 v[18:21], v[244:247], v[208:211], v[18:21]
	v_mfma_f32_16x16x32_bf16 v[6:9], v[236:239], v[228:231], v[6:9]
	v_mfma_f32_16x16x32_bf16 v[2:5], v[244:247], v[228:231], v[2:5]
	s_barrier
	s_add_u32 s22, s22, 0x80000
	s_addc_u32 s23, s23, 0
	s_mov_b32 m0, s46
	v_lshl_add_u64 v[232:233], s[22:23], 0, v[136:137]
	ds_read_b128 v[176:179], v158 offset:32768
	ds_read_b128 v[192:195], v158 offset:33792
	ds_read_b128 v[196:199], v158 offset:34816
	ds_read_b128 v[200:203], v158 offset:35840
	ds_read_b128 v[204:207], v158 offset:36864
	ds_read_b128 v[208:211], v158 offset:37888
	ds_read_b128 v[224:227], v158 offset:38912
	ds_read_b128 v[228:231], v158 offset:39936
	global_load_lds_dwordx4 v[232:233], off
	v_lshl_add_u64 v[232:233], s[22:23], 0, v[132:133]
	s_mov_b32 m0, s47
	s_nop 0
	global_load_lds_dwordx4 v[232:233], off
	s_waitcnt lgkmcnt(8)
	s_barrier
	s_waitcnt lgkmcnt(0)
	v_mfma_f32_16x16x32_bf16 v[126:129], v[160:163], v[176:179], v[126:129]
	v_mfma_f32_16x16x32_bf16 v[122:125], v[168:171], v[176:179], v[122:125]
	v_mfma_f32_16x16x32_bf16 v[110:113], v[160:163], v[196:199], v[110:113]
	v_mfma_f32_16x16x32_bf16 v[106:109], v[168:171], v[196:199], v[106:109]
	v_mfma_f32_16x16x32_bf16 v[94:97], v[160:163], v[204:207], v[94:97]
	v_mfma_f32_16x16x32_bf16 v[90:93], v[168:171], v[204:207], v[90:93]
	v_mfma_f32_16x16x32_bf16 v[78:81], v[160:163], v[224:227], v[78:81]
	v_mfma_f32_16x16x32_bf16 v[74:77], v[168:171], v[224:227], v[74:77]
	v_mfma_f32_16x16x32_bf16 v[126:129], v[164:167], v[192:195], v[126:129]
	v_mfma_f32_16x16x32_bf16 v[122:125], v[172:175], v[192:195], v[122:125]
	v_mfma_f32_16x16x32_bf16 v[110:113], v[164:167], v[200:203], v[110:113]
	v_mfma_f32_16x16x32_bf16 v[106:109], v[172:175], v[200:203], v[106:109]
	v_mfma_f32_16x16x32_bf16 v[94:97], v[164:167], v[208:211], v[94:97]
	v_mfma_f32_16x16x32_bf16 v[90:93], v[172:175], v[208:211], v[90:93]
	v_mfma_f32_16x16x32_bf16 v[78:81], v[164:167], v[228:231], v[78:81]
	v_mfma_f32_16x16x32_bf16 v[74:77], v[172:175], v[228:231], v[74:77]
	s_barrier
	s_add_i32 s22, 0, 0x1c000
	s_add_i32 s23, s58, s29
	v_add_u32_e32 v159, s22, v1
	v_lshl_add_u64 v[212:213], v[212:213], 0, s[78:79]
	s_mov_b32 m0, s23
	ds_read_b128 v[232:235], v159
	ds_read_b128 v[236:239], v159 offset:1024
	ds_read_b128 v[240:243], v159 offset:2048
	ds_read_b128 v[244:247], v159 offset:3072
	global_load_lds_dwordx4 v[212:213], off
	v_lshl_add_u64 v[212:213], v[248:249], 0, s[78:79]
	s_add_i32 m0, s23, 0x2000
	s_nop 0
	global_load_lds_dwordx4 v[212:213], off
	s_mov_b32 m0, s48
	v_lshl_add_u64 v[212:213], v[250:251], 0, s[78:79]
	s_barrier
	s_waitcnt lgkmcnt(0)
	v_mfma_f32_16x16x32_bf16 v[118:121], v[232:235], v[176:179], v[118:121]
	v_mfma_f32_16x16x32_bf16 v[114:117], v[240:243], v[176:179], v[114:117]
	v_mfma_f32_16x16x32_bf16 v[102:105], v[232:235], v[196:199], v[102:105]
	v_mfma_f32_16x16x32_bf16 v[98:101], v[240:243], v[196:199], v[98:101]
	v_mfma_f32_16x16x32_bf16 v[86:89], v[232:235], v[204:207], v[86:89]
	v_mfma_f32_16x16x32_bf16 v[82:85], v[240:243], v[204:207], v[82:85]
	v_mfma_f32_16x16x32_bf16 v[70:73], v[232:235], v[224:227], v[70:73]
	v_mfma_f32_16x16x32_bf16 v[66:69], v[240:243], v[224:227], v[66:69]
	v_mfma_f32_16x16x32_bf16 v[118:121], v[236:239], v[192:195], v[118:121]
	v_mfma_f32_16x16x32_bf16 v[114:117], v[244:247], v[192:195], v[114:117]
	v_mfma_f32_16x16x32_bf16 v[102:105], v[236:239], v[200:203], v[102:105]
	v_mfma_f32_16x16x32_bf16 v[98:101], v[244:247], v[200:203], v[98:101]
	v_mfma_f32_16x16x32_bf16 v[86:89], v[236:239], v[208:211], v[86:89]
	v_mfma_f32_16x16x32_bf16 v[82:85], v[244:247], v[208:211], v[82:85]
	v_mfma_f32_16x16x32_bf16 v[70:73], v[236:239], v[228:231], v[70:73]
	v_mfma_f32_16x16x32_bf16 v[66:69], v[244:247], v[228:231], v[66:69]
	s_barrier
	ds_read_b128 v[176:179], v158 offset:49152
	ds_read_b128 v[192:195], v158 offset:50176
	ds_read_b128 v[196:199], v158 offset:51200
	ds_read_b128 v[200:203], v158 offset:52224
	ds_read_b128 v[204:207], v158 offset:53248
	ds_read_b128 v[208:211], v158 offset:54272
	ds_read_b128 v[224:227], v158 offset:55296
	ds_read_b128 v[228:231], v158 offset:56320
	global_load_lds_dwordx4 v[212:213], off
	v_lshl_add_u64 v[212:213], v[222:223], 0, s[78:79]
	s_mov_b32 m0, s49
	s_nop 0
	global_load_lds_dwordx4 v[212:213], off
	s_waitcnt vmcnt(10)
	s_barrier
	s_waitcnt lgkmcnt(0)
	v_mfma_f32_16x16x32_bf16 v[62:65], v[160:163], v[176:179], v[62:65]
	v_mfma_f32_16x16x32_bf16 v[58:61], v[168:171], v[176:179], v[58:61]
	v_mfma_f32_16x16x32_bf16 v[46:49], v[160:163], v[196:199], v[46:49]
	v_mfma_f32_16x16x32_bf16 v[42:45], v[168:171], v[196:199], v[42:45]
	v_mfma_f32_16x16x32_bf16 v[30:33], v[160:163], v[204:207], v[30:33]
	v_mfma_f32_16x16x32_bf16 v[26:29], v[168:171], v[204:207], v[26:29]
	v_mfma_f32_16x16x32_bf16 v[14:17], v[160:163], v[224:227], v[14:17]
	v_mfma_f32_16x16x32_bf16 v[10:13], v[168:171], v[224:227], v[10:13]
	v_mfma_f32_16x16x32_bf16 v[62:65], v[164:167], v[192:195], v[62:65]
	v_mfma_f32_16x16x32_bf16 v[58:61], v[172:175], v[192:195], v[58:61]
	v_mfma_f32_16x16x32_bf16 v[46:49], v[164:167], v[200:203], v[46:49]
	v_mfma_f32_16x16x32_bf16 v[42:45], v[172:175], v[200:203], v[42:45]
	v_mfma_f32_16x16x32_bf16 v[30:33], v[164:167], v[208:211], v[30:33]
	v_mfma_f32_16x16x32_bf16 v[26:29], v[172:175], v[208:211], v[26:29]
	v_mfma_f32_16x16x32_bf16 v[14:17], v[164:167], v[228:231], v[14:17]
	v_mfma_f32_16x16x32_bf16 v[10:13], v[172:175], v[228:231], v[10:13]
	s_barrier
	s_add_u32 s20, s20, 0x80080
	s_addc_u32 s21, s21, 0
	s_add_i32 s22, s22, s29
	v_lshl_add_u64 v[160:161], s[20:21], 0, v[134:135]
	s_mov_b32 m0, s22
	s_nop 0
	global_load_lds_dwordx4 v[160:161], off
	v_lshl_add_u64 v[160:161], s[20:21], 0, v[130:131]
	s_add_i32 m0, s22, 0x2000
	s_nop 0
	global_load_lds_dwordx4 v[160:161], off
	v_add_u32_e32 v159, 0x10000, v1
	ds_read_b128 v[160:163], v159
	ds_read_b128 v[164:167], v159 offset:1024
	ds_read_b128 v[168:171], v159 offset:2048
	ds_read_b128 v[172:175], v159 offset:3072
	s_add_i32 s57, s57, 2
	s_add_u32 s18, s18, 0x100
	s_addc_u32 s19, s19, 0
	s_add_u32 s55, s55, 0x100
	s_addc_u32 s56, s56, 0
	s_cmp_gt_u32 s57, 29
	s_waitcnt vmcnt(6)
	s_barrier
	v_mfma_f32_16x16x32_bf16 v[54:57], v[232:235], v[176:179], v[54:57]
	v_mfma_f32_16x16x32_bf16 v[50:53], v[240:243], v[176:179], v[50:53]
	v_mfma_f32_16x16x32_bf16 v[38:41], v[232:235], v[196:199], v[38:41]
	v_mfma_f32_16x16x32_bf16 v[34:37], v[240:243], v[196:199], v[34:37]
	v_mfma_f32_16x16x32_bf16 v[22:25], v[232:235], v[204:207], v[22:25]
	v_mfma_f32_16x16x32_bf16 v[18:21], v[240:243], v[204:207], v[18:21]
	v_mfma_f32_16x16x32_bf16 v[6:9], v[232:235], v[224:227], v[6:9]
	v_mfma_f32_16x16x32_bf16 v[2:5], v[240:243], v[224:227], v[2:5]
	v_mfma_f32_16x16x32_bf16 v[54:57], v[236:239], v[192:195], v[54:57]
	v_mfma_f32_16x16x32_bf16 v[50:53], v[244:247], v[192:195], v[50:53]
	v_mfma_f32_16x16x32_bf16 v[38:41], v[236:239], v[200:203], v[38:41]
	v_mfma_f32_16x16x32_bf16 v[34:37], v[244:247], v[200:203], v[34:37]
	v_mfma_f32_16x16x32_bf16 v[22:25], v[236:239], v[208:211], v[22:25]
	v_mfma_f32_16x16x32_bf16 v[18:21], v[244:247], v[208:211], v[18:21]
	v_mfma_f32_16x16x32_bf16 v[6:9], v[236:239], v[228:231], v[6:9]
	v_mfma_f32_16x16x32_bf16 v[2:5], v[244:247], v[228:231], v[2:5]
	s_barrier
	s_cbranch_scc0 .LBB0_749
	s_waitcnt lgkmcnt(0)
	s_lshl_b32 s18, s52, 5
	s_add_i32 s18, s18, s51
	v_max_f32_e32 v122, 0, v122
	v_max_f32_e32 v123, 0, v123
	s_ashr_i32 s19, s18, 31
	v_pk_mul_f32 v[162:163], v[122:123], v[122:123]
	v_max_f32_e32 v123, v124, v124
	s_lshl_b64 s[18:19], s[18:19], 17
	v_max_f32_e32 v122, v128, v128
	v_max_f32_e32 v124, 0, v123
	v_max_f32_e32 v123, v129, v129
	s_add_u32 s18, s68, s18
	v_max_f32_e32 v126, 0, v126
	v_max_f32_e32 v127, 0, v127
	v_max_f32_e32 v122, 0, v122
	v_max_f32_e32 v123, 0, v123
	v_max_f32_e32 v125, 0, v125
	s_addc_u32 s19, s69, s19
	v_pk_mul_f32 v[126:127], v[126:127], v[126:127]
	v_pk_mul_f32 v[128:129], v[122:123], v[122:123]
	v_pk_mul_f32 v[164:165], v[124:125], v[124:125]
	v_lshl_add_u64 v[160:161], v[138:139], 1, s[18:19]
	v_cvt_pk_bf16_f32 v122, v126, v127
	v_cvt_pk_bf16_f32 v123, v128, v129
	v_cvt_pk_bf16_f32 v124, v162, v163
	v_cvt_pk_bf16_f32 v125, v164, v165
	v_max_f32_e32 v114, 0, v114
	v_max_f32_e32 v115, 0, v115
	global_store_dwordx4 v[160:161], v[122:125], off
	v_max_f32_e32 v118, v118, v118
	v_max_f32_e32 v119, v119, v119
	v_pk_mul_f32 v[122:123], v[114:115], v[114:115]
	v_max_f32_e32 v115, v116, v116
	v_max_f32_e32 v114, v120, v120
	v_max_f32_e32 v116, 0, v115
	v_max_f32_e32 v115, v121, v121
	v_max_f32_e32 v118, 0, v118
	v_max_f32_e32 v119, 0, v119
	v_max_f32_e32 v114, 0, v114
	v_max_f32_e32 v115, 0, v115
	v_max_f32_e32 v117, 0, v117
	v_pk_mul_f32 v[118:119], v[118:119], v[118:119]
	v_pk_mul_f32 v[120:121], v[114:115], v[114:115]
	v_pk_mul_f32 v[124:125], v[116:117], v[116:117]
	v_cvt_pk_bf16_f32 v114, v118, v119
	v_cvt_pk_bf16_f32 v115, v120, v121
	v_cvt_pk_bf16_f32 v116, v122, v123
	v_cvt_pk_bf16_f32 v117, v124, v125
	v_max_f32_e32 v106, 0, v106
	v_max_f32_e32 v107, 0, v107
	global_store_dwordx4 v[160:161], v[114:117], off offset:256
	v_max_f32_e32 v110, v110, v110
	v_max_f32_e32 v111, v111, v111
	v_pk_mul_f32 v[116:117], v[106:107], v[106:107]
	v_max_f32_e32 v107, v108, v108
	v_max_f32_e32 v106, v112, v112
	v_max_f32_e32 v108, 0, v107
	v_max_f32_e32 v107, v113, v113
	v_max_f32_e32 v110, 0, v110
	v_max_f32_e32 v111, 0, v111
	v_max_f32_e32 v106, 0, v106
	v_max_f32_e32 v107, 0, v107
	v_max_f32_e32 v109, 0, v109
	v_pk_mul_f32 v[110:111], v[110:111], v[110:111]
	v_pk_mul_f32 v[112:113], v[106:107], v[106:107]
	v_pk_mul_f32 v[118:119], v[108:109], v[108:109]
	v_lshl_add_u64 v[114:115], v[140:141], 1, s[18:19]
	v_cvt_pk_bf16_f32 v106, v110, v111
	v_cvt_pk_bf16_f32 v107, v112, v113
	v_cvt_pk_bf16_f32 v108, v116, v117
	v_cvt_pk_bf16_f32 v109, v118, v119
	v_max_f32_e32 v98, 0, v98
	v_max_f32_e32 v99, 0, v99
	global_store_dwordx4 v[114:115], v[106:109], off
	v_max_f32_e32 v102, v102, v102
	v_max_f32_e32 v103, v103, v103
	v_pk_mul_f32 v[106:107], v[98:99], v[98:99]
	v_max_f32_e32 v99, v100, v100
	v_max_f32_e32 v98, v104, v104
	v_max_f32_e32 v100, 0, v99
	v_max_f32_e32 v99, v105, v105
	v_max_f32_e32 v102, 0, v102
	v_max_f32_e32 v103, 0, v103
	v_max_f32_e32 v98, 0, v98
	v_max_f32_e32 v99, 0, v99
	v_max_f32_e32 v101, 0, v101
	v_pk_mul_f32 v[102:103], v[102:103], v[102:103]
	v_pk_mul_f32 v[104:105], v[98:99], v[98:99]
	v_pk_mul_f32 v[108:109], v[100:101], v[100:101]
	v_cvt_pk_bf16_f32 v98, v102, v103
	v_cvt_pk_bf16_f32 v99, v104, v105
	v_cvt_pk_bf16_f32 v100, v106, v107
	v_cvt_pk_bf16_f32 v101, v108, v109
	v_max_f32_e32 v90, 0, v90
	v_max_f32_e32 v91, 0, v91
	global_store_dwordx4 v[114:115], v[98:101], off offset:256
	v_max_f32_e32 v94, v94, v94
	v_max_f32_e32 v95, v95, v95
	v_pk_mul_f32 v[100:101], v[90:91], v[90:91]
	v_max_f32_e32 v91, v92, v92
	v_max_f32_e32 v90, v96, v96
	v_max_f32_e32 v92, 0, v91
	v_max_f32_e32 v91, v97, v97
	v_max_f32_e32 v94, 0, v94
	v_max_f32_e32 v95, 0, v95
	v_max_f32_e32 v90, 0, v90
	v_max_f32_e32 v91, 0, v91
	v_max_f32_e32 v93, 0, v93
	v_pk_mul_f32 v[94:95], v[94:95], v[94:95]
	v_pk_mul_f32 v[96:97], v[90:91], v[90:91]
	v_pk_mul_f32 v[102:103], v[92:93], v[92:93]
	v_lshl_add_u64 v[98:99], v[142:143], 1, s[18:19]
	v_cvt_pk_bf16_f32 v90, v94, v95
	v_cvt_pk_bf16_f32 v91, v96, v97
	v_cvt_pk_bf16_f32 v92, v100, v101
	v_cvt_pk_bf16_f32 v93, v102, v103
	v_max_f32_e32 v82, 0, v82
	v_max_f32_e32 v83, 0, v83
	global_store_dwordx4 v[98:99], v[90:93], off
	v_max_f32_e32 v86, v86, v86
	v_max_f32_e32 v87, v87, v87
	v_pk_mul_f32 v[90:91], v[82:83], v[82:83]
	v_max_f32_e32 v83, v84, v84
	v_max_f32_e32 v82, v88, v88
	v_max_f32_e32 v84, 0, v83
	v_max_f32_e32 v83, v89, v89
	v_max_f32_e32 v86, 0, v86
	v_max_f32_e32 v87, 0, v87
	v_max_f32_e32 v82, 0, v82
	v_max_f32_e32 v83, 0, v83
	v_max_f32_e32 v85, 0, v85
	v_pk_mul_f32 v[86:87], v[86:87], v[86:87]
	v_pk_mul_f32 v[88:89], v[82:83], v[82:83]
	v_pk_mul_f32 v[92:93], v[84:85], v[84:85]
	v_cvt_pk_bf16_f32 v82, v86, v87
	v_cvt_pk_bf16_f32 v83, v88, v89
	v_cvt_pk_bf16_f32 v84, v90, v91
	v_cvt_pk_bf16_f32 v85, v92, v93
	v_max_f32_e32 v74, 0, v74
	v_max_f32_e32 v75, 0, v75
	global_store_dwordx4 v[98:99], v[82:85], off offset:256
	v_max_f32_e32 v78, v78, v78
	v_max_f32_e32 v79, v79, v79
	v_pk_mul_f32 v[84:85], v[74:75], v[74:75]
	v_max_f32_e32 v75, v76, v76
	v_max_f32_e32 v74, v80, v80
	v_max_f32_e32 v76, 0, v75
	v_max_f32_e32 v75, v81, v81
	v_max_f32_e32 v78, 0, v78
	v_max_f32_e32 v79, 0, v79
	v_max_f32_e32 v74, 0, v74
	v_max_f32_e32 v75, 0, v75
	v_max_f32_e32 v77, 0, v77
	v_pk_mul_f32 v[78:79], v[78:79], v[78:79]
	v_pk_mul_f32 v[80:81], v[74:75], v[74:75]
	v_pk_mul_f32 v[86:87], v[76:77], v[76:77]
	v_lshl_add_u64 v[82:83], v[144:145], 1, s[18:19]
	v_cvt_pk_bf16_f32 v74, v78, v79
	v_cvt_pk_bf16_f32 v75, v80, v81
	v_cvt_pk_bf16_f32 v76, v84, v85
	v_cvt_pk_bf16_f32 v77, v86, v87
	v_max_f32_e32 v66, 0, v66
	v_max_f32_e32 v67, 0, v67
	global_store_dwordx4 v[82:83], v[74:77], off
	v_max_f32_e32 v70, v70, v70
	v_max_f32_e32 v71, v71, v71
	v_pk_mul_f32 v[74:75], v[66:67], v[66:67]
	v_max_f32_e32 v67, v68, v68
	v_max_f32_e32 v66, v72, v72
	v_max_f32_e32 v68, 0, v67
	v_max_f32_e32 v67, v73, v73
	v_max_f32_e32 v70, 0, v70
	v_max_f32_e32 v71, 0, v71
	v_max_f32_e32 v66, 0, v66
	v_max_f32_e32 v67, 0, v67
	v_max_f32_e32 v69, 0, v69
	v_pk_mul_f32 v[70:71], v[70:71], v[70:71]
	v_pk_mul_f32 v[72:73], v[66:67], v[66:67]
	v_pk_mul_f32 v[76:77], v[68:69], v[68:69]
	v_cvt_pk_bf16_f32 v66, v70, v71
	v_cvt_pk_bf16_f32 v67, v72, v73
	v_cvt_pk_bf16_f32 v68, v74, v75
	v_cvt_pk_bf16_f32 v69, v76, v77
	v_max_f32_e32 v58, 0, v58
	v_max_f32_e32 v59, 0, v59
	global_store_dwordx4 v[82:83], v[66:69], off offset:256
	v_max_f32_e32 v62, v62, v62
	v_max_f32_e32 v63, v63, v63
	v_pk_mul_f32 v[68:69], v[58:59], v[58:59]
	v_max_f32_e32 v59, v60, v60
	v_max_f32_e32 v58, v64, v64
	v_max_f32_e32 v60, 0, v59
	v_max_f32_e32 v59, v65, v65
	v_max_f32_e32 v62, 0, v62
	v_max_f32_e32 v63, 0, v63
	v_max_f32_e32 v58, 0, v58
	v_max_f32_e32 v59, 0, v59
	v_max_f32_e32 v61, 0, v61
	v_pk_mul_f32 v[62:63], v[62:63], v[62:63]
	v_pk_mul_f32 v[64:65], v[58:59], v[58:59]
	v_pk_mul_f32 v[70:71], v[60:61], v[60:61]
	v_lshl_add_u64 v[66:67], v[146:147], 1, s[18:19]
	v_cvt_pk_bf16_f32 v58, v62, v63
	v_cvt_pk_bf16_f32 v59, v64, v65
	v_cvt_pk_bf16_f32 v60, v68, v69
	v_cvt_pk_bf16_f32 v61, v70, v71
	v_max_f32_e32 v50, 0, v50
	v_max_f32_e32 v51, 0, v51
	global_store_dwordx4 v[66:67], v[58:61], off
	v_max_f32_e32 v54, v54, v54
	v_max_f32_e32 v55, v55, v55
	v_pk_mul_f32 v[58:59], v[50:51], v[50:51]
	v_max_f32_e32 v51, v52, v52
	v_max_f32_e32 v50, v56, v56
	v_max_f32_e32 v52, 0, v51
	v_max_f32_e32 v51, v57, v57
	v_max_f32_e32 v54, 0, v54
	v_max_f32_e32 v55, 0, v55
	v_max_f32_e32 v50, 0, v50
	v_max_f32_e32 v51, 0, v51
	v_max_f32_e32 v53, 0, v53
	v_pk_mul_f32 v[54:55], v[54:55], v[54:55]
	v_pk_mul_f32 v[56:57], v[50:51], v[50:51]
	v_pk_mul_f32 v[60:61], v[52:53], v[52:53]
	v_cvt_pk_bf16_f32 v50, v54, v55
	v_cvt_pk_bf16_f32 v51, v56, v57
	v_cvt_pk_bf16_f32 v52, v58, v59
	v_cvt_pk_bf16_f32 v53, v60, v61
	v_max_f32_e32 v42, 0, v42
	v_max_f32_e32 v43, 0, v43
	global_store_dwordx4 v[66:67], v[50:53], off offset:256
	v_max_f32_e32 v46, v46, v46
	v_max_f32_e32 v47, v47, v47
	v_pk_mul_f32 v[52:53], v[42:43], v[42:43]
	v_max_f32_e32 v43, v44, v44
	v_max_f32_e32 v42, v48, v48
	v_max_f32_e32 v44, 0, v43
	v_max_f32_e32 v43, v49, v49
	v_max_f32_e32 v46, 0, v46
	v_max_f32_e32 v47, 0, v47
	v_max_f32_e32 v42, 0, v42
	v_max_f32_e32 v43, 0, v43
	v_max_f32_e32 v45, 0, v45
	v_pk_mul_f32 v[46:47], v[46:47], v[46:47]
	v_pk_mul_f32 v[48:49], v[42:43], v[42:43]
	v_pk_mul_f32 v[54:55], v[44:45], v[44:45]
	v_lshl_add_u64 v[50:51], v[148:149], 1, s[18:19]
	v_cvt_pk_bf16_f32 v42, v46, v47
	v_cvt_pk_bf16_f32 v43, v48, v49
	v_cvt_pk_bf16_f32 v44, v52, v53
	v_cvt_pk_bf16_f32 v45, v54, v55
	v_max_f32_e32 v34, 0, v34
	v_max_f32_e32 v35, 0, v35
	global_store_dwordx4 v[50:51], v[42:45], off
	v_max_f32_e32 v38, v38, v38
	v_max_f32_e32 v39, v39, v39
	v_pk_mul_f32 v[42:43], v[34:35], v[34:35]
	v_max_f32_e32 v35, v36, v36
	v_max_f32_e32 v34, v40, v40
	v_max_f32_e32 v36, 0, v35
	v_max_f32_e32 v35, v41, v41
	v_max_f32_e32 v38, 0, v38
	v_max_f32_e32 v39, 0, v39
	v_max_f32_e32 v34, 0, v34
	v_max_f32_e32 v35, 0, v35
	v_max_f32_e32 v37, 0, v37
	v_pk_mul_f32 v[38:39], v[38:39], v[38:39]
	v_pk_mul_f32 v[40:41], v[34:35], v[34:35]
	v_pk_mul_f32 v[44:45], v[36:37], v[36:37]
	v_cvt_pk_bf16_f32 v34, v38, v39
	v_cvt_pk_bf16_f32 v35, v40, v41
	v_cvt_pk_bf16_f32 v36, v42, v43
	v_cvt_pk_bf16_f32 v37, v44, v45
	v_max_f32_e32 v26, 0, v26
	v_max_f32_e32 v27, 0, v27
	global_store_dwordx4 v[50:51], v[34:37], off offset:256
	v_max_f32_e32 v30, v30, v30
	v_max_f32_e32 v31, v31, v31
	v_pk_mul_f32 v[36:37], v[26:27], v[26:27]
	v_max_f32_e32 v27, v28, v28
	v_max_f32_e32 v26, v32, v32
	v_max_f32_e32 v28, 0, v27
	v_max_f32_e32 v27, v33, v33
	v_max_f32_e32 v30, 0, v30
	v_max_f32_e32 v31, 0, v31
	v_max_f32_e32 v26, 0, v26
	v_max_f32_e32 v27, 0, v27
	v_max_f32_e32 v29, 0, v29
	v_pk_mul_f32 v[30:31], v[30:31], v[30:31]
	v_pk_mul_f32 v[32:33], v[26:27], v[26:27]
	v_pk_mul_f32 v[38:39], v[28:29], v[28:29]
	v_lshl_add_u64 v[34:35], v[150:151], 1, s[18:19]
	v_cvt_pk_bf16_f32 v26, v30, v31
	v_cvt_pk_bf16_f32 v27, v32, v33
	v_cvt_pk_bf16_f32 v28, v36, v37
	v_cvt_pk_bf16_f32 v29, v38, v39
	v_max_f32_e32 v18, 0, v18
	v_max_f32_e32 v19, 0, v19
	global_store_dwordx4 v[34:35], v[26:29], off
	v_max_f32_e32 v22, v22, v22
	v_max_f32_e32 v23, v23, v23
	v_pk_mul_f32 v[26:27], v[18:19], v[18:19]
	v_max_f32_e32 v19, v20, v20
	v_max_f32_e32 v18, v24, v24
	v_max_f32_e32 v20, 0, v19
	v_max_f32_e32 v19, v25, v25
	v_max_f32_e32 v22, 0, v22
	v_max_f32_e32 v23, 0, v23
	v_max_f32_e32 v18, 0, v18
	v_max_f32_e32 v19, 0, v19
	v_max_f32_e32 v21, 0, v21
	v_pk_mul_f32 v[22:23], v[22:23], v[22:23]
	v_pk_mul_f32 v[24:25], v[18:19], v[18:19]
	v_pk_mul_f32 v[28:29], v[20:21], v[20:21]
	v_cvt_pk_bf16_f32 v18, v22, v23
	v_cvt_pk_bf16_f32 v19, v24, v25
	v_cvt_pk_bf16_f32 v20, v26, v27
	v_cvt_pk_bf16_f32 v21, v28, v29
	v_max_f32_e32 v10, 0, v10
	v_max_f32_e32 v11, 0, v11
	global_store_dwordx4 v[34:35], v[18:21], off offset:256
	v_max_f32_e32 v14, v14, v14
	v_max_f32_e32 v15, v15, v15
	v_pk_mul_f32 v[20:21], v[10:11], v[10:11]
	v_max_f32_e32 v11, v12, v12
	v_max_f32_e32 v10, v16, v16
	v_max_f32_e32 v12, 0, v11
	v_max_f32_e32 v11, v17, v17
	v_max_f32_e32 v14, 0, v14
	v_max_f32_e32 v15, 0, v15
	v_max_f32_e32 v10, 0, v10
	v_max_f32_e32 v11, 0, v11
	v_max_f32_e32 v13, 0, v13
	v_pk_mul_f32 v[14:15], v[14:15], v[14:15]
	v_pk_mul_f32 v[16:17], v[10:11], v[10:11]
	v_pk_mul_f32 v[22:23], v[12:13], v[12:13]
	v_lshl_add_u64 v[18:19], v[152:153], 1, s[18:19]
	v_cvt_pk_bf16_f32 v10, v14, v15
	v_cvt_pk_bf16_f32 v11, v16, v17
	v_cvt_pk_bf16_f32 v12, v20, v21
	v_cvt_pk_bf16_f32 v13, v22, v23
	v_max_f32_e32 v2, 0, v2
	v_max_f32_e32 v3, 0, v3
	global_store_dwordx4 v[18:19], v[10:13], off
	v_max_f32_e32 v6, v6, v6
	v_max_f32_e32 v7, v7, v7
	v_pk_mul_f32 v[10:11], v[2:3], v[2:3]
	v_max_f32_e32 v3, v4, v4
	v_max_f32_e32 v2, v8, v8
	v_max_f32_e32 v4, 0, v3
	v_max_f32_e32 v3, v9, v9
	v_max_f32_e32 v6, 0, v6
	v_max_f32_e32 v7, 0, v7
	v_max_f32_e32 v2, 0, v2
	v_max_f32_e32 v3, 0, v3
	v_max_f32_e32 v5, 0, v5
	v_pk_mul_f32 v[6:7], v[6:7], v[6:7]
	v_pk_mul_f32 v[8:9], v[2:3], v[2:3]
	v_pk_mul_f32 v[12:13], v[4:5], v[4:5]
	v_cvt_pk_bf16_f32 v2, v6, v7
	v_cvt_pk_bf16_f32 v3, v8, v9
	v_cvt_pk_bf16_f32 v4, v10, v11
	v_cvt_pk_bf16_f32 v5, v12, v13
	s_and_b64 vcc, exec, s[0:1]
	s_mov_b32 s51, s30
	s_mov_b32 s52, s38
	s_mov_b64 s[20:21], s[80:81]
	s_mov_b64 s[18:19], s[42:43]
	global_store_dwordx4 v[18:19], v[2:5], off offset:256
	s_cbranch_vccz .LBB0_742
	s_waitcnt vmcnt(0)
	v_readlane_b32 s38, v255, 28
	s_cmpk_gt_u32 s26, 0xff
	v_readlane_b32 s39, v255, 29
	v_readlane_b32 s42, v255, 32
	s_cbranch_scc1 .LBB0_753
	s_barrier

.LBB0_814:
	s_add_i32 s22, s55, 0xffff0000
	s_and_b32 s22, s22, 0x3e0000
	s_and_b32 s23, s90, 0x100
	s_or_b32 s56, s23, s22
	s_and_b32 s22, s55, 0x7e0000
	s_add_u32 vcc_lo, s90, 0x100
	s_addc_u32 vcc_hi, s91, 0
	s_and_b32 s23, vcc_lo, 0x100
	s_or_b32 s22, s22, s23
	s_add_u32 s22, s84, s22
	s_addc_u32 s23, s85, 0
	s_add_u32 s57, s30, s90
	s_addc_u32 s58, s31, s91
	s_add_u32 s57, s57, 0x100
	s_addc_u32 s58, s58, 0
	s_add_i32 s59, 0, 0x10000
	s_cmpk_eq_i32 s54, 0x7c
	s_cselect_b32 s91, s43, s58
	s_cselect_b32 s90, s53, s57
	s_cselect_b32 s23, s51, s23
	s_cselect_b32 s22, s52, s22
	s_add_u32 s56, s84, s56
	s_addc_u32 s57, s85, 0
	s_add_u32 s56, s56, 0x10080
	s_addc_u32 s57, s57, 0
	v_lshl_add_u64 v[204:205], s[56:57], 0, v[136:137]
	s_add_i32 m0, s28, 0xc000
	ds_read_b128 v[158:161], v140
	ds_read_b128 v[162:165], v140 offset:1024
	ds_read_b128 v[168:171], v140 offset:2048
	ds_read_b128 v[172:175], v140 offset:3072
	ds_read_b128 v[176:179], v140 offset:4096
	ds_read_b128 v[192:195], v140 offset:5120
	ds_read_b128 v[196:199], v140 offset:6144
	ds_read_b128 v[200:203], v140 offset:7168
	global_load_lds_dwordx4 v[204:205], off
	v_lshl_add_u64 v[204:205], s[56:57], 0, v[132:133]
	s_add_i32 m0, s28, 0xe000
	s_nop 0
	global_load_lds_dwordx4 v[204:205], off
	s_waitcnt lgkmcnt(8)
	s_barrier
	s_waitcnt lgkmcnt(0)
	v_mfma_f32_16x16x32_bf16 v[86:89], v[142:145], v[158:161], v[86:89]
	v_mfma_f32_16x16x32_bf16 v[94:97], v[150:153], v[158:161], v[94:97]
	v_mfma_f32_16x16x32_bf16 v[98:101], v[142:145], v[168:171], v[98:101]
	v_mfma_f32_16x16x32_bf16 v[102:105], v[150:153], v[168:171], v[102:105]
	v_mfma_f32_16x16x32_bf16 v[114:117], v[142:145], v[176:179], v[114:117]
	v_mfma_f32_16x16x32_bf16 v[122:125], v[150:153], v[176:179], v[122:125]
	v_mfma_f32_16x16x32_bf16 v[126:129], v[142:145], v[196:199], v[126:129]
	v_mfma_f32_16x16x32_bf16 v[118:121], v[150:153], v[196:199], v[118:121]
	v_mfma_f32_16x16x32_bf16 v[86:89], v[146:149], v[162:165], v[86:89]
	v_mfma_f32_16x16x32_bf16 v[94:97], v[154:157], v[162:165], v[94:97]
	v_mfma_f32_16x16x32_bf16 v[98:101], v[146:149], v[172:175], v[98:101]
	v_mfma_f32_16x16x32_bf16 v[102:105], v[154:157], v[172:175], v[102:105]
	v_mfma_f32_16x16x32_bf16 v[114:117], v[146:149], v[192:195], v[114:117]
	v_mfma_f32_16x16x32_bf16 v[122:125], v[154:157], v[192:195], v[122:125]
	v_mfma_f32_16x16x32_bf16 v[126:129], v[146:149], v[200:203], v[126:129]
	v_mfma_f32_16x16x32_bf16 v[118:121], v[154:157], v[200:203], v[118:121]
	s_barrier
	s_add_i32 s58, 0, 0x14000
	s_add_i32 s56, s59, s81
	v_add_u32_e32 v141, s58, v139
	v_lshl_add_u64 v[212:213], s[90:91], 0, v[134:135]
	s_mov_b32 m0, s56
	ds_read_b128 v[204:207], v141
	ds_read_b128 v[208:211], v141 offset:1024
	ds_read_b128 v[224:227], v141 offset:2048
	ds_read_b128 v[228:231], v141 offset:3072
	global_load_lds_dwordx4 v[212:213], off
	v_lshl_add_u64 v[222:223], s[90:91], 0, v[130:131]
	s_add_i32 m0, s56, 0x2000
	s_nop 0
	global_load_lds_dwordx4 v[222:223], off
	s_mov_b32 m0, s28
	v_lshl_add_u64 v[232:233], s[22:23], 0, v[136:137]
	s_barrier
	s_waitcnt lgkmcnt(0)
	v_mfma_f32_16x16x32_bf16 v[2:5], v[204:207], v[158:161], v[2:5]
	v_mfma_f32_16x16x32_bf16 v[6:9], v[224:227], v[158:161], v[6:9]
	v_mfma_f32_16x16x32_bf16 v[10:13], v[204:207], v[168:171], v[10:13]
	v_mfma_f32_16x16x32_bf16 v[14:17], v[224:227], v[168:171], v[14:17]
	v_mfma_f32_16x16x32_bf16 v[22:25], v[204:207], v[176:179], v[22:25]
	v_mfma_f32_16x16x32_bf16 v[18:21], v[224:227], v[176:179], v[18:21]
	v_mfma_f32_16x16x32_bf16 v[30:33], v[204:207], v[196:199], v[30:33]
	v_mfma_f32_16x16x32_bf16 v[26:29], v[224:227], v[196:199], v[26:29]
	v_mfma_f32_16x16x32_bf16 v[2:5], v[208:211], v[162:165], v[2:5]
	v_mfma_f32_16x16x32_bf16 v[6:9], v[228:231], v[162:165], v[6:9]
	v_mfma_f32_16x16x32_bf16 v[10:13], v[208:211], v[172:175], v[10:13]
	v_mfma_f32_16x16x32_bf16 v[14:17], v[228:231], v[172:175], v[14:17]
	v_mfma_f32_16x16x32_bf16 v[22:25], v[208:211], v[192:195], v[22:25]
	v_mfma_f32_16x16x32_bf16 v[18:21], v[228:231], v[192:195], v[18:21]
	v_mfma_f32_16x16x32_bf16 v[30:33], v[208:211], v[200:203], v[30:33]
	v_mfma_f32_16x16x32_bf16 v[26:29], v[228:231], v[200:203], v[26:29]
	s_barrier
	ds_read_b128 v[158:161], v140 offset:16384
	ds_read_b128 v[162:165], v140 offset:17408
	ds_read_b128 v[168:171], v140 offset:18432
	ds_read_b128 v[172:175], v140 offset:19456
	ds_read_b128 v[176:179], v140 offset:20480
	ds_read_b128 v[192:195], v140 offset:21504
	ds_read_b128 v[196:199], v140 offset:22528
	ds_read_b128 v[200:203], v140 offset:23552
	global_load_lds_dwordx4 v[232:233], off
	v_lshl_add_u64 v[234:235], s[22:23], 0, v[132:133]
	s_mov_b32 m0, s29
	s_nop 0
	global_load_lds_dwordx4 v[234:235], off
	s_waitcnt vmcnt(10)
	s_barrier
	s_waitcnt lgkmcnt(0)
	v_mfma_f32_16x16x32_bf16 v[110:113], v[142:145], v[158:161], v[110:113]
	v_mfma_f32_16x16x32_bf16 v[106:109], v[150:153], v[158:161], v[106:109]
	v_mfma_f32_16x16x32_bf16 v[90:93], v[142:145], v[168:171], v[90:93]
	v_mfma_f32_16x16x32_bf16 v[82:85], v[150:153], v[168:171], v[82:85]
	v_mfma_f32_16x16x32_bf16 v[78:81], v[142:145], v[176:179], v[78:81]
	v_mfma_f32_16x16x32_bf16 v[74:77], v[150:153], v[176:179], v[74:77]
	v_mfma_f32_16x16x32_bf16 v[70:73], v[142:145], v[196:199], v[70:73]
	v_mfma_f32_16x16x32_bf16 v[66:69], v[150:153], v[196:199], v[66:69]
	v_mfma_f32_16x16x32_bf16 v[110:113], v[146:149], v[162:165], v[110:113]
	v_mfma_f32_16x16x32_bf16 v[106:109], v[154:157], v[162:165], v[106:109]
	v_mfma_f32_16x16x32_bf16 v[90:93], v[146:149], v[172:175], v[90:93]
	v_mfma_f32_16x16x32_bf16 v[82:85], v[154:157], v[172:175], v[82:85]
	v_mfma_f32_16x16x32_bf16 v[78:81], v[146:149], v[192:195], v[78:81]
	v_mfma_f32_16x16x32_bf16 v[74:77], v[154:157], v[192:195], v[74:77]
	v_mfma_f32_16x16x32_bf16 v[70:73], v[146:149], v[200:203], v[70:73]
	v_mfma_f32_16x16x32_bf16 v[66:69], v[154:157], v[200:203], v[66:69]
	s_barrier
	s_add_u32 s56, s90, 0x200000
	s_addc_u32 s57, s91, 0
	s_add_i32 s58, s58, s81
	v_lshl_add_u64 v[142:143], s[56:57], 0, v[134:135]
	s_mov_b32 m0, s58
	s_nop 0
	global_load_lds_dwordx4 v[142:143], off
	v_lshl_add_u64 v[142:143], s[56:57], 0, v[130:131]
	s_add_i32 m0, s58, 0x2000
	s_nop 0
	global_load_lds_dwordx4 v[142:143], off
	v_add_u32_e32 v141, 0x18000, v139
	ds_read_b128 v[142:145], v141
	ds_read_b128 v[146:149], v141 offset:1024
	ds_read_b128 v[150:153], v141 offset:2048
	ds_read_b128 v[154:157], v141 offset:3072
	s_add_i32 s56, 0, 0x18000
	s_waitcnt vmcnt(6)
	s_barrier
	v_mfma_f32_16x16x32_bf16 v[38:41], v[204:207], v[158:161], v[38:41]
	v_mfma_f32_16x16x32_bf16 v[34:37], v[224:227], v[158:161], v[34:37]
	v_mfma_f32_16x16x32_bf16 v[46:49], v[204:207], v[168:171], v[46:49]
	v_mfma_f32_16x16x32_bf16 v[42:45], v[224:227], v[168:171], v[42:45]
	v_mfma_f32_16x16x32_bf16 v[54:57], v[204:207], v[176:179], v[54:57]
	v_mfma_f32_16x16x32_bf16 v[50:53], v[224:227], v[176:179], v[50:53]
	v_mfma_f32_16x16x32_bf16 v[62:65], v[204:207], v[196:199], v[62:65]
	v_mfma_f32_16x16x32_bf16 v[58:61], v[224:227], v[196:199], v[58:61]
	v_mfma_f32_16x16x32_bf16 v[38:41], v[208:211], v[162:165], v[38:41]
	v_mfma_f32_16x16x32_bf16 v[34:37], v[228:231], v[162:165], v[34:37]
	v_mfma_f32_16x16x32_bf16 v[46:49], v[208:211], v[172:175], v[46:49]
	v_mfma_f32_16x16x32_bf16 v[42:45], v[228:231], v[172:175], v[42:45]
	v_mfma_f32_16x16x32_bf16 v[54:57], v[208:211], v[192:195], v[54:57]
	v_mfma_f32_16x16x32_bf16 v[50:53], v[228:231], v[192:195], v[50:53]
	v_mfma_f32_16x16x32_bf16 v[62:65], v[208:211], v[200:203], v[62:65]
	v_mfma_f32_16x16x32_bf16 v[58:61], v[228:231], v[200:203], v[58:61]
	s_barrier
	s_add_u32 s22, s22, 0x10000
	s_addc_u32 s23, s23, 0
	s_mov_b32 m0, s44
	v_lshl_add_u64 v[204:205], s[22:23], 0, v[136:137]
	ds_read_b128 v[158:161], v140 offset:32768
	ds_read_b128 v[162:165], v140 offset:33792
	ds_read_b128 v[168:171], v140 offset:34816
	ds_read_b128 v[172:175], v140 offset:35840
	ds_read_b128 v[176:179], v140 offset:36864
	ds_read_b128 v[192:195], v140 offset:37888
	ds_read_b128 v[196:199], v140 offset:38912
	ds_read_b128 v[200:203], v140 offset:39936
	global_load_lds_dwordx4 v[204:205], off
	v_lshl_add_u64 v[204:205], s[22:23], 0, v[132:133]
	s_mov_b32 m0, s45
	s_nop 0
	global_load_lds_dwordx4 v[204:205], off
	s_waitcnt lgkmcnt(8)
	s_barrier
	s_waitcnt lgkmcnt(0)
	v_mfma_f32_16x16x32_bf16 v[86:89], v[142:145], v[158:161], v[86:89]
	v_mfma_f32_16x16x32_bf16 v[94:97], v[150:153], v[158:161], v[94:97]
	v_mfma_f32_16x16x32_bf16 v[98:101], v[142:145], v[168:171], v[98:101]
	v_mfma_f32_16x16x32_bf16 v[102:105], v[150:153], v[168:171], v[102:105]
	v_mfma_f32_16x16x32_bf16 v[114:117], v[142:145], v[176:179], v[114:117]
	v_mfma_f32_16x16x32_bf16 v[122:125], v[150:153], v[176:179], v[122:125]
	v_mfma_f32_16x16x32_bf16 v[126:129], v[142:145], v[196:199], v[126:129]
	v_mfma_f32_16x16x32_bf16 v[118:121], v[150:153], v[196:199], v[118:121]
	v_mfma_f32_16x16x32_bf16 v[86:89], v[146:149], v[162:165], v[86:89]
	v_mfma_f32_16x16x32_bf16 v[94:97], v[154:157], v[162:165], v[94:97]
	v_mfma_f32_16x16x32_bf16 v[98:101], v[146:149], v[172:175], v[98:101]
	v_mfma_f32_16x16x32_bf16 v[102:105], v[154:157], v[172:175], v[102:105]
	v_mfma_f32_16x16x32_bf16 v[114:117], v[146:149], v[192:195], v[114:117]
	v_mfma_f32_16x16x32_bf16 v[122:125], v[154:157], v[192:195], v[122:125]
	v_mfma_f32_16x16x32_bf16 v[126:129], v[146:149], v[200:203], v[126:129]
	v_mfma_f32_16x16x32_bf16 v[118:121], v[154:157], v[200:203], v[118:121]
	s_barrier
	s_add_i32 s57, 0, 0x1c000
	s_add_i32 s22, s56, s81
	v_add_u32_e32 v141, s57, v139
	v_lshl_add_u64 v[212:213], v[212:213], 0, s[78:79]
	s_mov_b32 m0, s22
	ds_read_b128 v[204:207], v141
	ds_read_b128 v[208:211], v141 offset:1024
	ds_read_b128 v[224:227], v141 offset:2048
	ds_read_b128 v[228:231], v141 offset:3072
	global_load_lds_dwordx4 v[212:213], off
	v_lshl_add_u64 v[212:213], v[222:223], 0, s[78:79]
	s_add_i32 m0, s22, 0x2000
	s_nop 0
	global_load_lds_dwordx4 v[212:213], off
	s_mov_b32 m0, s47
	v_lshl_add_u64 v[212:213], v[232:233], 0, s[78:79]
	s_barrier
	s_waitcnt lgkmcnt(0)
	v_mfma_f32_16x16x32_bf16 v[2:5], v[204:207], v[158:161], v[2:5]
	v_mfma_f32_16x16x32_bf16 v[6:9], v[224:227], v[158:161], v[6:9]
	v_mfma_f32_16x16x32_bf16 v[10:13], v[204:207], v[168:171], v[10:13]
	v_mfma_f32_16x16x32_bf16 v[14:17], v[224:227], v[168:171], v[14:17]
	v_mfma_f32_16x16x32_bf16 v[22:25], v[204:207], v[176:179], v[22:25]
	v_mfma_f32_16x16x32_bf16 v[18:21], v[224:227], v[176:179], v[18:21]
	v_mfma_f32_16x16x32_bf16 v[30:33], v[204:207], v[196:199], v[30:33]
	v_mfma_f32_16x16x32_bf16 v[26:29], v[224:227], v[196:199], v[26:29]
	v_mfma_f32_16x16x32_bf16 v[2:5], v[208:211], v[162:165], v[2:5]
	v_mfma_f32_16x16x32_bf16 v[6:9], v[228:231], v[162:165], v[6:9]
	v_mfma_f32_16x16x32_bf16 v[10:13], v[208:211], v[172:175], v[10:13]
	v_mfma_f32_16x16x32_bf16 v[14:17], v[228:231], v[172:175], v[14:17]
	v_mfma_f32_16x16x32_bf16 v[22:25], v[208:211], v[192:195], v[22:25]
	v_mfma_f32_16x16x32_bf16 v[18:21], v[228:231], v[192:195], v[18:21]
	v_mfma_f32_16x16x32_bf16 v[30:33], v[208:211], v[200:203], v[30:33]
	v_mfma_f32_16x16x32_bf16 v[26:29], v[228:231], v[200:203], v[26:29]
	s_barrier
	ds_read_b128 v[158:161], v140 offset:49152
	ds_read_b128 v[162:165], v140 offset:50176
	ds_read_b128 v[168:171], v140 offset:51200
	ds_read_b128 v[172:175], v140 offset:52224
	ds_read_b128 v[176:179], v140 offset:53248
	ds_read_b128 v[192:195], v140 offset:54272
	ds_read_b128 v[196:199], v140 offset:55296
	ds_read_b128 v[200:203], v140 offset:56320
	global_load_lds_dwordx4 v[212:213], off
	v_lshl_add_u64 v[212:213], v[234:235], 0, s[78:79]
	s_mov_b32 m0, s48
	s_nop 0
	global_load_lds_dwordx4 v[212:213], off
	s_waitcnt vmcnt(10)
	s_barrier
	s_waitcnt lgkmcnt(0)
	v_mfma_f32_16x16x32_bf16 v[110:113], v[142:145], v[158:161], v[110:113]
	v_mfma_f32_16x16x32_bf16 v[106:109], v[150:153], v[158:161], v[106:109]
	v_mfma_f32_16x16x32_bf16 v[90:93], v[142:145], v[168:171], v[90:93]
	v_mfma_f32_16x16x32_bf16 v[82:85], v[150:153], v[168:171], v[82:85]
	v_mfma_f32_16x16x32_bf16 v[78:81], v[142:145], v[176:179], v[78:81]
	v_mfma_f32_16x16x32_bf16 v[74:77], v[150:153], v[176:179], v[74:77]
	v_mfma_f32_16x16x32_bf16 v[70:73], v[142:145], v[196:199], v[70:73]
	v_mfma_f32_16x16x32_bf16 v[66:69], v[150:153], v[196:199], v[66:69]
	v_mfma_f32_16x16x32_bf16 v[110:113], v[146:149], v[162:165], v[110:113]
	v_mfma_f32_16x16x32_bf16 v[106:109], v[154:157], v[162:165], v[106:109]
	v_mfma_f32_16x16x32_bf16 v[90:93], v[146:149], v[172:175], v[90:93]
	v_mfma_f32_16x16x32_bf16 v[82:85], v[154:157], v[172:175], v[82:85]
	v_mfma_f32_16x16x32_bf16 v[78:81], v[146:149], v[192:195], v[78:81]
	v_mfma_f32_16x16x32_bf16 v[74:77], v[154:157], v[192:195], v[74:77]
	v_mfma_f32_16x16x32_bf16 v[70:73], v[146:149], v[200:203], v[70:73]
	v_mfma_f32_16x16x32_bf16 v[66:69], v[154:157], v[200:203], v[66:69]
	s_barrier
	s_add_u32 s22, s90, 0x200080
	s_addc_u32 s23, s91, 0
	s_add_i32 s56, s57, s81
	v_lshl_add_u64 v[142:143], s[22:23], 0, v[134:135]
	s_mov_b32 m0, s56
	s_nop 0
	global_load_lds_dwordx4 v[142:143], off
	v_lshl_add_u64 v[142:143], s[22:23], 0, v[130:131]
	s_add_i32 m0, s56, 0x2000
	s_nop 0
	global_load_lds_dwordx4 v[142:143], off
	v_add_u32_e32 v141, 0x10000, v139
	ds_read_b128 v[142:145], v141
	ds_read_b128 v[146:149], v141 offset:1024
	ds_read_b128 v[150:153], v141 offset:2048
	ds_read_b128 v[154:157], v141 offset:3072
	s_add_i32 s54, s54, 2
	s_add_i32 s55, s55, 0x10000
	s_cmpk_gt_u32 s54, 0x7d
	s_mov_b64 s[90:91], vcc
	s_waitcnt vmcnt(6)
	s_barrier
	v_mfma_f32_16x16x32_bf16 v[38:41], v[204:207], v[158:161], v[38:41]
	v_mfma_f32_16x16x32_bf16 v[34:37], v[224:227], v[158:161], v[34:37]
	v_mfma_f32_16x16x32_bf16 v[46:49], v[204:207], v[168:171], v[46:49]
	v_mfma_f32_16x16x32_bf16 v[42:45], v[224:227], v[168:171], v[42:45]
	v_mfma_f32_16x16x32_bf16 v[54:57], v[204:207], v[176:179], v[54:57]
	v_mfma_f32_16x16x32_bf16 v[50:53], v[224:227], v[176:179], v[50:53]
	v_mfma_f32_16x16x32_bf16 v[62:65], v[204:207], v[196:199], v[62:65]
	v_mfma_f32_16x16x32_bf16 v[58:61], v[224:227], v[196:199], v[58:61]
	v_mfma_f32_16x16x32_bf16 v[38:41], v[208:211], v[162:165], v[38:41]
	v_mfma_f32_16x16x32_bf16 v[34:37], v[228:231], v[162:165], v[34:37]
	v_mfma_f32_16x16x32_bf16 v[46:49], v[208:211], v[172:175], v[46:49]
	v_mfma_f32_16x16x32_bf16 v[42:45], v[228:231], v[172:175], v[42:45]
	v_mfma_f32_16x16x32_bf16 v[54:57], v[208:211], v[192:195], v[54:57]
	v_mfma_f32_16x16x32_bf16 v[50:53], v[228:231], v[192:195], v[50:53]
	v_mfma_f32_16x16x32_bf16 v[62:65], v[208:211], v[200:203], v[62:65]
	v_mfma_f32_16x16x32_bf16 v[58:61], v[228:231], v[200:203], v[58:61]
	s_barrier
	s_cbranch_scc0 .LBB0_814
	s_waitcnt lgkmcnt(0)
	s_andn2_b64 vcc, exec, s[38:39]
	s_cbranch_vccnz .LBB0_806
	v_mov_b32_e32 v58, 0
	s_mov_b32 s80, s42
	s_mov_b32 s25, s82
	s_mov_b64 s[30:31], s[20:21]
	s_mov_b64 s[84:85], s[18:19]
	s_mov_b32 s49, s50
	v_mov_b32_e32 v59, v58
	v_mov_b32_e32 v60, v58
	v_mov_b32_e32 v61, v58
	v_mov_b32_e32 v62, v58
	v_mov_b32_e32 v63, v58
	v_mov_b32_e32 v64, v58
	v_mov_b32_e32 v65, v58
	v_mov_b32_e32 v50, v58
	v_mov_b32_e32 v51, v58
	v_mov_b32_e32 v52, v58
	v_mov_b32_e32 v53, v58
	v_mov_b32_e32 v54, v58
	v_mov_b32_e32 v55, v58
	v_mov_b32_e32 v56, v58
	v_mov_b32_e32 v57, v58
	v_mov_b32_e32 v42, v58
	v_mov_b32_e32 v43, v58
	v_mov_b32_e32 v44, v58
	v_mov_b32_e32 v45, v58
	v_mov_b32_e32 v46, v58
	v_mov_b32_e32 v47, v58
	v_mov_b32_e32 v48, v58
	v_mov_b32_e32 v49, v58
	v_mov_b32_e32 v34, v58
	v_mov_b32_e32 v35, v58
	v_mov_b32_e32 v36, v58
	v_mov_b32_e32 v37, v58
	v_mov_b32_e32 v38, v58
	v_mov_b32_e32 v39, v58
	v_mov_b32_e32 v40, v58
	v_mov_b32_e32 v41, v58
	v_mov_b32_e32 v66, v58
	v_mov_b32_e32 v67, v58
	v_mov_b32_e32 v68, v58
	v_mov_b32_e32 v69, v58
	v_mov_b32_e32 v70, v58
	v_mov_b32_e32 v71, v58
	v_mov_b32_e32 v72, v58
	v_mov_b32_e32 v73, v58
	v_mov_b32_e32 v74, v58
	v_mov_b32_e32 v75, v58
	v_mov_b32_e32 v76, v58
	v_mov_b32_e32 v77, v58
	v_mov_b32_e32 v78, v58
	v_mov_b32_e32 v79, v58
	v_mov_b32_e32 v80, v58
	v_mov_b32_e32 v81, v58
	v_mov_b32_e32 v82, v58
	v_mov_b32_e32 v83, v58
	v_mov_b32_e32 v84, v58
	v_mov_b32_e32 v85, v58
	v_mov_b32_e32 v90, v58
	v_mov_b32_e32 v91, v58
	v_mov_b32_e32 v92, v58
	v_mov_b32_e32 v93, v58
	v_mov_b32_e32 v106, v58
	v_mov_b32_e32 v107, v58
	v_mov_b32_e32 v108, v58
	v_mov_b32_e32 v109, v58
	v_mov_b32_e32 v110, v58
	v_mov_b32_e32 v111, v58
	v_mov_b32_e32 v112, v58
	v_mov_b32_e32 v113, v58
	v_mov_b32_e32 v26, v58
	v_mov_b32_e32 v27, v58
	v_mov_b32_e32 v28, v58
	v_mov_b32_e32 v29, v58
	v_mov_b32_e32 v30, v58
	v_mov_b32_e32 v31, v58
	v_mov_b32_e32 v32, v58
	v_mov_b32_e32 v33, v58
	v_mov_b32_e32 v18, v58
	v_mov_b32_e32 v19, v58
	v_mov_b32_e32 v20, v58
	v_mov_b32_e32 v21, v58
	v_mov_b32_e32 v22, v58
	v_mov_b32_e32 v23, v58
	v_mov_b32_e32 v24, v58
	v_mov_b32_e32 v25, v58
	v_mov_b32_e32 v14, v58
	v_mov_b32_e32 v15, v58
	v_mov_b32_e32 v16, v58
	v_mov_b32_e32 v17, v58
	v_mov_b32_e32 v10, v58
	v_mov_b32_e32 v11, v58
	v_mov_b32_e32 v12, v58
	v_mov_b32_e32 v13, v58
	v_mov_b32_e32 v6, v58
	v_mov_b32_e32 v7, v58
	v_mov_b32_e32 v8, v58
	v_mov_b32_e32 v9, v58
	v_mov_b32_e32 v2, v58
	v_mov_b32_e32 v3, v58
	v_mov_b32_e32 v4, v58
	v_mov_b32_e32 v5, v58
	v_mov_b32_e32 v118, v58
	v_mov_b32_e32 v119, v58
	v_mov_b32_e32 v120, v58
	v_mov_b32_e32 v121, v58
	v_mov_b32_e32 v126, v58
	v_mov_b32_e32 v127, v58
	v_mov_b32_e32 v128, v58
	v_mov_b32_e32 v129, v58
	v_mov_b32_e32 v122, v58
	v_mov_b32_e32 v123, v58
	v_mov_b32_e32 v124, v58
	v_mov_b32_e32 v125, v58
	v_mov_b32_e32 v114, v58
	v_mov_b32_e32 v115, v58
	v_mov_b32_e32 v116, v58
	v_mov_b32_e32 v117, v58
	v_mov_b32_e32 v102, v58
	v_mov_b32_e32 v103, v58
	v_mov_b32_e32 v104, v58
	v_mov_b32_e32 v105, v58
	v_mov_b32_e32 v98, v58
	v_mov_b32_e32 v99, v58
	v_mov_b32_e32 v100, v58
	v_mov_b32_e32 v101, v58
	v_mov_b32_e32 v94, v58
	v_mov_b32_e32 v95, v58
	v_mov_b32_e32 v96, v58
	v_mov_b32_e32 v97, v58
	v_mov_b32_e32 v86, v58
	v_mov_b32_e32 v87, v58
	v_mov_b32_e32 v88, v58
	v_mov_b32_e32 v89, v58
	s_branch .LBB0_806
